# w_in elementwise epilogue straight-line per segment with packed f32; first K-iteration after an epilogue peeled with waits that leave the epilogue stores in flight (w_in and gate/up GEMMs)
# baseline (speedup 1.0000x reference)
; #define PG8_STAGE(bufoff, gbase, voff) do { _Pragma("unroll") for (int _i = 0; _i < 2; ++_i) \
;         __builtin_amdgcn_global_load_lds((const unsigned*)((const char*)(gbase) + (voff)[_i]), (LAS unsigned*)(lds + (bufoff) + ldsw + _i * 8192), 16, 0, 0); } while (0)
; #define PG8_LDA(dst, b, h) do { _Pragma("unroll") for (int m = 0; m < 4; ++m) _Pragma("unroll") for (int k = 0; k < 2; ++k) dst[m][k] = *(const LAS bf16x8*)(lds + PG8_SA(b, h) + aoff + m * 2048 + k * 1024); } while (0)
; #define PG8_LDB(dst, b, h) do { _Pragma("unroll") for (int n = 0; n < 2; ++n) _Pragma("unroll") for (int k = 0; k < 2; ++k) dst[n][k] = *(const LAS bf16x8*)(lds + PG8_SB(b, h) + boff + n * 2048 + k * 1024); } while (0)
; #define PG8_MMA(ai, bj, At, Bt) do { __builtin_amdgcn_s_setprio(1); _Pragma("unroll") for (int m = 0; m < 4; ++m) _Pragma("unroll") for (int n = 0; n < 2; ++n) _Pragma("unroll") for (int k = 0; k < 2; ++k) \
;         acc[ai][bj][m][n] = __builtin_amdgcn_mfma_f32_16x16x32_bf16(Bt[n][k], At[m][k], acc[ai][bj][m][n], 0, 0, 0); __builtin_amdgcn_s_setprio(0); } while (0)
; #define PG8_WAIT_V(n) asm volatile("s_waitcnt vmcnt(" #n ")" ::: "memory")
; #define PG8_WAIT_L(n) asm volatile("s_waitcnt lgkmcnt(" #n ")" ::: "memory")
; template <class Epi>
; __device__ __forceinline__ void gemm_phase(LAS unsigned char* lds, const Gemm g, const Epi& E) {
;     ...
;             PG8_LDB(B0, 0, 0); PG8_LDB(B1, 0, 1); PG8_SCHED; PG8_LDA(At, 0, 0); PG8_STAGE(PG8_SA(1, 1), a1 + hstep, voffA);
;             PG8_WAIT_V(8); PG8_WAIT_L(0); PG8_BAR; PG8_MMA(0, 0, At, B0); PG8_MMA(0, 1, At, B1); PG8_BAR; PG8_SCHED;
;             PG8_LDA(At, 0, 1); PG8_STAGE(PG8_SB(0, 0), b2, voffA); PG8_STAGE(PG8_SB(0, 1), b2 + hstep, voffA); PG8_STAGE(PG8_SA(0, 0), a2, voffA);
;             PG8_WAIT_V(8); PG8_WAIT_L(0); PG8_BAR; PG8_MMA(1, 0, At, B0); PG8_MMA(1, 1, At, B1); PG8_BAR; PG8_SCHED;
;             PG8_LDB(B0, 1, 0); PG8_LDB(B1, 1, 1); PG8_SCHED; PG8_LDA(At, 1, 0); PG8_STAGE(PG8_SA(0, 1), a2 + hstep, voffA);
;             PG8_WAIT_V(8); PG8_WAIT_L(0); PG8_BAR; PG8_MMA(0, 0, At, B0); PG8_MMA(0, 1, At, B1); PG8_BAR; PG8_SCHED;
;             PG8_LDA(At, 1, 1); PG8_STAGE(PG8_SB(1, 0), b3, voffA); PG8_STAGE(PG8_SB(1, 1), b3 + hstep, voffA); PG8_STAGE(PG8_SA(1, 0), a3, voffA);
;             PG8_WAIT_V(8); PG8_WAIT_L(0); PG8_BAR; PG8_MMA(1, 0, At, B0); PG8_MMA(1, 1, At, B1); PG8_BAR; PG8_SCHED;
.Lk1_peel:
	s_add_i32 s78, s4, 2
	s_add_u32 s5, s8, 0xfffc0080
	s_addc_u32 s10, s9, -1
	s_cmp_eq_u32 s69, s4
	s_cselect_b32 s11, s2, s10
	s_cselect_b32 s10, s12, s5
	s_cselect_b32 s5, s13, s75
	s_cselect_b32 s4, s15, s71
	s_add_i32 s25, 0, 0x14000
	v_add_u32_e32 v156, s21, v166
	v_add_u32_e32 v164, s25, v166
	ds_read_b128 v[130:133], v156
	ds_read_b128 v[134:137], v156 offset:1024
	ds_read_b128 v[152:155], v156 offset:2048
	ds_read_b128 v[156:159], v156 offset:3072
	ds_read_b128 v[160:163], v164
	ds_read_b128 v[190:193], v164 offset:1024
	ds_read_b128 v[194:197], v164 offset:2048
	ds_read_b128 v[198:201], v164 offset:3072
	v_lshl_add_u64 v[164:165], s[8:9], 0, v[148:149]
	s_add_i32 m0, s53, 0xc000
	ds_read_b128 v[202:205], v167
	ds_read_b128 v[206:209], v167 offset:1024
	ds_read_b128 v[210:213], v167 offset:2048
	ds_read_b128 v[214:217], v167 offset:3072
	ds_read_b128 v[218:221], v167 offset:4096
	ds_read_b128 v[222:225], v167 offset:5120
	ds_read_b128 v[226:229], v167 offset:6144
	ds_read_b128 v[230:233], v167 offset:7168
	global_load_lds_dwordx4 v[164:165], off
	v_lshl_add_u64 v[164:165], s[8:9], 0, v[150:151]
	s_add_i32 m0, s53, 0xe000
	s_nop 0
	global_load_lds_dwordx4 v[164:165], off
	s_cmp_eq_u32 s32, 1
	s_cbranch_scc1 .Lrw1a_1
	s_cmp_eq_u32 s32, 2
	s_cbranch_scc1 .Lrw1a_2
	s_waitcnt vmcnt(63)
	s_branch .Lrw1a_d
.Lrw1a_1:
	s_waitcnt vmcnt(24)
	s_branch .Lrw1a_d
.Lrw1a_2:
	s_waitcnt vmcnt(40)
	s_branch .Lrw1a_d
.Lrw1a_d:
	s_waitcnt lgkmcnt(0)
	s_barrier
	s_setprio 1
	s_waitcnt lgkmcnt(0)
	v_mfma_f32_16x16x32_bf16 v[122:125], v[130:133], v[202:205], v[122:125]
	v_mfma_f32_16x16x32_bf16 v[126:129], v[152:155], v[202:205], v[126:129]
	v_mfma_f32_16x16x32_bf16 v[106:109], v[130:133], v[210:213], v[106:109]
	v_mfma_f32_16x16x32_bf16 v[110:113], v[152:155], v[210:213], v[110:113]
	v_mfma_f32_16x16x32_bf16 v[90:93], v[130:133], v[218:221], v[90:93]
	v_mfma_f32_16x16x32_bf16 v[94:97], v[152:155], v[218:221], v[94:97]
	v_mfma_f32_16x16x32_bf16 v[74:77], v[130:133], v[226:229], v[74:77]
	v_mfma_f32_16x16x32_bf16 v[78:81], v[152:155], v[226:229], v[78:81]
	v_mfma_f32_16x16x32_bf16 v[122:125], v[134:137], v[206:209], v[122:125]
	v_mfma_f32_16x16x32_bf16 v[126:129], v[156:159], v[206:209], v[126:129]
	v_mfma_f32_16x16x32_bf16 v[106:109], v[134:137], v[214:217], v[106:109]
	v_mfma_f32_16x16x32_bf16 v[110:113], v[156:159], v[214:217], v[110:113]
	v_mfma_f32_16x16x32_bf16 v[90:93], v[134:137], v[222:225], v[90:93]
	v_mfma_f32_16x16x32_bf16 v[94:97], v[156:159], v[222:225], v[94:97]
	v_mfma_f32_16x16x32_bf16 v[74:77], v[134:137], v[230:233], v[74:77]
	v_mfma_f32_16x16x32_bf16 v[78:81], v[156:159], v[230:233], v[78:81]
	s_setprio 0
	s_setprio 1
	v_mfma_f32_16x16x32_bf16 v[114:117], v[160:163], v[202:205], v[114:117]
	v_mfma_f32_16x16x32_bf16 v[118:121], v[194:197], v[202:205], v[118:121]
	v_mfma_f32_16x16x32_bf16 v[98:101], v[160:163], v[210:213], v[98:101]
	v_mfma_f32_16x16x32_bf16 v[102:105], v[194:197], v[210:213], v[102:105]
	v_mfma_f32_16x16x32_bf16 v[82:85], v[160:163], v[218:221], v[82:85]
	v_mfma_f32_16x16x32_bf16 v[86:89], v[194:197], v[218:221], v[86:89]
	v_mfma_f32_16x16x32_bf16 v[66:69], v[160:163], v[226:229], v[66:69]
	v_mfma_f32_16x16x32_bf16 v[70:73], v[194:197], v[226:229], v[70:73]
	v_mfma_f32_16x16x32_bf16 v[114:117], v[190:193], v[206:209], v[114:117]
	v_mfma_f32_16x16x32_bf16 v[118:121], v[198:201], v[206:209], v[118:121]
	v_mfma_f32_16x16x32_bf16 v[98:101], v[190:193], v[214:217], v[98:101]
	v_mfma_f32_16x16x32_bf16 v[102:105], v[198:201], v[214:217], v[102:105]
	v_mfma_f32_16x16x32_bf16 v[82:85], v[190:193], v[222:225], v[82:85]
	v_mfma_f32_16x16x32_bf16 v[86:89], v[198:201], v[222:225], v[86:89]
	v_mfma_f32_16x16x32_bf16 v[66:69], v[190:193], v[230:233], v[66:69]
	v_mfma_f32_16x16x32_bf16 v[70:73], v[198:201], v[230:233], v[70:73]
	s_setprio 0
	s_barrier
	s_add_i32 s79, s21, s26
	v_lshl_add_u64 v[164:165], s[4:5], 0, v[0:1]
	s_mov_b32 m0, s79
	ds_read_b128 v[202:205], v167 offset:16384
	ds_read_b128 v[206:209], v167 offset:17408
	ds_read_b128 v[210:213], v167 offset:18432
	ds_read_b128 v[214:217], v167 offset:19456
	ds_read_b128 v[218:221], v167 offset:20480
	ds_read_b128 v[222:225], v167 offset:21504
	ds_read_b128 v[226:229], v167 offset:22528
	ds_read_b128 v[230:233], v167 offset:23552
	global_load_lds_dwordx4 v[164:165], off
	s_add_i32 m0, s79, 0x2000
	s_add_u32 vcc_lo, s4, 0x40000
	v_lshl_add_u64 v[168:169], s[4:5], 0, v[146:147]
	s_addc_u32 vcc_hi, s5, 0
	s_add_i32 s25, s25, s26
	global_load_lds_dwordx4 v[168:169], off
	v_lshl_add_u64 v[234:235], vcc, 0, v[0:1]
	s_mov_b32 m0, s25
	v_lshl_add_u64 v[236:237], s[10:11], 0, v[146:147]
	global_load_lds_dwordx4 v[234:235], off
	v_lshl_add_u64 v[234:235], vcc, 0, v[146:147]
	s_add_i32 m0, s25, 0x2000
	s_nop 0
	global_load_lds_dwordx4 v[234:235], off
	v_lshl_add_u64 v[234:235], s[10:11], 0, v[0:1]
	s_mov_b32 m0, s53
	s_nop 0
	global_load_lds_dwordx4 v[234:235], off
	s_mov_b32 m0, s73
	s_nop 0
	global_load_lds_dwordx4 v[236:237], off
	s_cmp_eq_u32 s32, 1
	s_cbranch_scc1 .Lrw1b_1
	s_cmp_eq_u32 s32, 2
	s_cbranch_scc1 .Lrw1b_2
	s_waitcnt vmcnt(63)
	s_branch .Lrw1b_d

; #define PG8_STAGE(bufoff, gbase, voff) do { _Pragma("unroll") for (int _i = 0; _i < 2; ++_i) \
;         __builtin_amdgcn_global_load_lds((const unsigned*)((const char*)(gbase) + (voff)[_i]), (LAS unsigned*)(lds + (bufoff) + ldsw + _i * 8192), 16, 0, 0); } while (0)
; #define PG8_LDA(dst, b, h) do { _Pragma("unroll") for (int m = 0; m < 4; ++m) _Pragma("unroll") for (int k = 0; k < 2; ++k) dst[m][k] = *(const LAS bf16x8*)(lds + PG8_SA(b, h) + aoff + m * 2048 + k * 1024); } while (0)
; #define PG8_LDB(dst, b, h) do { _Pragma("unroll") for (int n = 0; n < 2; ++n) _Pragma("unroll") for (int k = 0; k < 2; ++k) dst[n][k] = *(const LAS bf16x8*)(lds + PG8_SB(b, h) + boff + n * 2048 + k * 1024); } while (0)
; #define PG8_MMA(ai, bj, At, Bt) do { __builtin_amdgcn_s_setprio(1); _Pragma("unroll") for (int m = 0; m < 4; ++m) _Pragma("unroll") for (int n = 0; n < 2; ++n) _Pragma("unroll") for (int k = 0; k < 2; ++k) \
;         acc[ai][bj][m][n] = __builtin_amdgcn_mfma_f32_16x16x32_bf16(Bt[n][k], At[m][k], acc[ai][bj][m][n], 0, 0, 0); __builtin_amdgcn_s_setprio(0); } while (0)
; #define PG8_WAIT_V(n) asm volatile("s_waitcnt vmcnt(" #n ")" ::: "memory")
; #define PG8_WAIT_L(n) asm volatile("s_waitcnt lgkmcnt(" #n ")" ::: "memory")
; #define PG8_BAR __builtin_amdgcn_s_barrier()
; #define PG8_SCHED __builtin_amdgcn_sched_barrier(0)
; template <class Epi>
; __device__ __forceinline__ void gemm_phase(LAS unsigned char* lds, const Gemm g, const Epi& E) {
;     ...
;             PG8_LDA(At, 0, 1); PG8_STAGE(PG8_SB(0, 0), b2, voffA); PG8_STAGE(PG8_SB(0, 1), b2 + hstep, voffA); PG8_STAGE(PG8_SA(0, 0), a2, voffA);
;             PG8_WAIT_V(8); PG8_WAIT_L(0); PG8_BAR; PG8_MMA(1, 0, At, B0); PG8_MMA(1, 1, At, B1); PG8_BAR; PG8_SCHED;
;             PG8_LDB(B0, 1, 0); PG8_LDB(B1, 1, 1); PG8_SCHED; PG8_LDA(At, 1, 0); PG8_STAGE(PG8_SA(0, 1), a2 + hstep, voffA);
;             PG8_WAIT_V(8); PG8_WAIT_L(0); PG8_BAR; PG8_MMA(0, 0, At, B0); PG8_MMA(0, 1, At, B1); PG8_BAR; PG8_SCHED;
.Lrw1b_d:
	s_mov_b32 s32, 0
	s_waitcnt lgkmcnt(0)
	s_barrier
	s_setprio 1
	s_waitcnt lgkmcnt(0)
	v_mfma_f32_16x16x32_bf16 v[58:61], v[130:133], v[202:205], v[58:61]
	v_mfma_f32_16x16x32_bf16 v[62:65], v[152:155], v[202:205], v[62:65]
	v_mfma_f32_16x16x32_bf16 v[42:45], v[130:133], v[210:213], v[42:45]
	v_mfma_f32_16x16x32_bf16 v[46:49], v[152:155], v[210:213], v[46:49]
	v_mfma_f32_16x16x32_bf16 v[26:29], v[130:133], v[218:221], v[26:29]
	v_mfma_f32_16x16x32_bf16 v[30:33], v[152:155], v[218:221], v[30:33]
	v_mfma_f32_16x16x32_bf16 v[10:13], v[130:133], v[226:229], v[10:13]
	v_mfma_f32_16x16x32_bf16 v[14:17], v[152:155], v[226:229], v[14:17]
	v_mfma_f32_16x16x32_bf16 v[58:61], v[134:137], v[206:209], v[58:61]
	v_mfma_f32_16x16x32_bf16 v[62:65], v[156:159], v[206:209], v[62:65]
	v_mfma_f32_16x16x32_bf16 v[42:45], v[134:137], v[214:217], v[42:45]
	v_mfma_f32_16x16x32_bf16 v[46:49], v[156:159], v[214:217], v[46:49]
	v_mfma_f32_16x16x32_bf16 v[26:29], v[134:137], v[222:225], v[26:29]
	v_mfma_f32_16x16x32_bf16 v[30:33], v[156:159], v[222:225], v[30:33]
	v_mfma_f32_16x16x32_bf16 v[10:13], v[134:137], v[230:233], v[10:13]
	v_mfma_f32_16x16x32_bf16 v[14:17], v[156:159], v[230:233], v[14:17]
	s_setprio 0
	s_setprio 1
	v_mfma_f32_16x16x32_bf16 v[50:53], v[160:163], v[202:205], v[50:53]
	v_mfma_f32_16x16x32_bf16 v[54:57], v[194:197], v[202:205], v[54:57]
	v_mfma_f32_16x16x32_bf16 v[34:37], v[160:163], v[210:213], v[34:37]
	v_mfma_f32_16x16x32_bf16 v[38:41], v[194:197], v[210:213], v[38:41]
	v_mfma_f32_16x16x32_bf16 v[18:21], v[160:163], v[218:221], v[18:21]
	v_mfma_f32_16x16x32_bf16 v[22:25], v[194:197], v[218:221], v[22:25]
	v_mfma_f32_16x16x32_bf16 v[6:9], v[160:163], v[226:229], v[6:9]
	v_mfma_f32_16x16x32_bf16 v[2:5], v[194:197], v[226:229], v[2:5]
	v_mfma_f32_16x16x32_bf16 v[50:53], v[190:193], v[206:209], v[50:53]
	v_mfma_f32_16x16x32_bf16 v[54:57], v[198:201], v[206:209], v[54:57]
	v_mfma_f32_16x16x32_bf16 v[34:37], v[190:193], v[214:217], v[34:37]
	v_mfma_f32_16x16x32_bf16 v[38:41], v[198:201], v[214:217], v[38:41]
	v_mfma_f32_16x16x32_bf16 v[18:21], v[190:193], v[222:225], v[18:21]
	v_mfma_f32_16x16x32_bf16 v[22:25], v[198:201], v[222:225], v[22:25]
	v_mfma_f32_16x16x32_bf16 v[6:9], v[190:193], v[230:233], v[6:9]
	v_mfma_f32_16x16x32_bf16 v[2:5], v[198:201], v[230:233], v[2:5]
	s_setprio 0
	s_barrier
	s_add_i32 s25, 0, 0x18000
	s_add_i32 s79, 0, 0x1c000
	v_add_u32_e32 v156, s25, v166
	v_add_u32_e32 v189, s79, v166
	ds_read_b128 v[130:133], v156
	ds_read_b128 v[134:137], v156 offset:1024
	ds_read_b128 v[152:155], v156 offset:2048
	ds_read_b128 v[156:159], v156 offset:3072
	ds_read_b128 v[160:163], v189
	ds_read_b128 v[190:193], v189 offset:1024
	ds_read_b128 v[194:197], v189 offset:2048
	ds_read_b128 v[198:201], v189 offset:3072
	s_add_u32 s10, s10, 0x40000
	s_addc_u32 s11, s11, 0
	s_mov_b32 m0, s76
	v_lshl_add_u64 v[238:239], s[10:11], 0, v[0:1]
	ds_read_b128 v[202:205], v167 offset:32768
	ds_read_b128 v[206:209], v167 offset:33792
	ds_read_b128 v[210:213], v167 offset:34816
	ds_read_b128 v[214:217], v167 offset:35840
	ds_read_b128 v[218:221], v167 offset:36864
	ds_read_b128 v[222:225], v167 offset:37888
	ds_read_b128 v[226:229], v167 offset:38912
	ds_read_b128 v[230:233], v167 offset:39936
	global_load_lds_dwordx4 v[238:239], off
	v_lshl_add_u64 v[238:239], s[10:11], 0, v[146:147]
	s_mov_b32 m0, s77
	s_nop 0
	global_load_lds_dwordx4 v[238:239], off
	s_waitcnt vmcnt(8)
	s_waitcnt lgkmcnt(0)
	s_barrier
	s_setprio 1
	s_waitcnt lgkmcnt(0)
	v_mfma_f32_16x16x32_bf16 v[122:125], v[130:133], v[202:205], v[122:125]
	v_mfma_f32_16x16x32_bf16 v[126:129], v[152:155], v[202:205], v[126:129]
	v_mfma_f32_16x16x32_bf16 v[106:109], v[130:133], v[210:213], v[106:109]
	v_mfma_f32_16x16x32_bf16 v[110:113], v[152:155], v[210:213], v[110:113]
	v_mfma_f32_16x16x32_bf16 v[90:93], v[130:133], v[218:221], v[90:93]
	v_mfma_f32_16x16x32_bf16 v[94:97], v[152:155], v[218:221], v[94:97]
	v_mfma_f32_16x16x32_bf16 v[74:77], v[130:133], v[226:229], v[74:77]
	v_mfma_f32_16x16x32_bf16 v[78:81], v[152:155], v[226:229], v[78:81]
	v_mfma_f32_16x16x32_bf16 v[122:125], v[134:137], v[206:209], v[122:125]
	v_mfma_f32_16x16x32_bf16 v[126:129], v[156:159], v[206:209], v[126:129]
	v_mfma_f32_16x16x32_bf16 v[106:109], v[134:137], v[214:217], v[106:109]
	v_mfma_f32_16x16x32_bf16 v[110:113], v[156:159], v[214:217], v[110:113]
	v_mfma_f32_16x16x32_bf16 v[90:93], v[134:137], v[222:225], v[90:93]
	v_mfma_f32_16x16x32_bf16 v[94:97], v[156:159], v[222:225], v[94:97]
	v_mfma_f32_16x16x32_bf16 v[74:77], v[134:137], v[230:233], v[74:77]
	v_mfma_f32_16x16x32_bf16 v[78:81], v[156:159], v[230:233], v[78:81]
	s_setprio 0
	s_setprio 1
	v_mfma_f32_16x16x32_bf16 v[114:117], v[160:163], v[202:205], v[114:117]
	v_mfma_f32_16x16x32_bf16 v[118:121], v[194:197], v[202:205], v[118:121]
	v_mfma_f32_16x16x32_bf16 v[98:101], v[160:163], v[210:213], v[98:101]
	v_mfma_f32_16x16x32_bf16 v[102:105], v[194:197], v[210:213], v[102:105]
	v_mfma_f32_16x16x32_bf16 v[82:85], v[160:163], v[218:221], v[82:85]
	v_mfma_f32_16x16x32_bf16 v[86:89], v[194:197], v[218:221], v[86:89]
	v_mfma_f32_16x16x32_bf16 v[66:69], v[160:163], v[226:229], v[66:69]
	v_mfma_f32_16x16x32_bf16 v[70:73], v[194:197], v[226:229], v[70:73]
	v_mfma_f32_16x16x32_bf16 v[114:117], v[190:193], v[206:209], v[114:117]
	v_mfma_f32_16x16x32_bf16 v[118:121], v[198:201], v[206:209], v[118:121]
	v_mfma_f32_16x16x32_bf16 v[98:101], v[190:193], v[214:217], v[98:101]
	v_mfma_f32_16x16x32_bf16 v[102:105], v[198:201], v[214:217], v[102:105]
	v_mfma_f32_16x16x32_bf16 v[82:85], v[190:193], v[222:225], v[82:85]
	v_mfma_f32_16x16x32_bf16 v[86:89], v[198:201], v[222:225], v[86:89]
	v_mfma_f32_16x16x32_bf16 v[66:69], v[190:193], v[230:233], v[66:69]
	v_mfma_f32_16x16x32_bf16 v[70:73], v[198:201], v[230:233], v[70:73]
	s_setprio 0
	s_barrier
; #define PG8_STAGE(bufoff, gbase, voff) do { _Pragma("unroll") for (int _i = 0; _i < 2; ++_i) \
;         __builtin_amdgcn_global_load_lds((const unsigned*)((const char*)(gbase) + (voff)[_i]), (LAS unsigned*)(lds + (bufoff) + ldsw + _i * 8192), 16, 0, 0); } while (0)
; #define PG8_LDA(dst, b, h) do { _Pragma("unroll") for (int m = 0; m < 4; ++m) _Pragma("unroll") for (int k = 0; k < 2; ++k) dst[m][k] = *(const LAS bf16x8*)(lds + PG8_SA(b, h) + aoff + m * 2048 + k * 1024); } while (0)
; #define PG8_MMA(ai, bj, At, Bt) do { __builtin_amdgcn_s_setprio(1); _Pragma("unroll") for (int m = 0; m < 4; ++m) _Pragma("unroll") for (int n = 0; n < 2; ++n) _Pragma("unroll") for (int k = 0; k < 2; ++k) \
;         acc[ai][bj][m][n] = __builtin_amdgcn_mfma_f32_16x16x32_bf16(Bt[n][k], At[m][k], acc[ai][bj][m][n], 0, 0, 0); __builtin_amdgcn_s_setprio(0); } while (0)
; #define PG8_WAIT_V(n) asm volatile("s_waitcnt vmcnt(" #n ")" ::: "memory")
; #define PG8_WAIT_L(n) asm volatile("s_waitcnt lgkmcnt(" #n ")" ::: "memory")
; #define PG8_BAR __builtin_amdgcn_s_barrier()
; #define PG8_SCHED __builtin_amdgcn_sched_barrier(0)
; template <class Epi>
; __device__ __forceinline__ void gemm_phase(LAS unsigned char* lds, const Gemm g, const Epi& E) {
;     ...
;         for (int t = 0; t < nt; t += 2) {
;     ...
;             PG8_LDA(At, 1, 1); PG8_STAGE(PG8_SB(1, 0), b3, voffA); PG8_STAGE(PG8_SB(1, 1), b3 + hstep, voffA); PG8_STAGE(PG8_SA(1, 0), a3, voffA);
;             PG8_WAIT_V(8); PG8_WAIT_L(0); PG8_BAR; PG8_MMA(1, 0, At, B0); PG8_MMA(1, 1, At, B1); PG8_BAR; PG8_SCHED;
	s_add_i32 s10, s25, s26
	v_lshl_add_u64 v[164:165], v[164:165], 0, s[80:81]
	s_mov_b32 m0, s10
	ds_read_b128 v[202:205], v167 offset:49152
	ds_read_b128 v[206:209], v167 offset:50176
	ds_read_b128 v[210:213], v167 offset:51200
	ds_read_b128 v[214:217], v167 offset:52224
	ds_read_b128 v[218:221], v167 offset:53248
	ds_read_b128 v[222:225], v167 offset:54272
	ds_read_b128 v[226:229], v167 offset:55296
	ds_read_b128 v[230:233], v167 offset:56320
	global_load_lds_dwordx4 v[164:165], off
	s_add_i32 m0, s10, 0x2000
	s_add_u32 s4, s4, 0x40080
	v_lshl_add_u64 v[164:165], v[168:169], 0, s[80:81]
	s_addc_u32 s5, s5, 0
	s_add_i32 s10, s79, s26
	global_load_lds_dwordx4 v[164:165], off
	v_lshl_add_u64 v[164:165], s[4:5], 0, v[0:1]
	s_mov_b32 m0, s10
	s_nop 0
	global_load_lds_dwordx4 v[164:165], off
	v_lshl_add_u64 v[164:165], s[4:5], 0, v[146:147]
	s_add_i32 m0, s10, 0x2000
	s_nop 0
	global_load_lds_dwordx4 v[164:165], off
	v_lshl_add_u64 v[164:165], v[234:235], 0, s[80:81]
	s_mov_b32 m0, s37
	s_nop 0
	global_load_lds_dwordx4 v[164:165], off
	v_lshl_add_u64 v[164:165], v[236:237], 0, s[80:81]
	s_mov_b32 m0, s93
	s_nop 0
	global_load_lds_dwordx4 v[164:165], off
	s_waitcnt vmcnt(8)
	s_waitcnt lgkmcnt(0)
	s_barrier
	s_setprio 1
	s_waitcnt lgkmcnt(0)
	v_mfma_f32_16x16x32_bf16 v[58:61], v[130:133], v[202:205], v[58:61]
	v_mfma_f32_16x16x32_bf16 v[62:65], v[152:155], v[202:205], v[62:65]
	v_mfma_f32_16x16x32_bf16 v[42:45], v[130:133], v[210:213], v[42:45]
	v_mfma_f32_16x16x32_bf16 v[46:49], v[152:155], v[210:213], v[46:49]
	v_mfma_f32_16x16x32_bf16 v[26:29], v[130:133], v[218:221], v[26:29]
	v_mfma_f32_16x16x32_bf16 v[30:33], v[152:155], v[218:221], v[30:33]
	v_mfma_f32_16x16x32_bf16 v[10:13], v[130:133], v[226:229], v[10:13]
	v_mfma_f32_16x16x32_bf16 v[14:17], v[152:155], v[226:229], v[14:17]
	v_mfma_f32_16x16x32_bf16 v[58:61], v[134:137], v[206:209], v[58:61]
	v_mfma_f32_16x16x32_bf16 v[62:65], v[156:159], v[206:209], v[62:65]
	v_mfma_f32_16x16x32_bf16 v[42:45], v[134:137], v[214:217], v[42:45]
	v_mfma_f32_16x16x32_bf16 v[46:49], v[156:159], v[214:217], v[46:49]
	v_mfma_f32_16x16x32_bf16 v[26:29], v[134:137], v[222:225], v[26:29]
	v_mfma_f32_16x16x32_bf16 v[30:33], v[156:159], v[222:225], v[30:33]
	v_mfma_f32_16x16x32_bf16 v[10:13], v[134:137], v[230:233], v[10:13]
	v_mfma_f32_16x16x32_bf16 v[14:17], v[156:159], v[230:233], v[14:17]
	s_setprio 0
	s_setprio 1
	v_mfma_f32_16x16x32_bf16 v[50:53], v[160:163], v[202:205], v[50:53]
	v_mfma_f32_16x16x32_bf16 v[54:57], v[194:197], v[202:205], v[54:57]
	v_mfma_f32_16x16x32_bf16 v[34:37], v[160:163], v[210:213], v[34:37]
	v_mfma_f32_16x16x32_bf16 v[38:41], v[194:197], v[210:213], v[38:41]
	v_mfma_f32_16x16x32_bf16 v[18:21], v[160:163], v[218:221], v[18:21]
	v_mfma_f32_16x16x32_bf16 v[22:25], v[194:197], v[218:221], v[22:25]
	v_mfma_f32_16x16x32_bf16 v[6:9], v[160:163], v[226:229], v[6:9]
	v_mfma_f32_16x16x32_bf16 v[2:5], v[194:197], v[226:229], v[2:5]
	v_mfma_f32_16x16x32_bf16 v[50:53], v[190:193], v[206:209], v[50:53]
	v_mfma_f32_16x16x32_bf16 v[54:57], v[198:201], v[206:209], v[54:57]
	v_mfma_f32_16x16x32_bf16 v[34:37], v[190:193], v[214:217], v[34:37]
	v_mfma_f32_16x16x32_bf16 v[38:41], v[198:201], v[214:217], v[38:41]
	v_mfma_f32_16x16x32_bf16 v[18:21], v[190:193], v[222:225], v[18:21]
	v_mfma_f32_16x16x32_bf16 v[22:25], v[198:201], v[222:225], v[22:25]
	v_mfma_f32_16x16x32_bf16 v[6:9], v[190:193], v[230:233], v[6:9]
	v_mfma_f32_16x16x32_bf16 v[2:5], v[198:201], v[230:233], v[2:5]
	s_setprio 0
	s_barrier
	s_add_u32 s8, s8, 0x100
	s_addc_u32 s9, s9, 0
	s_add_u32 s71, s71, 0x100
	s_addc_u32 s75, s75, 0
	s_cmp_ge_i32 s78, s72
	s_mov_b32 s4, s78
	s_cbranch_scc0 .LBB0_95
	s_branch .Lk1_exit

; template <class Epi>
; __device__ __forceinline__ void gemm_phase(LAS unsigned char* lds, const Gemm g, const Epi& E) {
;     ...
;         Unit nxt; const bool has_next = get_unit(lds, ui + 1, nxt);
;         const char* nA = has_next ? (const char*)((nxt.sub & 1) ? g.A1 : g.A0) + (size_t)nxt.pm * tstep + (size_t)nxt.kt0 * kstep : cA; const char* nB = has_next ? (const char*)((nxt.sub & 1) ? g.B1 : g.B0) + (size_t)nxt.pn * tstep + (size_t)nxt.kt0 * kstep : cB;
;         const int nt = cur.nt;
;         for (int t = 0; t < nt; t += 2) {
;             const bool last = (t == nt - 2);
;             const char* a1 = cA + (size_t)(t + 1) * kstep;
;             const char* a2 = last ? nA : cA + (size_t)(t + 2) * kstep; const char* b2 = last ? nB : cB + (size_t)(t + 2) * kstep;
;             const char* a3 = a2 + kstep; const char* b3 = b2 + kstep;
;     ...
; #pragma unroll
;         for (int a = 0; a < 2; ++a)
; #pragma unroll
;             for (int b = 0; b < 2; ++b)
; #pragma unroll
;                 for (int m = 0; m < 4; ++m)
; #pragma unroll
;                     for (int n = 0; n < 2; ++n) acc[a][b][m][n] = (f32x4){0.f, 0.f, 0.f, 0.f};
.LBB0_93:
	s_ashr_i32 s69, s68, 31
	s_lshl_b64 s[10:11], s[68:69], 19
	s_add_u32 s2, s35, s10
	s_addc_u32 s12, s28, s11
	s_ashr_i32 s75, s74, 31
	s_lshl_b64 s[10:11], s[74:75], 7
	s_add_u32 s58, s2, s10
	s_addc_u32 s59, s12, s11
	s_ashr_i32 s71, s70, 31
	s_lshl_b64 s[12:13], s[70:71], 19
	s_add_u32 s2, s29, s12
	s_addc_u32 s12, s45, s13
	s_add_u32 s62, s2, s10
	s_addc_u32 s63, s12, s11
	s_cmp_lt_i32 s72, 1
	s_cbranch_scc1 .LBB0_268
	s_and_b64 s[10:11], s[6:7], exec
	s_cselect_b32 s2, s59, s9
	s_cselect_b32 s12, s58, s8
	s_cselect_b32 s13, s63, s5
	s_cselect_b32 s15, s62, s4
	s_add_i32 s69, s72, -2
	s_add_u32 s8, s8, 0x40080
	s_addc_u32 s9, s9, 0
	s_add_u32 s71, s4, 0x100
	v_mov_b32_e32 v2, 0
	s_addc_u32 s75, s5, 0
	s_mov_b32 s4, 0
	v_mov_b32_e32 v3, v2
	v_mov_b32_e32 v4, v2
	v_mov_b32_e32 v5, v2
	v_mov_b32_e32 v6, v2
	v_mov_b32_e32 v7, v2
	v_mov_b32_e32 v8, v2
	v_mov_b32_e32 v9, v2
	v_mov_b32_e32 v22, v2
	v_mov_b32_e32 v23, v2
	v_mov_b32_e32 v24, v2
	v_mov_b32_e32 v25, v2
	v_mov_b32_e32 v18, v2
	v_mov_b32_e32 v19, v2
	v_mov_b32_e32 v20, v2
	v_mov_b32_e32 v21, v2
	v_mov_b32_e32 v38, v2
	v_mov_b32_e32 v39, v2
	v_mov_b32_e32 v40, v2
	v_mov_b32_e32 v41, v2
	v_mov_b32_e32 v34, v2
	v_mov_b32_e32 v35, v2
	v_mov_b32_e32 v36, v2
	v_mov_b32_e32 v37, v2
	v_mov_b32_e32 v54, v2
	v_mov_b32_e32 v55, v2
	v_mov_b32_e32 v56, v2
	v_mov_b32_e32 v57, v2
	v_mov_b32_e32 v50, v2
	v_mov_b32_e32 v51, v2
	v_mov_b32_e32 v52, v2
	v_mov_b32_e32 v53, v2
	v_mov_b32_e32 v14, v2
	v_mov_b32_e32 v15, v2
	v_mov_b32_e32 v16, v2
	v_mov_b32_e32 v17, v2
	v_mov_b32_e32 v10, v2
	v_mov_b32_e32 v11, v2
	v_mov_b32_e32 v12, v2
	v_mov_b32_e32 v13, v2
	v_mov_b32_e32 v30, v2
	v_mov_b32_e32 v31, v2
	v_mov_b32_e32 v32, v2
	v_mov_b32_e32 v33, v2
	v_mov_b32_e32 v26, v2
	v_mov_b32_e32 v27, v2
	v_mov_b32_e32 v28, v2
	v_mov_b32_e32 v29, v2
	v_mov_b32_e32 v46, v2
	v_mov_b32_e32 v47, v2
	v_mov_b32_e32 v48, v2
	v_mov_b32_e32 v49, v2
	v_mov_b32_e32 v42, v2
	v_mov_b32_e32 v43, v2
	v_mov_b32_e32 v44, v2
	v_mov_b32_e32 v45, v2
	v_mov_b32_e32 v62, v2
	v_mov_b32_e32 v63, v2
	v_mov_b32_e32 v64, v2
	v_mov_b32_e32 v65, v2
	v_mov_b32_e32 v58, v2
	v_mov_b32_e32 v59, v2
	v_mov_b32_e32 v60, v2
	v_mov_b32_e32 v61, v2
	v_mov_b32_e32 v70, v2
	v_mov_b32_e32 v71, v2
	v_mov_b32_e32 v72, v2
	v_mov_b32_e32 v73, v2
	v_mov_b32_e32 v66, v2
	v_mov_b32_e32 v67, v2
	v_mov_b32_e32 v68, v2
	v_mov_b32_e32 v69, v2
	v_mov_b32_e32 v86, v2
	v_mov_b32_e32 v87, v2
	v_mov_b32_e32 v88, v2
	v_mov_b32_e32 v89, v2
	v_mov_b32_e32 v82, v2
	v_mov_b32_e32 v83, v2
	v_mov_b32_e32 v84, v2
	v_mov_b32_e32 v85, v2
	v_mov_b32_e32 v102, v2
	v_mov_b32_e32 v103, v2
	v_mov_b32_e32 v104, v2
	v_mov_b32_e32 v105, v2
	v_mov_b32_e32 v98, v2
	v_mov_b32_e32 v99, v2
	v_mov_b32_e32 v100, v2
	v_mov_b32_e32 v101, v2
	v_mov_b32_e32 v118, v2
	v_mov_b32_e32 v119, v2
	v_mov_b32_e32 v120, v2
	v_mov_b32_e32 v121, v2
	v_mov_b32_e32 v114, v2
	v_mov_b32_e32 v115, v2
	v_mov_b32_e32 v116, v2
	v_mov_b32_e32 v117, v2
	v_mov_b32_e32 v78, v2
	v_mov_b32_e32 v79, v2
	v_mov_b32_e32 v80, v2
	v_mov_b32_e32 v81, v2
	v_mov_b32_e32 v74, v2
	v_mov_b32_e32 v75, v2
	v_mov_b32_e32 v76, v2
	v_mov_b32_e32 v77, v2
	v_mov_b32_e32 v94, v2
	v_mov_b32_e32 v95, v2
	v_mov_b32_e32 v96, v2
	v_mov_b32_e32 v97, v2
	v_mov_b32_e32 v90, v2
	v_mov_b32_e32 v91, v2
	v_mov_b32_e32 v92, v2
	v_mov_b32_e32 v93, v2
	v_mov_b32_e32 v110, v2
	v_mov_b32_e32 v111, v2
	v_mov_b32_e32 v112, v2
	v_mov_b32_e32 v113, v2
	v_mov_b32_e32 v106, v2
	v_mov_b32_e32 v107, v2
	v_mov_b32_e32 v108, v2
	v_mov_b32_e32 v109, v2
	v_mov_b32_e32 v126, v2
	v_mov_b32_e32 v127, v2
	v_mov_b32_e32 v128, v2
	v_mov_b32_e32 v129, v2
	v_mov_b32_e32 v122, v2
	v_mov_b32_e32 v123, v2
	v_mov_b32_e32 v124, v2
	v_mov_b32_e32 v125, v2
	s_cmp_lg_u32 s32, 0
	s_cbranch_scc1 .Lk1_peel

; #define PG8_BAR __builtin_amdgcn_s_barrier()
; template <class Epi>
; __device__ __forceinline__ void gemm_phase(LAS unsigned char* lds, const Gemm g, const Epi& E) {
;     ...
;         if (wr == 0) PG8_BAR;
.Lk1_exit:
	s_and_b64 vcc, exec, s[66:67]
	s_cbranch_vccz .LBB0_98

; __device__ __forceinline__ unsigned pk2(float lo, float hi) { const f32x2_t v = {lo, hi}; const bf16v2_t b = __builtin_convertvector(v, bf16v2_t); return __builtin_bit_cast(unsigned, b); }
; __device__ __forceinline__ float sigmoidf_(float x) { return frcp(1.f + __expf(-x)); }
; __device__ __forceinline__ float siluf_(float x) { return x * sigmoidf_(x); }
; __device__ __forceinline__ float gelu_tanh_(float x) { const float y = 0.7978845608028654f * (x + 0.044715f * x * x * x); return x * sigmoidf_(2.f * y); }
;     __device__ __forceinline__ void operator()(const AccT& acc, const pg8::Unit& u, int wr, int wc, int fr_, int fq_) const {
;     ...
;             const int seg = (pn - 8) >> 2;
;             bf16_t* base = (bf16_t*)(ws + WS_SG + (size_t)seg * ((size_t)MROWS * D * 2));
;             const int cbase = 256 * ((pn - 8) & 3) + wc * 32 + 8 * fq;
; #pragma unroll
;             for (int ai = 0; ai < 2; ++ai)
; #pragma unroll
;                 for (int m = 0; m < 4; ++m) {
;                     const size_t row = (size_t)u.pm * 256 + rl0 + ai * 128 + m * 16;
; #pragma unroll
;                     for (int bj = 0; bj < 2; ++bj) {
;                         f32x4 a0 = acc[ai][bj][m][0], a1 = acc[ai][bj][m][1];
;                         if (seg == 0) { a0[0] = siluf_(a0[0]); a0[1] = siluf_(a0[1]); a0[2] = siluf_(a0[2]); a0[3] = siluf_(a0[3]); a1[0] = siluf_(a1[0]); a1[1] = siluf_(a1[1]); a1[2] = siluf_(a1[2]); a1[3] = siluf_(a1[3]); }
;                         else if (seg == 2) { a0[0] = gelu_tanh_(a0[0]); a0[1] = gelu_tanh_(a0[1]); a0[2] = gelu_tanh_(a0[2]); a0[3] = gelu_tanh_(a0[3]); a1[0] = gelu_tanh_(a1[0]); a1[1] = gelu_tanh_(a1[1]); a1[2] = gelu_tanh_(a1[2]); a1[3] = gelu_tanh_(a1[3]); }
;                         else if (seg >= 3) { a0[0] = sigmoidf_(a0[0]); a0[1] = sigmoidf_(a0[1]); a0[2] = sigmoidf_(a0[2]); a0[3] = sigmoidf_(a0[3]); a1[0] = sigmoidf_(a1[0]); a1[1] = sigmoidf_(a1[1]); a1[2] = sigmoidf_(a1[2]); a1[3] = sigmoidf_(a1[3]); }
;                         u32x4 o; o[0] = pk2(a0[0], a0[1]); o[1] = pk2(a0[2], a0[3]); o[2] = pk2(a1[0], a1[1]); o[3] = pk2(a1[2], a1[3]);
;                         *(u32x4*)(base + row * D + cbase + bj * 128) = o;
;                     }
.LBB0_98:
	s_mul_hi_i32 s2, s14, 0x38e38e39
	s_lshr_b32 s4, s2, 31
	s_ashr_i32 s69, s2, 1
	s_add_i32 s69, s69, s4
	s_mul_i32 s71, s69, -9
	v_mov_b32_e32 v156, v143
	v_mov_b32_e32 v130, v141
	s_add_i32 s71, s71, s14
	s_cmp_gt_i32 s52, 3
	v_add_u32_e32 v152, s92, v130
	s_mov_b64 s[4:5], -1
	s_cbranch_scc0 .LBB0_265
	s_cmp_gt_u32 s52, 7
	s_cbranch_scc0 .LBB0_261
	s_add_i32 s2, s52, -8
	s_lshr_b32 s4, s2, 2
	s_and_b32 s2, s2, 3
	s_mul_i32 s5, s4, 0x2400000
	s_add_u32 s78, s50, s5
	s_addc_u32 s79, s51, 0
	s_lshl_b32 s5, s14, 19
	s_add_u32 s78, s78, s5
	s_addc_u32 s79, s79, 0
	s_lshl_b32 s2, s2, 8
	s_add_i32 s2, s2, s33
	s_lshl_b32 s2, s2, 1
	s_add_u32 s78, s78, s2
	s_addc_u32 s79, s79, 0
	v_lshlrev_b32_e32 v153, 4, v156
	v_lshl_add_u32 v153, v152, 11, v153
	s_mov_b32 s8, 0xbfb8aa3b
	s_mov_b32 s10, 1.0
	s_mov_b32 s12, 0x3d372713
	s_mov_b32 s100, 0x3f4c422a
	s_cmp_eq_u32 s4, 0
	s_cbranch_scc1 .Lew_silu
	s_cmp_eq_u32 s4, 1
	s_cbranch_scc1 .Lew_copy
	s_cmp_eq_u32 s4, 2
	s_cbranch_scc1 .Lew_gelu
	v_pk_mul_f32 v[130:131], v[122:123], s[8:9] op_sel_hi:[1,0]
	v_pk_mul_f32 v[132:133], v[124:125], s[8:9] op_sel_hi:[1,0]
	v_pk_mul_f32 v[134:135], v[126:127], s[8:9] op_sel_hi:[1,0]
	v_pk_mul_f32 v[136:137], v[128:129], s[8:9] op_sel_hi:[1,0]
	v_exp_f32_e32 v130, v130
	v_exp_f32_e32 v131, v131
	v_exp_f32_e32 v132, v132
	v_exp_f32_e32 v133, v133
	v_exp_f32_e32 v134, v134
	v_exp_f32_e32 v135, v135
	v_exp_f32_e32 v136, v136
	v_exp_f32_e32 v137, v137
	v_pk_add_f32 v[130:131], v[130:131], s[10:11] op_sel_hi:[1,0]
	v_pk_add_f32 v[132:133], v[132:133], s[10:11] op_sel_hi:[1,0]
	v_pk_add_f32 v[134:135], v[134:135], s[10:11] op_sel_hi:[1,0]
	v_pk_add_f32 v[136:137], v[136:137], s[10:11] op_sel_hi:[1,0]
	v_rcp_f32_e32 v130, v130
	v_rcp_f32_e32 v131, v131
	v_rcp_f32_e32 v132, v132
	v_rcp_f32_e32 v133, v133
	v_rcp_f32_e32 v134, v134
	v_rcp_f32_e32 v135, v135
	v_rcp_f32_e32 v136, v136
	v_rcp_f32_e32 v137, v137
	v_cvt_pk_bf16_f32 v122, v130, v131
	v_cvt_pk_bf16_f32 v123, v132, v133
	v_cvt_pk_bf16_f32 v124, v134, v135
	v_cvt_pk_bf16_f32 v125, v136, v137
	global_store_dwordx4 v153, v[122:125], s[78:79]
	v_pk_mul_f32 v[130:131], v[114:115], s[8:9] op_sel_hi:[1,0]
	v_pk_mul_f32 v[132:133], v[116:117], s[8:9] op_sel_hi:[1,0]
	v_pk_mul_f32 v[134:135], v[118:119], s[8:9] op_sel_hi:[1,0]
	v_pk_mul_f32 v[136:137], v[120:121], s[8:9] op_sel_hi:[1,0]
	v_exp_f32_e32 v130, v130
	v_exp_f32_e32 v131, v131
	v_exp_f32_e32 v132, v132
	v_exp_f32_e32 v133, v133
	v_exp_f32_e32 v134, v134
	v_exp_f32_e32 v135, v135
	v_exp_f32_e32 v136, v136
	v_exp_f32_e32 v137, v137
	v_pk_add_f32 v[130:131], v[130:131], s[10:11] op_sel_hi:[1,0]
	v_pk_add_f32 v[132:133], v[132:133], s[10:11] op_sel_hi:[1,0]
	v_pk_add_f32 v[134:135], v[134:135], s[10:11] op_sel_hi:[1,0]
	v_pk_add_f32 v[136:137], v[136:137], s[10:11] op_sel_hi:[1,0]
	v_rcp_f32_e32 v130, v130
	v_rcp_f32_e32 v131, v131
	v_rcp_f32_e32 v132, v132
	v_rcp_f32_e32 v133, v133
	v_rcp_f32_e32 v134, v134
	v_rcp_f32_e32 v135, v135
	v_rcp_f32_e32 v136, v136
	v_rcp_f32_e32 v137, v137
	v_cvt_pk_bf16_f32 v114, v130, v131
	v_cvt_pk_bf16_f32 v115, v132, v133
	v_cvt_pk_bf16_f32 v116, v134, v135
	v_cvt_pk_bf16_f32 v117, v136, v137
	global_store_dwordx4 v153, v[114:117], s[78:79] offset:256
	s_add_u32 s98, s78, 0x8000
	s_addc_u32 s99, s79, 0
	v_pk_mul_f32 v[130:131], v[106:107], s[8:9] op_sel_hi:[1,0]
	v_pk_mul_f32 v[132:133], v[108:109], s[8:9] op_sel_hi:[1,0]
	v_pk_mul_f32 v[134:135], v[110:111], s[8:9] op_sel_hi:[1,0]
	v_pk_mul_f32 v[136:137], v[112:113], s[8:9] op_sel_hi:[1,0]
	v_exp_f32_e32 v130, v130
	v_exp_f32_e32 v131, v131
	v_exp_f32_e32 v132, v132
	v_exp_f32_e32 v133, v133
	v_exp_f32_e32 v134, v134
	v_exp_f32_e32 v135, v135
	v_exp_f32_e32 v136, v136
	v_exp_f32_e32 v137, v137
	v_pk_add_f32 v[130:131], v[130:131], s[10:11] op_sel_hi:[1,0]
	v_pk_add_f32 v[132:133], v[132:133], s[10:11] op_sel_hi:[1,0]
	v_pk_add_f32 v[134:135], v[134:135], s[10:11] op_sel_hi:[1,0]
	v_pk_add_f32 v[136:137], v[136:137], s[10:11] op_sel_hi:[1,0]
	v_rcp_f32_e32 v130, v130
	v_rcp_f32_e32 v131, v131
	v_rcp_f32_e32 v132, v132
	v_rcp_f32_e32 v133, v133
	v_rcp_f32_e32 v134, v134
	v_rcp_f32_e32 v135, v135
	v_rcp_f32_e32 v136, v136
	v_rcp_f32_e32 v137, v137
	v_cvt_pk_bf16_f32 v106, v130, v131
	v_cvt_pk_bf16_f32 v107, v132, v133
	v_cvt_pk_bf16_f32 v108, v134, v135
	v_cvt_pk_bf16_f32 v109, v136, v137
	global_store_dwordx4 v153, v[106:109], s[98:99]
	v_pk_mul_f32 v[130:131], v[98:99], s[8:9] op_sel_hi:[1,0]
	v_pk_mul_f32 v[132:133], v[100:101], s[8:9] op_sel_hi:[1,0]
	v_pk_mul_f32 v[134:135], v[102:103], s[8:9] op_sel_hi:[1,0]
	v_pk_mul_f32 v[136:137], v[104:105], s[8:9] op_sel_hi:[1,0]
	v_exp_f32_e32 v130, v130
	v_exp_f32_e32 v131, v131
	v_exp_f32_e32 v132, v132
	v_exp_f32_e32 v133, v133
	v_exp_f32_e32 v134, v134
	v_exp_f32_e32 v135, v135
	v_exp_f32_e32 v136, v136
	v_exp_f32_e32 v137, v137
	v_pk_add_f32 v[130:131], v[130:131], s[10:11] op_sel_hi:[1,0]
	v_pk_add_f32 v[132:133], v[132:133], s[10:11] op_sel_hi:[1,0]
	v_pk_add_f32 v[134:135], v[134:135], s[10:11] op_sel_hi:[1,0]
	v_pk_add_f32 v[136:137], v[136:137], s[10:11] op_sel_hi:[1,0]
	v_rcp_f32_e32 v130, v130
	v_rcp_f32_e32 v131, v131
	v_rcp_f32_e32 v132, v132
	v_rcp_f32_e32 v133, v133
	v_rcp_f32_e32 v134, v134
	v_rcp_f32_e32 v135, v135
	v_rcp_f32_e32 v136, v136
	v_rcp_f32_e32 v137, v137
	v_cvt_pk_bf16_f32 v98, v130, v131
	v_cvt_pk_bf16_f32 v99, v132, v133
	v_cvt_pk_bf16_f32 v100, v134, v135
	v_cvt_pk_bf16_f32 v101, v136, v137
	global_store_dwordx4 v153, v[98:101], s[98:99] offset:256
	s_add_u32 s98, s78, 0x10000
	s_addc_u32 s99, s79, 0
	v_pk_mul_f32 v[130:131], v[90:91], s[8:9] op_sel_hi:[1,0]
	v_pk_mul_f32 v[132:133], v[92:93], s[8:9] op_sel_hi:[1,0]
; __device__ __forceinline__ unsigned pk2(float lo, float hi) { const f32x2_t v = {lo, hi}; const bf16v2_t b = __builtin_convertvector(v, bf16v2_t); return __builtin_bit_cast(unsigned, b); }
; __device__ __forceinline__ float sigmoidf_(float x) { return frcp(1.f + __expf(-x)); }
;     __device__ __forceinline__ void operator()(const AccT& acc, const pg8::Unit& u, int wr, int wc, int fr_, int fq_) const {
;     ...
;                         else if (seg >= 3) { a0[0] = sigmoidf_(a0[0]); a0[1] = sigmoidf_(a0[1]); a0[2] = sigmoidf_(a0[2]); a0[3] = sigmoidf_(a0[3]); a1[0] = sigmoidf_(a1[0]); a1[1] = sigmoidf_(a1[1]); a1[2] = sigmoidf_(a1[2]); a1[3] = sigmoidf_(a1[3]); }
;                         u32x4 o; o[0] = pk2(a0[0], a0[1]); o[1] = pk2(a0[2], a0[3]); o[2] = pk2(a1[0], a1[1]); o[3] = pk2(a1[2], a1[3]);
;                         *(u32x4*)(base + row * D + cbase + bj * 128) = o;
	v_pk_mul_f32 v[134:135], v[94:95], s[8:9] op_sel_hi:[1,0]
	v_pk_mul_f32 v[136:137], v[96:97], s[8:9] op_sel_hi:[1,0]
	v_exp_f32_e32 v130, v130
	v_exp_f32_e32 v131, v131
	v_exp_f32_e32 v132, v132
	v_exp_f32_e32 v133, v133
	v_exp_f32_e32 v134, v134
	v_exp_f32_e32 v135, v135
	v_exp_f32_e32 v136, v136
	v_exp_f32_e32 v137, v137
	v_pk_add_f32 v[130:131], v[130:131], s[10:11] op_sel_hi:[1,0]
	v_pk_add_f32 v[132:133], v[132:133], s[10:11] op_sel_hi:[1,0]
	v_pk_add_f32 v[134:135], v[134:135], s[10:11] op_sel_hi:[1,0]
	v_pk_add_f32 v[136:137], v[136:137], s[10:11] op_sel_hi:[1,0]
	v_rcp_f32_e32 v130, v130
	v_rcp_f32_e32 v131, v131
	v_rcp_f32_e32 v132, v132
	v_rcp_f32_e32 v133, v133
	v_rcp_f32_e32 v134, v134
	v_rcp_f32_e32 v135, v135
	v_rcp_f32_e32 v136, v136
	v_rcp_f32_e32 v137, v137
	v_cvt_pk_bf16_f32 v90, v130, v131
	v_cvt_pk_bf16_f32 v91, v132, v133
	v_cvt_pk_bf16_f32 v92, v134, v135
	v_cvt_pk_bf16_f32 v93, v136, v137
	global_store_dwordx4 v153, v[90:93], s[98:99]
	v_pk_mul_f32 v[130:131], v[82:83], s[8:9] op_sel_hi:[1,0]
	v_pk_mul_f32 v[132:133], v[84:85], s[8:9] op_sel_hi:[1,0]
	v_pk_mul_f32 v[134:135], v[86:87], s[8:9] op_sel_hi:[1,0]
	v_pk_mul_f32 v[136:137], v[88:89], s[8:9] op_sel_hi:[1,0]
	v_exp_f32_e32 v130, v130
	v_exp_f32_e32 v131, v131
	v_exp_f32_e32 v132, v132
	v_exp_f32_e32 v133, v133
	v_exp_f32_e32 v134, v134
	v_exp_f32_e32 v135, v135
	v_exp_f32_e32 v136, v136
	v_exp_f32_e32 v137, v137
	v_pk_add_f32 v[130:131], v[130:131], s[10:11] op_sel_hi:[1,0]
	v_pk_add_f32 v[132:133], v[132:133], s[10:11] op_sel_hi:[1,0]
	v_pk_add_f32 v[134:135], v[134:135], s[10:11] op_sel_hi:[1,0]
	v_pk_add_f32 v[136:137], v[136:137], s[10:11] op_sel_hi:[1,0]
	v_rcp_f32_e32 v130, v130
	v_rcp_f32_e32 v131, v131
	v_rcp_f32_e32 v132, v132
	v_rcp_f32_e32 v133, v133
	v_rcp_f32_e32 v134, v134
	v_rcp_f32_e32 v135, v135
	v_rcp_f32_e32 v136, v136
	v_rcp_f32_e32 v137, v137
	v_cvt_pk_bf16_f32 v82, v130, v131
	v_cvt_pk_bf16_f32 v83, v132, v133
	v_cvt_pk_bf16_f32 v84, v134, v135
	v_cvt_pk_bf16_f32 v85, v136, v137
	global_store_dwordx4 v153, v[82:85], s[98:99] offset:256
	s_add_u32 s98, s78, 0x18000
	s_addc_u32 s99, s79, 0
	v_pk_mul_f32 v[130:131], v[74:75], s[8:9] op_sel_hi:[1,0]
	v_pk_mul_f32 v[132:133], v[76:77], s[8:9] op_sel_hi:[1,0]
	v_pk_mul_f32 v[134:135], v[78:79], s[8:9] op_sel_hi:[1,0]
	v_pk_mul_f32 v[136:137], v[80:81], s[8:9] op_sel_hi:[1,0]
	v_exp_f32_e32 v130, v130
	v_exp_f32_e32 v131, v131
	v_exp_f32_e32 v132, v132
	v_exp_f32_e32 v133, v133
	v_exp_f32_e32 v134, v134
	v_exp_f32_e32 v135, v135
	v_exp_f32_e32 v136, v136
	v_exp_f32_e32 v137, v137
	v_pk_add_f32 v[130:131], v[130:131], s[10:11] op_sel_hi:[1,0]
	v_pk_add_f32 v[132:133], v[132:133], s[10:11] op_sel_hi:[1,0]
	v_pk_add_f32 v[134:135], v[134:135], s[10:11] op_sel_hi:[1,0]
	v_pk_add_f32 v[136:137], v[136:137], s[10:11] op_sel_hi:[1,0]
	v_rcp_f32_e32 v130, v130
	v_rcp_f32_e32 v131, v131
	v_rcp_f32_e32 v132, v132
	v_rcp_f32_e32 v133, v133
	v_rcp_f32_e32 v134, v134
	v_rcp_f32_e32 v135, v135
	v_rcp_f32_e32 v136, v136
	v_rcp_f32_e32 v137, v137
	v_cvt_pk_bf16_f32 v74, v130, v131
	v_cvt_pk_bf16_f32 v75, v132, v133
	v_cvt_pk_bf16_f32 v76, v134, v135
	v_cvt_pk_bf16_f32 v77, v136, v137
	global_store_dwordx4 v153, v[74:77], s[98:99]
	v_pk_mul_f32 v[130:131], v[66:67], s[8:9] op_sel_hi:[1,0]
	v_pk_mul_f32 v[132:133], v[68:69], s[8:9] op_sel_hi:[1,0]
	v_pk_mul_f32 v[134:135], v[70:71], s[8:9] op_sel_hi:[1,0]
	v_pk_mul_f32 v[136:137], v[72:73], s[8:9] op_sel_hi:[1,0]
	v_exp_f32_e32 v130, v130
	v_exp_f32_e32 v131, v131
	v_exp_f32_e32 v132, v132
	v_exp_f32_e32 v133, v133
	v_exp_f32_e32 v134, v134
	v_exp_f32_e32 v135, v135
	v_exp_f32_e32 v136, v136
	v_exp_f32_e32 v137, v137
	v_pk_add_f32 v[130:131], v[130:131], s[10:11] op_sel_hi:[1,0]
	v_pk_add_f32 v[132:133], v[132:133], s[10:11] op_sel_hi:[1,0]
	v_pk_add_f32 v[134:135], v[134:135], s[10:11] op_sel_hi:[1,0]
	v_pk_add_f32 v[136:137], v[136:137], s[10:11] op_sel_hi:[1,0]
	v_rcp_f32_e32 v130, v130
	v_rcp_f32_e32 v131, v131
	v_rcp_f32_e32 v132, v132
	v_rcp_f32_e32 v133, v133
	v_rcp_f32_e32 v134, v134
	v_rcp_f32_e32 v135, v135
	v_rcp_f32_e32 v136, v136
	v_rcp_f32_e32 v137, v137
	v_cvt_pk_bf16_f32 v66, v130, v131
	v_cvt_pk_bf16_f32 v67, v132, v133
	v_cvt_pk_bf16_f32 v68, v134, v135
	v_cvt_pk_bf16_f32 v69, v136, v137
	global_store_dwordx4 v153, v[66:69], s[98:99] offset:256
	s_add_u32 s98, s78, 0x40000
	s_addc_u32 s99, s79, 0
	v_pk_mul_f32 v[130:131], v[58:59], s[8:9] op_sel_hi:[1,0]
	v_pk_mul_f32 v[132:133], v[60:61], s[8:9] op_sel_hi:[1,0]
	v_pk_mul_f32 v[134:135], v[62:63], s[8:9] op_sel_hi:[1,0]
	v_pk_mul_f32 v[136:137], v[64:65], s[8:9] op_sel_hi:[1,0]
	v_exp_f32_e32 v130, v130
	v_exp_f32_e32 v131, v131
	v_exp_f32_e32 v132, v132
	v_exp_f32_e32 v133, v133
	v_exp_f32_e32 v134, v134
	v_exp_f32_e32 v135, v135
	v_exp_f32_e32 v136, v136
	v_exp_f32_e32 v137, v137
	v_pk_add_f32 v[130:131], v[130:131], s[10:11] op_sel_hi:[1,0]
	v_pk_add_f32 v[132:133], v[132:133], s[10:11] op_sel_hi:[1,0]
	v_pk_add_f32 v[134:135], v[134:135], s[10:11] op_sel_hi:[1,0]
	v_pk_add_f32 v[136:137], v[136:137], s[10:11] op_sel_hi:[1,0]
	v_rcp_f32_e32 v130, v130
	v_rcp_f32_e32 v131, v131
	v_rcp_f32_e32 v132, v132
	v_rcp_f32_e32 v133, v133
	v_rcp_f32_e32 v134, v134
	v_rcp_f32_e32 v135, v135
	v_rcp_f32_e32 v136, v136
	v_rcp_f32_e32 v137, v137
	v_cvt_pk_bf16_f32 v58, v130, v131
	v_cvt_pk_bf16_f32 v59, v132, v133
	v_cvt_pk_bf16_f32 v60, v134, v135
	v_cvt_pk_bf16_f32 v61, v136, v137
	global_store_dwordx4 v153, v[58:61], s[98:99]
	v_pk_mul_f32 v[130:131], v[50:51], s[8:9] op_sel_hi:[1,0]
	v_pk_mul_f32 v[132:133], v[52:53], s[8:9] op_sel_hi:[1,0]
	v_pk_mul_f32 v[134:135], v[54:55], s[8:9] op_sel_hi:[1,0]
; __device__ __forceinline__ unsigned pk2(float lo, float hi) { const f32x2_t v = {lo, hi}; const bf16v2_t b = __builtin_convertvector(v, bf16v2_t); return __builtin_bit_cast(unsigned, b); }
; __device__ __forceinline__ float sigmoidf_(float x) { return frcp(1.f + __expf(-x)); }
;     __device__ __forceinline__ void operator()(const AccT& acc, const pg8::Unit& u, int wr, int wc, int fr_, int fq_) const {
;     ...
;                         else if (seg >= 3) { a0[0] = sigmoidf_(a0[0]); a0[1] = sigmoidf_(a0[1]); a0[2] = sigmoidf_(a0[2]); a0[3] = sigmoidf_(a0[3]); a1[0] = sigmoidf_(a1[0]); a1[1] = sigmoidf_(a1[1]); a1[2] = sigmoidf_(a1[2]); a1[3] = sigmoidf_(a1[3]); }
;                         u32x4 o; o[0] = pk2(a0[0], a0[1]); o[1] = pk2(a0[2], a0[3]); o[2] = pk2(a1[0], a1[1]); o[3] = pk2(a1[2], a1[3]);
;                         *(u32x4*)(base + row * D + cbase + bj * 128) = o;
	v_pk_mul_f32 v[136:137], v[56:57], s[8:9] op_sel_hi:[1,0]
	v_exp_f32_e32 v130, v130
	v_exp_f32_e32 v131, v131
	v_exp_f32_e32 v132, v132
	v_exp_f32_e32 v133, v133
	v_exp_f32_e32 v134, v134
	v_exp_f32_e32 v135, v135
	v_exp_f32_e32 v136, v136
	v_exp_f32_e32 v137, v137
	v_pk_add_f32 v[130:131], v[130:131], s[10:11] op_sel_hi:[1,0]
	v_pk_add_f32 v[132:133], v[132:133], s[10:11] op_sel_hi:[1,0]
	v_pk_add_f32 v[134:135], v[134:135], s[10:11] op_sel_hi:[1,0]
	v_pk_add_f32 v[136:137], v[136:137], s[10:11] op_sel_hi:[1,0]
	v_rcp_f32_e32 v130, v130
	v_rcp_f32_e32 v131, v131
	v_rcp_f32_e32 v132, v132
	v_rcp_f32_e32 v133, v133
	v_rcp_f32_e32 v134, v134
	v_rcp_f32_e32 v135, v135
	v_rcp_f32_e32 v136, v136
	v_rcp_f32_e32 v137, v137
	v_cvt_pk_bf16_f32 v50, v130, v131
	v_cvt_pk_bf16_f32 v51, v132, v133
	v_cvt_pk_bf16_f32 v52, v134, v135
	v_cvt_pk_bf16_f32 v53, v136, v137
	global_store_dwordx4 v153, v[50:53], s[98:99] offset:256
	s_add_u32 s98, s78, 0x48000
	s_addc_u32 s99, s79, 0
	v_pk_mul_f32 v[130:131], v[42:43], s[8:9] op_sel_hi:[1,0]
	v_pk_mul_f32 v[132:133], v[44:45], s[8:9] op_sel_hi:[1,0]
	v_pk_mul_f32 v[134:135], v[46:47], s[8:9] op_sel_hi:[1,0]
	v_pk_mul_f32 v[136:137], v[48:49], s[8:9] op_sel_hi:[1,0]
	v_exp_f32_e32 v130, v130
	v_exp_f32_e32 v131, v131
	v_exp_f32_e32 v132, v132
	v_exp_f32_e32 v133, v133
	v_exp_f32_e32 v134, v134
	v_exp_f32_e32 v135, v135
	v_exp_f32_e32 v136, v136
	v_exp_f32_e32 v137, v137
	v_pk_add_f32 v[130:131], v[130:131], s[10:11] op_sel_hi:[1,0]
	v_pk_add_f32 v[132:133], v[132:133], s[10:11] op_sel_hi:[1,0]
	v_pk_add_f32 v[134:135], v[134:135], s[10:11] op_sel_hi:[1,0]
	v_pk_add_f32 v[136:137], v[136:137], s[10:11] op_sel_hi:[1,0]
	v_rcp_f32_e32 v130, v130
	v_rcp_f32_e32 v131, v131
	v_rcp_f32_e32 v132, v132
	v_rcp_f32_e32 v133, v133
	v_rcp_f32_e32 v134, v134
	v_rcp_f32_e32 v135, v135
	v_rcp_f32_e32 v136, v136
	v_rcp_f32_e32 v137, v137
	v_cvt_pk_bf16_f32 v42, v130, v131
	v_cvt_pk_bf16_f32 v43, v132, v133
	v_cvt_pk_bf16_f32 v44, v134, v135
	v_cvt_pk_bf16_f32 v45, v136, v137
	global_store_dwordx4 v153, v[42:45], s[98:99]
	v_pk_mul_f32 v[130:131], v[34:35], s[8:9] op_sel_hi:[1,0]
	v_pk_mul_f32 v[132:133], v[36:37], s[8:9] op_sel_hi:[1,0]
	v_pk_mul_f32 v[134:135], v[38:39], s[8:9] op_sel_hi:[1,0]
	v_pk_mul_f32 v[136:137], v[40:41], s[8:9] op_sel_hi:[1,0]
	v_exp_f32_e32 v130, v130
	v_exp_f32_e32 v131, v131
	v_exp_f32_e32 v132, v132
	v_exp_f32_e32 v133, v133
	v_exp_f32_e32 v134, v134
	v_exp_f32_e32 v135, v135
	v_exp_f32_e32 v136, v136
	v_exp_f32_e32 v137, v137
	v_pk_add_f32 v[130:131], v[130:131], s[10:11] op_sel_hi:[1,0]
	v_pk_add_f32 v[132:133], v[132:133], s[10:11] op_sel_hi:[1,0]
	v_pk_add_f32 v[134:135], v[134:135], s[10:11] op_sel_hi:[1,0]
	v_pk_add_f32 v[136:137], v[136:137], s[10:11] op_sel_hi:[1,0]
	v_rcp_f32_e32 v130, v130
	v_rcp_f32_e32 v131, v131
	v_rcp_f32_e32 v132, v132
	v_rcp_f32_e32 v133, v133
	v_rcp_f32_e32 v134, v134
	v_rcp_f32_e32 v135, v135
	v_rcp_f32_e32 v136, v136
	v_rcp_f32_e32 v137, v137
	v_cvt_pk_bf16_f32 v34, v130, v131
	v_cvt_pk_bf16_f32 v35, v132, v133
	v_cvt_pk_bf16_f32 v36, v134, v135
	v_cvt_pk_bf16_f32 v37, v136, v137
	global_store_dwordx4 v153, v[34:37], s[98:99] offset:256
	s_add_u32 s98, s78, 0x50000
	s_addc_u32 s99, s79, 0
	v_pk_mul_f32 v[130:131], v[26:27], s[8:9] op_sel_hi:[1,0]
	v_pk_mul_f32 v[132:133], v[28:29], s[8:9] op_sel_hi:[1,0]
	v_pk_mul_f32 v[134:135], v[30:31], s[8:9] op_sel_hi:[1,0]
	v_pk_mul_f32 v[136:137], v[32:33], s[8:9] op_sel_hi:[1,0]
	v_exp_f32_e32 v130, v130
	v_exp_f32_e32 v131, v131
	v_exp_f32_e32 v132, v132
	v_exp_f32_e32 v133, v133
	v_exp_f32_e32 v134, v134
	v_exp_f32_e32 v135, v135
	v_exp_f32_e32 v136, v136
	v_exp_f32_e32 v137, v137
	v_pk_add_f32 v[130:131], v[130:131], s[10:11] op_sel_hi:[1,0]
	v_pk_add_f32 v[132:133], v[132:133], s[10:11] op_sel_hi:[1,0]
	v_pk_add_f32 v[134:135], v[134:135], s[10:11] op_sel_hi:[1,0]
	v_pk_add_f32 v[136:137], v[136:137], s[10:11] op_sel_hi:[1,0]
	v_rcp_f32_e32 v130, v130
	v_rcp_f32_e32 v131, v131
	v_rcp_f32_e32 v132, v132
	v_rcp_f32_e32 v133, v133
	v_rcp_f32_e32 v134, v134
	v_rcp_f32_e32 v135, v135
	v_rcp_f32_e32 v136, v136
	v_rcp_f32_e32 v137, v137
	v_cvt_pk_bf16_f32 v26, v130, v131
	v_cvt_pk_bf16_f32 v27, v132, v133
	v_cvt_pk_bf16_f32 v28, v134, v135
	v_cvt_pk_bf16_f32 v29, v136, v137
	global_store_dwordx4 v153, v[26:29], s[98:99]
	v_pk_mul_f32 v[130:131], v[18:19], s[8:9] op_sel_hi:[1,0]
	v_pk_mul_f32 v[132:133], v[20:21], s[8:9] op_sel_hi:[1,0]
	v_pk_mul_f32 v[134:135], v[22:23], s[8:9] op_sel_hi:[1,0]
	v_pk_mul_f32 v[136:137], v[24:25], s[8:9] op_sel_hi:[1,0]
	v_exp_f32_e32 v130, v130
	v_exp_f32_e32 v131, v131
	v_exp_f32_e32 v132, v132
	v_exp_f32_e32 v133, v133
	v_exp_f32_e32 v134, v134
	v_exp_f32_e32 v135, v135
	v_exp_f32_e32 v136, v136
	v_exp_f32_e32 v137, v137
	v_pk_add_f32 v[130:131], v[130:131], s[10:11] op_sel_hi:[1,0]
	v_pk_add_f32 v[132:133], v[132:133], s[10:11] op_sel_hi:[1,0]
	v_pk_add_f32 v[134:135], v[134:135], s[10:11] op_sel_hi:[1,0]
	v_pk_add_f32 v[136:137], v[136:137], s[10:11] op_sel_hi:[1,0]
	v_rcp_f32_e32 v130, v130
	v_rcp_f32_e32 v131, v131
	v_rcp_f32_e32 v132, v132
	v_rcp_f32_e32 v133, v133
	v_rcp_f32_e32 v134, v134
	v_rcp_f32_e32 v135, v135
	v_rcp_f32_e32 v136, v136
	v_rcp_f32_e32 v137, v137
	v_cvt_pk_bf16_f32 v18, v130, v131
	v_cvt_pk_bf16_f32 v19, v132, v133
	v_cvt_pk_bf16_f32 v20, v134, v135
	v_cvt_pk_bf16_f32 v21, v136, v137
	global_store_dwordx4 v153, v[18:21], s[98:99] offset:256
	s_add_u32 s98, s78, 0x58000
	s_addc_u32 s99, s79, 0
	v_pk_mul_f32 v[130:131], v[10:11], s[8:9] op_sel_hi:[1,0]
	v_pk_mul_f32 v[132:133], v[12:13], s[8:9] op_sel_hi:[1,0]
	v_pk_mul_f32 v[134:135], v[14:15], s[8:9] op_sel_hi:[1,0]
; __device__ __forceinline__ unsigned pk2(float lo, float hi) { const f32x2_t v = {lo, hi}; const bf16v2_t b = __builtin_convertvector(v, bf16v2_t); return __builtin_bit_cast(unsigned, b); }
; __device__ __forceinline__ float sigmoidf_(float x) { return frcp(1.f + __expf(-x)); }
; __device__ __forceinline__ float siluf_(float x) { return x * sigmoidf_(x); }
; __device__ __forceinline__ float gelu_tanh_(float x) { const float y = 0.7978845608028654f * (x + 0.044715f * x * x * x); return x * sigmoidf_(2.f * y); }
;     __device__ __forceinline__ void operator()(const AccT& acc, const pg8::Unit& u, int wr, int wc, int fr_, int fq_) const {
;     ...
;                         if (seg == 0) { a0[0] = siluf_(a0[0]); a0[1] = siluf_(a0[1]); a0[2] = siluf_(a0[2]); a0[3] = siluf_(a0[3]); a1[0] = siluf_(a1[0]); a1[1] = siluf_(a1[1]); a1[2] = siluf_(a1[2]); a1[3] = siluf_(a1[3]); }
;                         else if (seg == 2) { a0[0] = gelu_tanh_(a0[0]); a0[1] = gelu_tanh_(a0[1]); a0[2] = gelu_tanh_(a0[2]); a0[3] = gelu_tanh_(a0[3]); a1[0] = gelu_tanh_(a1[0]); a1[1] = gelu_tanh_(a1[1]); a1[2] = gelu_tanh_(a1[2]); a1[3] = gelu_tanh_(a1[3]); }
;                         else if (seg >= 3) { a0[0] = sigmoidf_(a0[0]); a0[1] = sigmoidf_(a0[1]); a0[2] = sigmoidf_(a0[2]); a0[3] = sigmoidf_(a0[3]); a1[0] = sigmoidf_(a1[0]); a1[1] = sigmoidf_(a1[1]); a1[2] = sigmoidf_(a1[2]); a1[3] = sigmoidf_(a1[3]); }
;                         u32x4 o; o[0] = pk2(a0[0], a0[1]); o[1] = pk2(a0[2], a0[3]); o[2] = pk2(a1[0], a1[1]); o[3] = pk2(a1[2], a1[3]);
;                         *(u32x4*)(base + row * D + cbase + bj * 128) = o;
	v_pk_mul_f32 v[136:137], v[16:17], s[8:9] op_sel_hi:[1,0]
	v_exp_f32_e32 v130, v130
	v_exp_f32_e32 v131, v131
	v_exp_f32_e32 v132, v132
	v_exp_f32_e32 v133, v133
	v_exp_f32_e32 v134, v134
	v_exp_f32_e32 v135, v135
	v_exp_f32_e32 v136, v136
	v_exp_f32_e32 v137, v137
	v_pk_add_f32 v[130:131], v[130:131], s[10:11] op_sel_hi:[1,0]
	v_pk_add_f32 v[132:133], v[132:133], s[10:11] op_sel_hi:[1,0]
	v_pk_add_f32 v[134:135], v[134:135], s[10:11] op_sel_hi:[1,0]
	v_pk_add_f32 v[136:137], v[136:137], s[10:11] op_sel_hi:[1,0]
	v_rcp_f32_e32 v130, v130
	v_rcp_f32_e32 v131, v131
	v_rcp_f32_e32 v132, v132
	v_rcp_f32_e32 v133, v133
	v_rcp_f32_e32 v134, v134
	v_rcp_f32_e32 v135, v135
	v_rcp_f32_e32 v136, v136
	v_rcp_f32_e32 v137, v137
	v_cvt_pk_bf16_f32 v10, v130, v131
	v_cvt_pk_bf16_f32 v11, v132, v133
	v_cvt_pk_bf16_f32 v12, v134, v135
	v_cvt_pk_bf16_f32 v13, v136, v137
	global_store_dwordx4 v153, v[10:13], s[98:99]
	v_pk_mul_f32 v[130:131], v[6:7], s[8:9] op_sel_hi:[1,0]
	v_pk_mul_f32 v[132:133], v[8:9], s[8:9] op_sel_hi:[1,0]
	v_pk_mul_f32 v[134:135], v[2:3], s[8:9] op_sel_hi:[1,0]
	v_pk_mul_f32 v[136:137], v[4:5], s[8:9] op_sel_hi:[1,0]
	v_exp_f32_e32 v130, v130
	v_exp_f32_e32 v131, v131
	v_exp_f32_e32 v132, v132
	v_exp_f32_e32 v133, v133
	v_exp_f32_e32 v134, v134
	v_exp_f32_e32 v135, v135
	v_exp_f32_e32 v136, v136
	v_exp_f32_e32 v137, v137
	v_pk_add_f32 v[130:131], v[130:131], s[10:11] op_sel_hi:[1,0]
	v_pk_add_f32 v[132:133], v[132:133], s[10:11] op_sel_hi:[1,0]
	v_pk_add_f32 v[134:135], v[134:135], s[10:11] op_sel_hi:[1,0]
	v_pk_add_f32 v[136:137], v[136:137], s[10:11] op_sel_hi:[1,0]
	v_rcp_f32_e32 v130, v130
	v_rcp_f32_e32 v131, v131
	v_rcp_f32_e32 v132, v132
	v_rcp_f32_e32 v133, v133
	v_rcp_f32_e32 v134, v134
	v_rcp_f32_e32 v135, v135
	v_rcp_f32_e32 v136, v136
	v_rcp_f32_e32 v137, v137
	v_cvt_pk_bf16_f32 v6, v130, v131
	v_cvt_pk_bf16_f32 v7, v132, v133
	v_cvt_pk_bf16_f32 v8, v134, v135
	v_cvt_pk_bf16_f32 v9, v136, v137
	global_store_dwordx4 v153, v[6:9], s[98:99] offset:256
	s_mov_b32 s32, 1
	s_branch .LBB0_264
.Lew_silu:
	v_pk_mul_f32 v[130:131], v[122:123], s[8:9] op_sel_hi:[1,0]
	v_pk_mul_f32 v[132:133], v[124:125], s[8:9] op_sel_hi:[1,0]
	v_pk_mul_f32 v[134:135], v[126:127], s[8:9] op_sel_hi:[1,0]
	v_pk_mul_f32 v[136:137], v[128:129], s[8:9] op_sel_hi:[1,0]
	v_exp_f32_e32 v130, v130
	v_exp_f32_e32 v131, v131
	v_exp_f32_e32 v132, v132
	v_exp_f32_e32 v133, v133
	v_exp_f32_e32 v134, v134
	v_exp_f32_e32 v135, v135
	v_exp_f32_e32 v136, v136
	v_exp_f32_e32 v137, v137
	v_pk_add_f32 v[130:131], v[130:131], s[10:11] op_sel_hi:[1,0]
	v_pk_add_f32 v[132:133], v[132:133], s[10:11] op_sel_hi:[1,0]
	v_pk_add_f32 v[134:135], v[134:135], s[10:11] op_sel_hi:[1,0]
	v_pk_add_f32 v[136:137], v[136:137], s[10:11] op_sel_hi:[1,0]
	v_rcp_f32_e32 v130, v130
	v_rcp_f32_e32 v131, v131
	v_rcp_f32_e32 v132, v132
	v_rcp_f32_e32 v133, v133
	v_rcp_f32_e32 v134, v134
	v_rcp_f32_e32 v135, v135
	v_rcp_f32_e32 v136, v136
	v_rcp_f32_e32 v137, v137
	v_pk_mul_f32 v[130:131], v[122:123], v[130:131]
	v_pk_mul_f32 v[132:133], v[124:125], v[132:133]
	v_pk_mul_f32 v[134:135], v[126:127], v[134:135]
	v_pk_mul_f32 v[136:137], v[128:129], v[136:137]
	v_cvt_pk_bf16_f32 v122, v130, v131
	v_cvt_pk_bf16_f32 v123, v132, v133
	v_cvt_pk_bf16_f32 v124, v134, v135
	v_cvt_pk_bf16_f32 v125, v136, v137
	global_store_dwordx4 v153, v[122:125], s[78:79]
	v_pk_mul_f32 v[130:131], v[114:115], s[8:9] op_sel_hi:[1,0]
	v_pk_mul_f32 v[132:133], v[116:117], s[8:9] op_sel_hi:[1,0]
	v_pk_mul_f32 v[134:135], v[118:119], s[8:9] op_sel_hi:[1,0]
	v_pk_mul_f32 v[136:137], v[120:121], s[8:9] op_sel_hi:[1,0]
	v_exp_f32_e32 v130, v130
	v_exp_f32_e32 v131, v131
	v_exp_f32_e32 v132, v132
	v_exp_f32_e32 v133, v133
	v_exp_f32_e32 v134, v134
	v_exp_f32_e32 v135, v135
	v_exp_f32_e32 v136, v136
	v_exp_f32_e32 v137, v137
	v_pk_add_f32 v[130:131], v[130:131], s[10:11] op_sel_hi:[1,0]
	v_pk_add_f32 v[132:133], v[132:133], s[10:11] op_sel_hi:[1,0]
	v_pk_add_f32 v[134:135], v[134:135], s[10:11] op_sel_hi:[1,0]
	v_pk_add_f32 v[136:137], v[136:137], s[10:11] op_sel_hi:[1,0]
	v_rcp_f32_e32 v130, v130
	v_rcp_f32_e32 v131, v131
	v_rcp_f32_e32 v132, v132
	v_rcp_f32_e32 v133, v133
	v_rcp_f32_e32 v134, v134
	v_rcp_f32_e32 v135, v135
	v_rcp_f32_e32 v136, v136
	v_rcp_f32_e32 v137, v137
	v_pk_mul_f32 v[130:131], v[114:115], v[130:131]
	v_pk_mul_f32 v[132:133], v[116:117], v[132:133]
	v_pk_mul_f32 v[134:135], v[118:119], v[134:135]
	v_pk_mul_f32 v[136:137], v[120:121], v[136:137]
	v_cvt_pk_bf16_f32 v114, v130, v131
	v_cvt_pk_bf16_f32 v115, v132, v133
	v_cvt_pk_bf16_f32 v116, v134, v135
	v_cvt_pk_bf16_f32 v117, v136, v137
	global_store_dwordx4 v153, v[114:117], s[78:79] offset:256
	s_add_u32 s98, s78, 0x8000
	s_addc_u32 s99, s79, 0
	v_pk_mul_f32 v[130:131], v[106:107], s[8:9] op_sel_hi:[1,0]
	v_pk_mul_f32 v[132:133], v[108:109], s[8:9] op_sel_hi:[1,0]
	v_pk_mul_f32 v[134:135], v[110:111], s[8:9] op_sel_hi:[1,0]
	v_pk_mul_f32 v[136:137], v[112:113], s[8:9] op_sel_hi:[1,0]
	v_exp_f32_e32 v130, v130
	v_exp_f32_e32 v131, v131
	v_exp_f32_e32 v132, v132
	v_exp_f32_e32 v133, v133
	v_exp_f32_e32 v134, v134
	v_exp_f32_e32 v135, v135
	v_exp_f32_e32 v136, v136
	v_exp_f32_e32 v137, v137
	v_pk_add_f32 v[130:131], v[130:131], s[10:11] op_sel_hi:[1,0]
	v_pk_add_f32 v[132:133], v[132:133], s[10:11] op_sel_hi:[1,0]
	v_pk_add_f32 v[134:135], v[134:135], s[10:11] op_sel_hi:[1,0]
	v_pk_add_f32 v[136:137], v[136:137], s[10:11] op_sel_hi:[1,0]
	v_rcp_f32_e32 v130, v130
	v_rcp_f32_e32 v131, v131
	v_rcp_f32_e32 v132, v132
	v_rcp_f32_e32 v133, v133
	v_rcp_f32_e32 v134, v134
	v_rcp_f32_e32 v135, v135
	v_rcp_f32_e32 v136, v136
	v_rcp_f32_e32 v137, v137
; __device__ __forceinline__ unsigned pk2(float lo, float hi) { const f32x2_t v = {lo, hi}; const bf16v2_t b = __builtin_convertvector(v, bf16v2_t); return __builtin_bit_cast(unsigned, b); }
; __device__ __forceinline__ float siluf_(float x) { return x * sigmoidf_(x); }
;     __device__ __forceinline__ void operator()(const AccT& acc, const pg8::Unit& u, int wr, int wc, int fr_, int fq_) const {
;     ...
;                         if (seg == 0) { a0[0] = siluf_(a0[0]); a0[1] = siluf_(a0[1]); a0[2] = siluf_(a0[2]); a0[3] = siluf_(a0[3]); a1[0] = siluf_(a1[0]); a1[1] = siluf_(a1[1]); a1[2] = siluf_(a1[2]); a1[3] = siluf_(a1[3]); }
;     ...
;                         u32x4 o; o[0] = pk2(a0[0], a0[1]); o[1] = pk2(a0[2], a0[3]); o[2] = pk2(a1[0], a1[1]); o[3] = pk2(a1[2], a1[3]);
;                         *(u32x4*)(base + row * D + cbase + bj * 128) = o;
	v_pk_mul_f32 v[130:131], v[106:107], v[130:131]
	v_pk_mul_f32 v[132:133], v[108:109], v[132:133]
	v_pk_mul_f32 v[134:135], v[110:111], v[134:135]
	v_pk_mul_f32 v[136:137], v[112:113], v[136:137]
	v_cvt_pk_bf16_f32 v106, v130, v131
	v_cvt_pk_bf16_f32 v107, v132, v133
	v_cvt_pk_bf16_f32 v108, v134, v135
	v_cvt_pk_bf16_f32 v109, v136, v137
	global_store_dwordx4 v153, v[106:109], s[98:99]
	v_pk_mul_f32 v[130:131], v[98:99], s[8:9] op_sel_hi:[1,0]
	v_pk_mul_f32 v[132:133], v[100:101], s[8:9] op_sel_hi:[1,0]
	v_pk_mul_f32 v[134:135], v[102:103], s[8:9] op_sel_hi:[1,0]
	v_pk_mul_f32 v[136:137], v[104:105], s[8:9] op_sel_hi:[1,0]
	v_exp_f32_e32 v130, v130
	v_exp_f32_e32 v131, v131
	v_exp_f32_e32 v132, v132
	v_exp_f32_e32 v133, v133
	v_exp_f32_e32 v134, v134
	v_exp_f32_e32 v135, v135
	v_exp_f32_e32 v136, v136
	v_exp_f32_e32 v137, v137
	v_pk_add_f32 v[130:131], v[130:131], s[10:11] op_sel_hi:[1,0]
	v_pk_add_f32 v[132:133], v[132:133], s[10:11] op_sel_hi:[1,0]
	v_pk_add_f32 v[134:135], v[134:135], s[10:11] op_sel_hi:[1,0]
	v_pk_add_f32 v[136:137], v[136:137], s[10:11] op_sel_hi:[1,0]
	v_rcp_f32_e32 v130, v130
	v_rcp_f32_e32 v131, v131
	v_rcp_f32_e32 v132, v132
	v_rcp_f32_e32 v133, v133
	v_rcp_f32_e32 v134, v134
	v_rcp_f32_e32 v135, v135
	v_rcp_f32_e32 v136, v136
	v_rcp_f32_e32 v137, v137
	v_pk_mul_f32 v[130:131], v[98:99], v[130:131]
	v_pk_mul_f32 v[132:133], v[100:101], v[132:133]
	v_pk_mul_f32 v[134:135], v[102:103], v[134:135]
	v_pk_mul_f32 v[136:137], v[104:105], v[136:137]
	v_cvt_pk_bf16_f32 v98, v130, v131
	v_cvt_pk_bf16_f32 v99, v132, v133
	v_cvt_pk_bf16_f32 v100, v134, v135
	v_cvt_pk_bf16_f32 v101, v136, v137
	global_store_dwordx4 v153, v[98:101], s[98:99] offset:256
	s_add_u32 s98, s78, 0x10000
	s_addc_u32 s99, s79, 0
	v_pk_mul_f32 v[130:131], v[90:91], s[8:9] op_sel_hi:[1,0]
	v_pk_mul_f32 v[132:133], v[92:93], s[8:9] op_sel_hi:[1,0]
	v_pk_mul_f32 v[134:135], v[94:95], s[8:9] op_sel_hi:[1,0]
	v_pk_mul_f32 v[136:137], v[96:97], s[8:9] op_sel_hi:[1,0]
	v_exp_f32_e32 v130, v130
	v_exp_f32_e32 v131, v131
	v_exp_f32_e32 v132, v132
	v_exp_f32_e32 v133, v133
	v_exp_f32_e32 v134, v134
	v_exp_f32_e32 v135, v135
	v_exp_f32_e32 v136, v136
	v_exp_f32_e32 v137, v137
	v_pk_add_f32 v[130:131], v[130:131], s[10:11] op_sel_hi:[1,0]
	v_pk_add_f32 v[132:133], v[132:133], s[10:11] op_sel_hi:[1,0]
	v_pk_add_f32 v[134:135], v[134:135], s[10:11] op_sel_hi:[1,0]
	v_pk_add_f32 v[136:137], v[136:137], s[10:11] op_sel_hi:[1,0]
	v_rcp_f32_e32 v130, v130
	v_rcp_f32_e32 v131, v131
	v_rcp_f32_e32 v132, v132
	v_rcp_f32_e32 v133, v133
	v_rcp_f32_e32 v134, v134
	v_rcp_f32_e32 v135, v135
	v_rcp_f32_e32 v136, v136
	v_rcp_f32_e32 v137, v137
	v_pk_mul_f32 v[130:131], v[90:91], v[130:131]
	v_pk_mul_f32 v[132:133], v[92:93], v[132:133]
	v_pk_mul_f32 v[134:135], v[94:95], v[134:135]
	v_pk_mul_f32 v[136:137], v[96:97], v[136:137]
	v_cvt_pk_bf16_f32 v90, v130, v131
	v_cvt_pk_bf16_f32 v91, v132, v133
	v_cvt_pk_bf16_f32 v92, v134, v135
	v_cvt_pk_bf16_f32 v93, v136, v137
	global_store_dwordx4 v153, v[90:93], s[98:99]
	v_pk_mul_f32 v[130:131], v[82:83], s[8:9] op_sel_hi:[1,0]
	v_pk_mul_f32 v[132:133], v[84:85], s[8:9] op_sel_hi:[1,0]
	v_pk_mul_f32 v[134:135], v[86:87], s[8:9] op_sel_hi:[1,0]
	v_pk_mul_f32 v[136:137], v[88:89], s[8:9] op_sel_hi:[1,0]
	v_exp_f32_e32 v130, v130
	v_exp_f32_e32 v131, v131
	v_exp_f32_e32 v132, v132
	v_exp_f32_e32 v133, v133
	v_exp_f32_e32 v134, v134
	v_exp_f32_e32 v135, v135
	v_exp_f32_e32 v136, v136
	v_exp_f32_e32 v137, v137
	v_pk_add_f32 v[130:131], v[130:131], s[10:11] op_sel_hi:[1,0]
	v_pk_add_f32 v[132:133], v[132:133], s[10:11] op_sel_hi:[1,0]
	v_pk_add_f32 v[134:135], v[134:135], s[10:11] op_sel_hi:[1,0]
	v_pk_add_f32 v[136:137], v[136:137], s[10:11] op_sel_hi:[1,0]
	v_rcp_f32_e32 v130, v130
	v_rcp_f32_e32 v131, v131
	v_rcp_f32_e32 v132, v132
	v_rcp_f32_e32 v133, v133
	v_rcp_f32_e32 v134, v134
	v_rcp_f32_e32 v135, v135
	v_rcp_f32_e32 v136, v136
	v_rcp_f32_e32 v137, v137
	v_pk_mul_f32 v[130:131], v[82:83], v[130:131]
	v_pk_mul_f32 v[132:133], v[84:85], v[132:133]
	v_pk_mul_f32 v[134:135], v[86:87], v[134:135]
	v_pk_mul_f32 v[136:137], v[88:89], v[136:137]
	v_cvt_pk_bf16_f32 v82, v130, v131
	v_cvt_pk_bf16_f32 v83, v132, v133
	v_cvt_pk_bf16_f32 v84, v134, v135
	v_cvt_pk_bf16_f32 v85, v136, v137
	global_store_dwordx4 v153, v[82:85], s[98:99] offset:256
	s_add_u32 s98, s78, 0x18000
	s_addc_u32 s99, s79, 0
	v_pk_mul_f32 v[130:131], v[74:75], s[8:9] op_sel_hi:[1,0]
	v_pk_mul_f32 v[132:133], v[76:77], s[8:9] op_sel_hi:[1,0]
	v_pk_mul_f32 v[134:135], v[78:79], s[8:9] op_sel_hi:[1,0]
	v_pk_mul_f32 v[136:137], v[80:81], s[8:9] op_sel_hi:[1,0]
	v_exp_f32_e32 v130, v130
	v_exp_f32_e32 v131, v131
	v_exp_f32_e32 v132, v132
	v_exp_f32_e32 v133, v133
	v_exp_f32_e32 v134, v134
	v_exp_f32_e32 v135, v135
	v_exp_f32_e32 v136, v136
	v_exp_f32_e32 v137, v137
	v_pk_add_f32 v[130:131], v[130:131], s[10:11] op_sel_hi:[1,0]
	v_pk_add_f32 v[132:133], v[132:133], s[10:11] op_sel_hi:[1,0]
	v_pk_add_f32 v[134:135], v[134:135], s[10:11] op_sel_hi:[1,0]
	v_pk_add_f32 v[136:137], v[136:137], s[10:11] op_sel_hi:[1,0]
	v_rcp_f32_e32 v130, v130
	v_rcp_f32_e32 v131, v131
	v_rcp_f32_e32 v132, v132
	v_rcp_f32_e32 v133, v133
	v_rcp_f32_e32 v134, v134
	v_rcp_f32_e32 v135, v135
	v_rcp_f32_e32 v136, v136
	v_rcp_f32_e32 v137, v137
	v_pk_mul_f32 v[130:131], v[74:75], v[130:131]
	v_pk_mul_f32 v[132:133], v[76:77], v[132:133]
	v_pk_mul_f32 v[134:135], v[78:79], v[134:135]
	v_pk_mul_f32 v[136:137], v[80:81], v[136:137]
	v_cvt_pk_bf16_f32 v74, v130, v131
	v_cvt_pk_bf16_f32 v75, v132, v133
	v_cvt_pk_bf16_f32 v76, v134, v135
	v_cvt_pk_bf16_f32 v77, v136, v137
	global_store_dwordx4 v153, v[74:77], s[98:99]
; __device__ __forceinline__ unsigned pk2(float lo, float hi) { const f32x2_t v = {lo, hi}; const bf16v2_t b = __builtin_convertvector(v, bf16v2_t); return __builtin_bit_cast(unsigned, b); }
; __device__ __forceinline__ float frcp(float x) { return __builtin_amdgcn_rcpf(x); }
; __device__ __forceinline__ float gelu_tanh_(float x) { const float y = 0.7978845608028654f * (x + 0.044715f * x * x * x); return x * sigmoidf_(2.f * y); }
; __device__ __forceinline__ float sigmoidf_(float x) { return frcp(1.f + __expf(-x)); }
; __device__ __forceinline__ float siluf_(float x) { return x * sigmoidf_(x); }
;     __device__ __forceinline__ void operator()(const AccT& acc, const pg8::Unit& u, int wr, int wc, int fr_, int fq_) const {
;     ...
;             const int seg = (pn - 8) >> 2;
;             bf16_t* base = (bf16_t*)(ws + WS_SG + (size_t)seg * ((size_t)MROWS * D * 2));
;             const int cbase = 256 * ((pn - 8) & 3) + wc * 32 + 8 * fq;
; #pragma unroll
;             for (int ai = 0; ai < 2; ++ai)
; #pragma unroll
;                 for (int m = 0; m < 4; ++m) {
;                     const size_t row = (size_t)u.pm * 256 + rl0 + ai * 128 + m * 16;
; #pragma unroll
;                     for (int bj = 0; bj < 2; ++bj) {
;                         f32x4 a0 = acc[ai][bj][m][0], a1 = acc[ai][bj][m][1];
;                         if (seg == 0) { a0[0] = siluf_(a0[0]); a0[1] = siluf_(a0[1]); a0[2] = siluf_(a0[2]); a0[3] = siluf_(a0[3]); a1[0] = siluf_(a1[0]); a1[1] = siluf_(a1[1]); a1[2] = siluf_(a1[2]); a1[3] = siluf_(a1[3]); }
;                         else if (seg == 2) { a0[0] = gelu_tanh_(a0[0]); a0[1] = gelu_tanh_(a0[1]); a0[2] = gelu_tanh_(a0[2]); a0[3] = gelu_tanh_(a0[3]); a1[0] = gelu_tanh_(a1[0]); a1[1] = gelu_tanh_(a1[1]); a1[2] = gelu_tanh_(a1[2]); a1[3] = gelu_tanh_(a1[3]); }
;                         else if (seg >= 3) { a0[0] = sigmoidf_(a0[0]); a0[1] = sigmoidf_(a0[1]); a0[2] = sigmoidf_(a0[2]); a0[3] = sigmoidf_(a0[3]); a1[0] = sigmoidf_(a1[0]); a1[1] = sigmoidf_(a1[1]); a1[2] = sigmoidf_(a1[2]); a1[3] = sigmoidf_(a1[3]); }
;                         u32x4 o; o[0] = pk2(a0[0], a0[1]); o[1] = pk2(a0[2], a0[3]); o[2] = pk2(a1[0], a1[1]); o[3] = pk2(a1[2], a1[3]);
;                         *(u32x4*)(base + row * D + cbase + bj * 128) = o;
;                     }
;                 }
	v_pk_mul_f32 v[130:131], v[66:67], s[8:9] op_sel_hi:[1,0]
	v_pk_mul_f32 v[132:133], v[68:69], s[8:9] op_sel_hi:[1,0]
	v_pk_mul_f32 v[134:135], v[70:71], s[8:9] op_sel_hi:[1,0]
	v_pk_mul_f32 v[136:137], v[72:73], s[8:9] op_sel_hi:[1,0]
	v_exp_f32_e32 v130, v130
	v_exp_f32_e32 v131, v131
	v_exp_f32_e32 v132, v132
	v_exp_f32_e32 v133, v133
	v_exp_f32_e32 v134, v134
	v_exp_f32_e32 v135, v135
	v_exp_f32_e32 v136, v136
	v_exp_f32_e32 v137, v137
	v_pk_add_f32 v[130:131], v[130:131], s[10:11] op_sel_hi:[1,0]
	v_pk_add_f32 v[132:133], v[132:133], s[10:11] op_sel_hi:[1,0]
	v_pk_add_f32 v[134:135], v[134:135], s[10:11] op_sel_hi:[1,0]
	v_pk_add_f32 v[136:137], v[136:137], s[10:11] op_sel_hi:[1,0]
	v_rcp_f32_e32 v130, v130
	v_rcp_f32_e32 v131, v131
	v_rcp_f32_e32 v132, v132
	v_rcp_f32_e32 v133, v133
	v_rcp_f32_e32 v134, v134
	v_rcp_f32_e32 v135, v135
	v_rcp_f32_e32 v136, v136
	v_rcp_f32_e32 v137, v137
	v_pk_mul_f32 v[130:131], v[66:67], v[130:131]
	v_pk_mul_f32 v[132:133], v[68:69], v[132:133]
	v_pk_mul_f32 v[134:135], v[70:71], v[134:135]
	v_pk_mul_f32 v[136:137], v[72:73], v[136:137]
	v_cvt_pk_bf16_f32 v66, v130, v131
	v_cvt_pk_bf16_f32 v67, v132, v133
	v_cvt_pk_bf16_f32 v68, v134, v135
	v_cvt_pk_bf16_f32 v69, v136, v137
	global_store_dwordx4 v153, v[66:69], s[98:99] offset:256
	s_add_u32 s98, s78, 0x40000
	s_addc_u32 s99, s79, 0
	v_pk_mul_f32 v[130:131], v[58:59], s[8:9] op_sel_hi:[1,0]
	v_pk_mul_f32 v[132:133], v[60:61], s[8:9] op_sel_hi:[1,0]
	v_pk_mul_f32 v[134:135], v[62:63], s[8:9] op_sel_hi:[1,0]
	v_pk_mul_f32 v[136:137], v[64:65], s[8:9] op_sel_hi:[1,0]
	v_exp_f32_e32 v130, v130
	v_exp_f32_e32 v131, v131
	v_exp_f32_e32 v132, v132
	v_exp_f32_e32 v133, v133
	v_exp_f32_e32 v134, v134
	v_exp_f32_e32 v135, v135
	v_exp_f32_e32 v136, v136
	v_exp_f32_e32 v137, v137
	v_pk_add_f32 v[130:131], v[130:131], s[10:11] op_sel_hi:[1,0]
	v_pk_add_f32 v[132:133], v[132:133], s[10:11] op_sel_hi:[1,0]
	v_pk_add_f32 v[134:135], v[134:135], s[10:11] op_sel_hi:[1,0]
	v_pk_add_f32 v[136:137], v[136:137], s[10:11] op_sel_hi:[1,0]
	v_rcp_f32_e32 v130, v130
	v_rcp_f32_e32 v131, v131
	v_rcp_f32_e32 v132, v132
	v_rcp_f32_e32 v133, v133
	v_rcp_f32_e32 v134, v134
	v_rcp_f32_e32 v135, v135
	v_rcp_f32_e32 v136, v136
	v_rcp_f32_e32 v137, v137
	v_pk_mul_f32 v[130:131], v[58:59], v[130:131]
	v_pk_mul_f32 v[132:133], v[60:61], v[132:133]
	v_pk_mul_f32 v[134:135], v[62:63], v[134:135]
	v_pk_mul_f32 v[136:137], v[64:65], v[136:137]
	v_cvt_pk_bf16_f32 v58, v130, v131
	v_cvt_pk_bf16_f32 v59, v132, v133
	v_cvt_pk_bf16_f32 v60, v134, v135
	v_cvt_pk_bf16_f32 v61, v136, v137
	global_store_dwordx4 v153, v[58:61], s[98:99]
	v_pk_mul_f32 v[130:131], v[50:51], s[8:9] op_sel_hi:[1,0]
	v_pk_mul_f32 v[132:133], v[52:53], s[8:9] op_sel_hi:[1,0]
	v_pk_mul_f32 v[134:135], v[54:55], s[8:9] op_sel_hi:[1,0]
	v_pk_mul_f32 v[136:137], v[56:57], s[8:9] op_sel_hi:[1,0]
	v_exp_f32_e32 v130, v130
	v_exp_f32_e32 v131, v131
	v_exp_f32_e32 v132, v132
	v_exp_f32_e32 v133, v133
	v_exp_f32_e32 v134, v134
	v_exp_f32_e32 v135, v135
	v_exp_f32_e32 v136, v136
	v_exp_f32_e32 v137, v137
	v_pk_add_f32 v[130:131], v[130:131], s[10:11] op_sel_hi:[1,0]
	v_pk_add_f32 v[132:133], v[132:133], s[10:11] op_sel_hi:[1,0]
	v_pk_add_f32 v[134:135], v[134:135], s[10:11] op_sel_hi:[1,0]
	v_pk_add_f32 v[136:137], v[136:137], s[10:11] op_sel_hi:[1,0]
	v_rcp_f32_e32 v130, v130
	v_rcp_f32_e32 v131, v131
	v_rcp_f32_e32 v132, v132
	v_rcp_f32_e32 v133, v133
	v_rcp_f32_e32 v134, v134
	v_rcp_f32_e32 v135, v135
	v_rcp_f32_e32 v136, v136
	v_rcp_f32_e32 v137, v137
	v_pk_mul_f32 v[130:131], v[50:51], v[130:131]
	v_pk_mul_f32 v[132:133], v[52:53], v[132:133]
	v_pk_mul_f32 v[134:135], v[54:55], v[134:135]
	v_pk_mul_f32 v[136:137], v[56:57], v[136:137]
	v_cvt_pk_bf16_f32 v50, v130, v131
	v_cvt_pk_bf16_f32 v51, v132, v133
	v_cvt_pk_bf16_f32 v52, v134, v135
	v_cvt_pk_bf16_f32 v53, v136, v137
	global_store_dwordx4 v153, v[50:53], s[98:99] offset:256
	s_add_u32 s98, s78, 0x48000
	s_addc_u32 s99, s79, 0
	v_pk_mul_f32 v[130:131], v[42:43], s[8:9] op_sel_hi:[1,0]
	v_pk_mul_f32 v[132:133], v[44:45], s[8:9] op_sel_hi:[1,0]
	v_pk_mul_f32 v[134:135], v[46:47], s[8:9] op_sel_hi:[1,0]
	v_pk_mul_f32 v[136:137], v[48:49], s[8:9] op_sel_hi:[1,0]
	v_exp_f32_e32 v130, v130
	v_exp_f32_e32 v131, v131
	v_exp_f32_e32 v132, v132
	v_exp_f32_e32 v133, v133
	v_exp_f32_e32 v134, v134
	v_exp_f32_e32 v135, v135
	v_exp_f32_e32 v136, v136
	v_exp_f32_e32 v137, v137
	v_pk_add_f32 v[130:131], v[130:131], s[10:11] op_sel_hi:[1,0]
	v_pk_add_f32 v[132:133], v[132:133], s[10:11] op_sel_hi:[1,0]
	v_pk_add_f32 v[134:135], v[134:135], s[10:11] op_sel_hi:[1,0]
	v_pk_add_f32 v[136:137], v[136:137], s[10:11] op_sel_hi:[1,0]
	v_rcp_f32_e32 v130, v130
	v_rcp_f32_e32 v131, v131
	v_rcp_f32_e32 v132, v132
	v_rcp_f32_e32 v133, v133
	v_rcp_f32_e32 v134, v134
	v_rcp_f32_e32 v135, v135
	v_rcp_f32_e32 v136, v136
	v_rcp_f32_e32 v137, v137
	v_pk_mul_f32 v[130:131], v[42:43], v[130:131]
	v_pk_mul_f32 v[132:133], v[44:45], v[132:133]
	v_pk_mul_f32 v[134:135], v[46:47], v[134:135]
	v_pk_mul_f32 v[136:137], v[48:49], v[136:137]
	v_cvt_pk_bf16_f32 v42, v130, v131
	v_cvt_pk_bf16_f32 v43, v132, v133
	v_cvt_pk_bf16_f32 v44, v134, v135
	v_cvt_pk_bf16_f32 v45, v136, v137
	global_store_dwordx4 v153, v[42:45], s[98:99]
	v_pk_mul_f32 v[130:131], v[34:35], s[8:9] op_sel_hi:[1,0]
	v_pk_mul_f32 v[132:133], v[36:37], s[8:9] op_sel_hi:[1,0]
	v_pk_mul_f32 v[134:135], v[38:39], s[8:9] op_sel_hi:[1,0]
	v_pk_mul_f32 v[136:137], v[40:41], s[8:9] op_sel_hi:[1,0]
	v_exp_f32_e32 v130, v130
	v_exp_f32_e32 v131, v131
	v_exp_f32_e32 v132, v132
	v_exp_f32_e32 v133, v133
	v_exp_f32_e32 v134, v134
	v_exp_f32_e32 v135, v135
; __device__ __forceinline__ unsigned pk2(float lo, float hi) { const f32x2_t v = {lo, hi}; const bf16v2_t b = __builtin_convertvector(v, bf16v2_t); return __builtin_bit_cast(unsigned, b); }
; __device__ __forceinline__ float frcp(float x) { return __builtin_amdgcn_rcpf(x); }
; __device__ __forceinline__ float gelu_tanh_(float x) { const float y = 0.7978845608028654f * (x + 0.044715f * x * x * x); return x * sigmoidf_(2.f * y); }
; __device__ __forceinline__ float sigmoidf_(float x) { return frcp(1.f + __expf(-x)); }
; __device__ __forceinline__ float siluf_(float x) { return x * sigmoidf_(x); }
;     __device__ __forceinline__ void operator()(const AccT& acc, const pg8::Unit& u, int wr, int wc, int fr_, int fq_) const {
;     ...
;             const int seg = (pn - 8) >> 2;
;             bf16_t* base = (bf16_t*)(ws + WS_SG + (size_t)seg * ((size_t)MROWS * D * 2));
;             const int cbase = 256 * ((pn - 8) & 3) + wc * 32 + 8 * fq;
; #pragma unroll
;             for (int ai = 0; ai < 2; ++ai)
; #pragma unroll
;                 for (int m = 0; m < 4; ++m) {
;                     const size_t row = (size_t)u.pm * 256 + rl0 + ai * 128 + m * 16;
; #pragma unroll
;                     for (int bj = 0; bj < 2; ++bj) {
;                         f32x4 a0 = acc[ai][bj][m][0], a1 = acc[ai][bj][m][1];
;                         if (seg == 0) { a0[0] = siluf_(a0[0]); a0[1] = siluf_(a0[1]); a0[2] = siluf_(a0[2]); a0[3] = siluf_(a0[3]); a1[0] = siluf_(a1[0]); a1[1] = siluf_(a1[1]); a1[2] = siluf_(a1[2]); a1[3] = siluf_(a1[3]); }
;                         else if (seg == 2) { a0[0] = gelu_tanh_(a0[0]); a0[1] = gelu_tanh_(a0[1]); a0[2] = gelu_tanh_(a0[2]); a0[3] = gelu_tanh_(a0[3]); a1[0] = gelu_tanh_(a1[0]); a1[1] = gelu_tanh_(a1[1]); a1[2] = gelu_tanh_(a1[2]); a1[3] = gelu_tanh_(a1[3]); }
;                         else if (seg >= 3) { a0[0] = sigmoidf_(a0[0]); a0[1] = sigmoidf_(a0[1]); a0[2] = sigmoidf_(a0[2]); a0[3] = sigmoidf_(a0[3]); a1[0] = sigmoidf_(a1[0]); a1[1] = sigmoidf_(a1[1]); a1[2] = sigmoidf_(a1[2]); a1[3] = sigmoidf_(a1[3]); }
;                         u32x4 o; o[0] = pk2(a0[0], a0[1]); o[1] = pk2(a0[2], a0[3]); o[2] = pk2(a1[0], a1[1]); o[3] = pk2(a1[2], a1[3]);
;                         *(u32x4*)(base + row * D + cbase + bj * 128) = o;
;                     }
;                 }
	v_exp_f32_e32 v136, v136
	v_exp_f32_e32 v137, v137
	v_pk_add_f32 v[130:131], v[130:131], s[10:11] op_sel_hi:[1,0]
	v_pk_add_f32 v[132:133], v[132:133], s[10:11] op_sel_hi:[1,0]
	v_pk_add_f32 v[134:135], v[134:135], s[10:11] op_sel_hi:[1,0]
	v_pk_add_f32 v[136:137], v[136:137], s[10:11] op_sel_hi:[1,0]
	v_rcp_f32_e32 v130, v130
	v_rcp_f32_e32 v131, v131
	v_rcp_f32_e32 v132, v132
	v_rcp_f32_e32 v133, v133
	v_rcp_f32_e32 v134, v134
	v_rcp_f32_e32 v135, v135
	v_rcp_f32_e32 v136, v136
	v_rcp_f32_e32 v137, v137
	v_pk_mul_f32 v[130:131], v[34:35], v[130:131]
	v_pk_mul_f32 v[132:133], v[36:37], v[132:133]
	v_pk_mul_f32 v[134:135], v[38:39], v[134:135]
	v_pk_mul_f32 v[136:137], v[40:41], v[136:137]
	v_cvt_pk_bf16_f32 v34, v130, v131
	v_cvt_pk_bf16_f32 v35, v132, v133
	v_cvt_pk_bf16_f32 v36, v134, v135
	v_cvt_pk_bf16_f32 v37, v136, v137
	global_store_dwordx4 v153, v[34:37], s[98:99] offset:256
	s_add_u32 s98, s78, 0x50000
	s_addc_u32 s99, s79, 0
	v_pk_mul_f32 v[130:131], v[26:27], s[8:9] op_sel_hi:[1,0]
	v_pk_mul_f32 v[132:133], v[28:29], s[8:9] op_sel_hi:[1,0]
	v_pk_mul_f32 v[134:135], v[30:31], s[8:9] op_sel_hi:[1,0]
	v_pk_mul_f32 v[136:137], v[32:33], s[8:9] op_sel_hi:[1,0]
	v_exp_f32_e32 v130, v130
	v_exp_f32_e32 v131, v131
	v_exp_f32_e32 v132, v132
	v_exp_f32_e32 v133, v133
	v_exp_f32_e32 v134, v134
	v_exp_f32_e32 v135, v135
	v_exp_f32_e32 v136, v136
	v_exp_f32_e32 v137, v137
	v_pk_add_f32 v[130:131], v[130:131], s[10:11] op_sel_hi:[1,0]
	v_pk_add_f32 v[132:133], v[132:133], s[10:11] op_sel_hi:[1,0]
	v_pk_add_f32 v[134:135], v[134:135], s[10:11] op_sel_hi:[1,0]
	v_pk_add_f32 v[136:137], v[136:137], s[10:11] op_sel_hi:[1,0]
	v_rcp_f32_e32 v130, v130
	v_rcp_f32_e32 v131, v131
	v_rcp_f32_e32 v132, v132
	v_rcp_f32_e32 v133, v133
	v_rcp_f32_e32 v134, v134
	v_rcp_f32_e32 v135, v135
	v_rcp_f32_e32 v136, v136
	v_rcp_f32_e32 v137, v137
	v_pk_mul_f32 v[130:131], v[26:27], v[130:131]
	v_pk_mul_f32 v[132:133], v[28:29], v[132:133]
	v_pk_mul_f32 v[134:135], v[30:31], v[134:135]
	v_pk_mul_f32 v[136:137], v[32:33], v[136:137]
	v_cvt_pk_bf16_f32 v26, v130, v131
	v_cvt_pk_bf16_f32 v27, v132, v133
	v_cvt_pk_bf16_f32 v28, v134, v135
	v_cvt_pk_bf16_f32 v29, v136, v137
	global_store_dwordx4 v153, v[26:29], s[98:99]
	v_pk_mul_f32 v[130:131], v[18:19], s[8:9] op_sel_hi:[1,0]
	v_pk_mul_f32 v[132:133], v[20:21], s[8:9] op_sel_hi:[1,0]
	v_pk_mul_f32 v[134:135], v[22:23], s[8:9] op_sel_hi:[1,0]
	v_pk_mul_f32 v[136:137], v[24:25], s[8:9] op_sel_hi:[1,0]
	v_exp_f32_e32 v130, v130
	v_exp_f32_e32 v131, v131
	v_exp_f32_e32 v132, v132
	v_exp_f32_e32 v133, v133
	v_exp_f32_e32 v134, v134
	v_exp_f32_e32 v135, v135
	v_exp_f32_e32 v136, v136
	v_exp_f32_e32 v137, v137
	v_pk_add_f32 v[130:131], v[130:131], s[10:11] op_sel_hi:[1,0]
	v_pk_add_f32 v[132:133], v[132:133], s[10:11] op_sel_hi:[1,0]
	v_pk_add_f32 v[134:135], v[134:135], s[10:11] op_sel_hi:[1,0]
	v_pk_add_f32 v[136:137], v[136:137], s[10:11] op_sel_hi:[1,0]
	v_rcp_f32_e32 v130, v130
	v_rcp_f32_e32 v131, v131
	v_rcp_f32_e32 v132, v132
	v_rcp_f32_e32 v133, v133
	v_rcp_f32_e32 v134, v134
	v_rcp_f32_e32 v135, v135
	v_rcp_f32_e32 v136, v136
	v_rcp_f32_e32 v137, v137
	v_pk_mul_f32 v[130:131], v[18:19], v[130:131]
	v_pk_mul_f32 v[132:133], v[20:21], v[132:133]
	v_pk_mul_f32 v[134:135], v[22:23], v[134:135]
	v_pk_mul_f32 v[136:137], v[24:25], v[136:137]
	v_cvt_pk_bf16_f32 v18, v130, v131
	v_cvt_pk_bf16_f32 v19, v132, v133
	v_cvt_pk_bf16_f32 v20, v134, v135
	v_cvt_pk_bf16_f32 v21, v136, v137
	global_store_dwordx4 v153, v[18:21], s[98:99] offset:256
	s_add_u32 s98, s78, 0x58000
	s_addc_u32 s99, s79, 0
	v_pk_mul_f32 v[130:131], v[10:11], s[8:9] op_sel_hi:[1,0]
	v_pk_mul_f32 v[132:133], v[12:13], s[8:9] op_sel_hi:[1,0]
	v_pk_mul_f32 v[134:135], v[14:15], s[8:9] op_sel_hi:[1,0]
	v_pk_mul_f32 v[136:137], v[16:17], s[8:9] op_sel_hi:[1,0]
	v_exp_f32_e32 v130, v130
	v_exp_f32_e32 v131, v131
	v_exp_f32_e32 v132, v132
	v_exp_f32_e32 v133, v133
	v_exp_f32_e32 v134, v134
	v_exp_f32_e32 v135, v135
	v_exp_f32_e32 v136, v136
	v_exp_f32_e32 v137, v137
	v_pk_add_f32 v[130:131], v[130:131], s[10:11] op_sel_hi:[1,0]
	v_pk_add_f32 v[132:133], v[132:133], s[10:11] op_sel_hi:[1,0]
	v_pk_add_f32 v[134:135], v[134:135], s[10:11] op_sel_hi:[1,0]
	v_pk_add_f32 v[136:137], v[136:137], s[10:11] op_sel_hi:[1,0]
	v_rcp_f32_e32 v130, v130
	v_rcp_f32_e32 v131, v131
	v_rcp_f32_e32 v132, v132
	v_rcp_f32_e32 v133, v133
	v_rcp_f32_e32 v134, v134
	v_rcp_f32_e32 v135, v135
	v_rcp_f32_e32 v136, v136
	v_rcp_f32_e32 v137, v137
	v_pk_mul_f32 v[130:131], v[10:11], v[130:131]
	v_pk_mul_f32 v[132:133], v[12:13], v[132:133]
	v_pk_mul_f32 v[134:135], v[14:15], v[134:135]
	v_pk_mul_f32 v[136:137], v[16:17], v[136:137]
	v_cvt_pk_bf16_f32 v10, v130, v131
	v_cvt_pk_bf16_f32 v11, v132, v133
	v_cvt_pk_bf16_f32 v12, v134, v135
	v_cvt_pk_bf16_f32 v13, v136, v137
	global_store_dwordx4 v153, v[10:13], s[98:99]
	v_pk_mul_f32 v[130:131], v[6:7], s[8:9] op_sel_hi:[1,0]
	v_pk_mul_f32 v[132:133], v[8:9], s[8:9] op_sel_hi:[1,0]
	v_pk_mul_f32 v[134:135], v[2:3], s[8:9] op_sel_hi:[1,0]
	v_pk_mul_f32 v[136:137], v[4:5], s[8:9] op_sel_hi:[1,0]
	v_exp_f32_e32 v130, v130
	v_exp_f32_e32 v131, v131
	v_exp_f32_e32 v132, v132
	v_exp_f32_e32 v133, v133
	v_exp_f32_e32 v134, v134
	v_exp_f32_e32 v135, v135
	v_exp_f32_e32 v136, v136
	v_exp_f32_e32 v137, v137
	v_pk_add_f32 v[130:131], v[130:131], s[10:11] op_sel_hi:[1,0]
	v_pk_add_f32 v[132:133], v[132:133], s[10:11] op_sel_hi:[1,0]
	v_pk_add_f32 v[134:135], v[134:135], s[10:11] op_sel_hi:[1,0]
	v_pk_add_f32 v[136:137], v[136:137], s[10:11] op_sel_hi:[1,0]
	v_rcp_f32_e32 v130, v130
	v_rcp_f32_e32 v131, v131
	v_rcp_f32_e32 v132, v132
	v_rcp_f32_e32 v133, v133
	v_rcp_f32_e32 v134, v134
	v_rcp_f32_e32 v135, v135
	v_rcp_f32_e32 v136, v136
	v_rcp_f32_e32 v137, v137
	v_pk_mul_f32 v[130:131], v[6:7], v[130:131]
	v_pk_mul_f32 v[132:133], v[8:9], v[132:133]
	v_pk_mul_f32 v[134:135], v[2:3], v[134:135]
	v_pk_mul_f32 v[136:137], v[4:5], v[136:137]
	v_cvt_pk_bf16_f32 v6, v130, v131
	v_cvt_pk_bf16_f32 v7, v132, v133
	v_cvt_pk_bf16_f32 v8, v134, v135
	v_cvt_pk_bf16_f32 v9, v136, v137
	global_store_dwordx4 v153, v[6:9], s[98:99] offset:256
	s_mov_b32 s32, 1
	s_branch .LBB0_264
; __device__ __forceinline__ unsigned pk2(float lo, float hi) { const f32x2_t v = {lo, hi}; const bf16v2_t b = __builtin_convertvector(v, bf16v2_t); return __builtin_bit_cast(unsigned, b); }
; __device__ __forceinline__ float sigmoidf_(float x) { return frcp(1.f + __expf(-x)); }
; __device__ __forceinline__ float siluf_(float x) { return x * sigmoidf_(x); }
; __device__ __forceinline__ float gelu_tanh_(float x) { const float y = 0.7978845608028654f * (x + 0.044715f * x * x * x); return x * sigmoidf_(2.f * y); }
;     __device__ __forceinline__ void operator()(const AccT& acc, const pg8::Unit& u, int wr, int wc, int fr_, int fq_) const {
;     ...
;             const int seg = (pn - 8) >> 2;
;             bf16_t* base = (bf16_t*)(ws + WS_SG + (size_t)seg * ((size_t)MROWS * D * 2));
;             const int cbase = 256 * ((pn - 8) & 3) + wc * 32 + 8 * fq;
; #pragma unroll
;             for (int ai = 0; ai < 2; ++ai)
; #pragma unroll
;                 for (int m = 0; m < 4; ++m) {
;                     const size_t row = (size_t)u.pm * 256 + rl0 + ai * 128 + m * 16;
; #pragma unroll
;                     for (int bj = 0; bj < 2; ++bj) {
;                         f32x4 a0 = acc[ai][bj][m][0], a1 = acc[ai][bj][m][1];
;                         if (seg == 0) { a0[0] = siluf_(a0[0]); a0[1] = siluf_(a0[1]); a0[2] = siluf_(a0[2]); a0[3] = siluf_(a0[3]); a1[0] = siluf_(a1[0]); a1[1] = siluf_(a1[1]); a1[2] = siluf_(a1[2]); a1[3] = siluf_(a1[3]); }
;                         else if (seg == 2) { a0[0] = gelu_tanh_(a0[0]); a0[1] = gelu_tanh_(a0[1]); a0[2] = gelu_tanh_(a0[2]); a0[3] = gelu_tanh_(a0[3]); a1[0] = gelu_tanh_(a1[0]); a1[1] = gelu_tanh_(a1[1]); a1[2] = gelu_tanh_(a1[2]); a1[3] = gelu_tanh_(a1[3]); }
;                         else if (seg >= 3) { a0[0] = sigmoidf_(a0[0]); a0[1] = sigmoidf_(a0[1]); a0[2] = sigmoidf_(a0[2]); a0[3] = sigmoidf_(a0[3]); a1[0] = sigmoidf_(a1[0]); a1[1] = sigmoidf_(a1[1]); a1[2] = sigmoidf_(a1[2]); a1[3] = sigmoidf_(a1[3]); }
;                         u32x4 o; o[0] = pk2(a0[0], a0[1]); o[1] = pk2(a0[2], a0[3]); o[2] = pk2(a1[0], a1[1]); o[3] = pk2(a1[2], a1[3]);
;                         *(u32x4*)(base + row * D + cbase + bj * 128) = o;
;                     }
;                 }
.Lew_copy:
	v_cvt_pk_bf16_f32 v122, v122, v123
	v_cvt_pk_bf16_f32 v123, v124, v125
	v_cvt_pk_bf16_f32 v124, v126, v127
	v_cvt_pk_bf16_f32 v125, v128, v129
	global_store_dwordx4 v153, v[122:125], s[78:79]
	v_cvt_pk_bf16_f32 v114, v114, v115
	v_cvt_pk_bf16_f32 v115, v116, v117
	v_cvt_pk_bf16_f32 v116, v118, v119
	v_cvt_pk_bf16_f32 v117, v120, v121
	global_store_dwordx4 v153, v[114:117], s[78:79] offset:256
	s_add_u32 s98, s78, 0x8000
	s_addc_u32 s99, s79, 0
	v_cvt_pk_bf16_f32 v106, v106, v107
	v_cvt_pk_bf16_f32 v107, v108, v109
	v_cvt_pk_bf16_f32 v108, v110, v111
	v_cvt_pk_bf16_f32 v109, v112, v113
	global_store_dwordx4 v153, v[106:109], s[98:99]
	v_cvt_pk_bf16_f32 v98, v98, v99
	v_cvt_pk_bf16_f32 v99, v100, v101
	v_cvt_pk_bf16_f32 v100, v102, v103
	v_cvt_pk_bf16_f32 v101, v104, v105
	global_store_dwordx4 v153, v[98:101], s[98:99] offset:256
	s_add_u32 s98, s78, 0x10000
	s_addc_u32 s99, s79, 0
	v_cvt_pk_bf16_f32 v90, v90, v91
	v_cvt_pk_bf16_f32 v91, v92, v93
	v_cvt_pk_bf16_f32 v92, v94, v95
	v_cvt_pk_bf16_f32 v93, v96, v97
	global_store_dwordx4 v153, v[90:93], s[98:99]
	v_cvt_pk_bf16_f32 v82, v82, v83
	v_cvt_pk_bf16_f32 v83, v84, v85
	v_cvt_pk_bf16_f32 v84, v86, v87
	v_cvt_pk_bf16_f32 v85, v88, v89
	global_store_dwordx4 v153, v[82:85], s[98:99] offset:256
	s_add_u32 s98, s78, 0x18000
	s_addc_u32 s99, s79, 0
	v_cvt_pk_bf16_f32 v74, v74, v75
	v_cvt_pk_bf16_f32 v75, v76, v77
	v_cvt_pk_bf16_f32 v76, v78, v79
	v_cvt_pk_bf16_f32 v77, v80, v81
	global_store_dwordx4 v153, v[74:77], s[98:99]
	v_cvt_pk_bf16_f32 v66, v66, v67
	v_cvt_pk_bf16_f32 v67, v68, v69
	v_cvt_pk_bf16_f32 v68, v70, v71
	v_cvt_pk_bf16_f32 v69, v72, v73
	global_store_dwordx4 v153, v[66:69], s[98:99] offset:256
	s_add_u32 s98, s78, 0x40000
	s_addc_u32 s99, s79, 0
	v_cvt_pk_bf16_f32 v58, v58, v59
	v_cvt_pk_bf16_f32 v59, v60, v61
	v_cvt_pk_bf16_f32 v60, v62, v63
	v_cvt_pk_bf16_f32 v61, v64, v65
	global_store_dwordx4 v153, v[58:61], s[98:99]
	v_cvt_pk_bf16_f32 v50, v50, v51
	v_cvt_pk_bf16_f32 v51, v52, v53
	v_cvt_pk_bf16_f32 v52, v54, v55
	v_cvt_pk_bf16_f32 v53, v56, v57
	global_store_dwordx4 v153, v[50:53], s[98:99] offset:256
	s_add_u32 s98, s78, 0x48000
	s_addc_u32 s99, s79, 0
	v_cvt_pk_bf16_f32 v42, v42, v43
	v_cvt_pk_bf16_f32 v43, v44, v45
	v_cvt_pk_bf16_f32 v44, v46, v47
	v_cvt_pk_bf16_f32 v45, v48, v49
	global_store_dwordx4 v153, v[42:45], s[98:99]
	v_cvt_pk_bf16_f32 v34, v34, v35
	v_cvt_pk_bf16_f32 v35, v36, v37
	v_cvt_pk_bf16_f32 v36, v38, v39
	v_cvt_pk_bf16_f32 v37, v40, v41
	global_store_dwordx4 v153, v[34:37], s[98:99] offset:256
	s_add_u32 s98, s78, 0x50000
	s_addc_u32 s99, s79, 0
	v_cvt_pk_bf16_f32 v26, v26, v27
	v_cvt_pk_bf16_f32 v27, v28, v29
	v_cvt_pk_bf16_f32 v28, v30, v31
	v_cvt_pk_bf16_f32 v29, v32, v33
	global_store_dwordx4 v153, v[26:29], s[98:99]
	v_cvt_pk_bf16_f32 v18, v18, v19
	v_cvt_pk_bf16_f32 v19, v20, v21
	v_cvt_pk_bf16_f32 v20, v22, v23
	v_cvt_pk_bf16_f32 v21, v24, v25
	global_store_dwordx4 v153, v[18:21], s[98:99] offset:256
	s_add_u32 s98, s78, 0x58000
	s_addc_u32 s99, s79, 0
	v_cvt_pk_bf16_f32 v10, v10, v11
	v_cvt_pk_bf16_f32 v11, v12, v13
	v_cvt_pk_bf16_f32 v12, v14, v15
	v_cvt_pk_bf16_f32 v13, v16, v17
	global_store_dwordx4 v153, v[10:13], s[98:99]
	v_cvt_pk_bf16_f32 v6, v6, v7
	v_cvt_pk_bf16_f32 v7, v8, v9
	v_cvt_pk_bf16_f32 v8, v2, v3
	v_cvt_pk_bf16_f32 v9, v4, v5
	global_store_dwordx4 v153, v[6:9], s[98:99] offset:256
	s_mov_b32 s32, 1
	s_branch .LBB0_264
.Lew_gelu:
	v_pk_mul_f32 v[130:131], v[122:123], s[12:13] op_sel_hi:[1,0]
	v_pk_mul_f32 v[132:133], v[124:125], s[12:13] op_sel_hi:[1,0]
	v_pk_mul_f32 v[134:135], v[126:127], s[12:13] op_sel_hi:[1,0]
	v_pk_mul_f32 v[136:137], v[128:129], s[12:13] op_sel_hi:[1,0]
	v_pk_mul_f32 v[130:131], v[122:123], v[130:131]
	v_pk_mul_f32 v[132:133], v[124:125], v[132:133]
	v_pk_mul_f32 v[134:135], v[126:127], v[134:135]
	v_pk_mul_f32 v[136:137], v[128:129], v[136:137]
	v_pk_fma_f32 v[130:131], v[122:123], v[130:131], v[122:123]
	v_pk_fma_f32 v[132:133], v[124:125], v[132:133], v[124:125]
	v_pk_fma_f32 v[134:135], v[126:127], v[134:135], v[126:127]
	v_pk_fma_f32 v[136:137], v[128:129], v[136:137], v[128:129]
	v_pk_mul_f32 v[130:131], v[130:131], s[100:101] op_sel_hi:[1,0]
	v_pk_mul_f32 v[132:133], v[132:133], s[100:101] op_sel_hi:[1,0]
	v_pk_mul_f32 v[134:135], v[134:135], s[100:101] op_sel_hi:[1,0]
	v_pk_mul_f32 v[136:137], v[136:137], s[100:101] op_sel_hi:[1,0]
	v_pk_add_f32 v[130:131], v[130:131], v[130:131]
	v_pk_add_f32 v[132:133], v[132:133], v[132:133]
	v_pk_add_f32 v[134:135], v[134:135], v[134:135]
	v_pk_add_f32 v[136:137], v[136:137], v[136:137]
	v_pk_mul_f32 v[130:131], v[130:131], s[8:9] op_sel_hi:[1,0]
	v_pk_mul_f32 v[132:133], v[132:133], s[8:9] op_sel_hi:[1,0]
	v_pk_mul_f32 v[134:135], v[134:135], s[8:9] op_sel_hi:[1,0]
	v_pk_mul_f32 v[136:137], v[136:137], s[8:9] op_sel_hi:[1,0]
	v_exp_f32_e32 v130, v130
	v_exp_f32_e32 v131, v131
	v_exp_f32_e32 v132, v132
	v_exp_f32_e32 v133, v133
	v_exp_f32_e32 v134, v134
	v_exp_f32_e32 v135, v135
	v_exp_f32_e32 v136, v136
	v_exp_f32_e32 v137, v137
	v_pk_add_f32 v[130:131], v[130:131], s[10:11] op_sel_hi:[1,0]
	v_pk_add_f32 v[132:133], v[132:133], s[10:11] op_sel_hi:[1,0]
	v_pk_add_f32 v[134:135], v[134:135], s[10:11] op_sel_hi:[1,0]
	v_pk_add_f32 v[136:137], v[136:137], s[10:11] op_sel_hi:[1,0]
	v_rcp_f32_e32 v130, v130
	v_rcp_f32_e32 v131, v131
	v_rcp_f32_e32 v132, v132
	v_rcp_f32_e32 v133, v133
	v_rcp_f32_e32 v134, v134
	v_rcp_f32_e32 v135, v135
	v_rcp_f32_e32 v136, v136
	v_rcp_f32_e32 v137, v137
	v_pk_mul_f32 v[130:131], v[122:123], v[130:131]
	v_pk_mul_f32 v[132:133], v[124:125], v[132:133]
	v_pk_mul_f32 v[134:135], v[126:127], v[134:135]
; __device__ __forceinline__ unsigned pk2(float lo, float hi) { const f32x2_t v = {lo, hi}; const bf16v2_t b = __builtin_convertvector(v, bf16v2_t); return __builtin_bit_cast(unsigned, b); }
; __device__ __forceinline__ float sigmoidf_(float x) { return frcp(1.f + __expf(-x)); }
; __device__ __forceinline__ float siluf_(float x) { return x * sigmoidf_(x); }
; __device__ __forceinline__ float gelu_tanh_(float x) { const float y = 0.7978845608028654f * (x + 0.044715f * x * x * x); return x * sigmoidf_(2.f * y); }
;     __device__ __forceinline__ void operator()(const AccT& acc, const pg8::Unit& u, int wr, int wc, int fr_, int fq_) const {
;     ...
;             const int seg = (pn - 8) >> 2;
;             bf16_t* base = (bf16_t*)(ws + WS_SG + (size_t)seg * ((size_t)MROWS * D * 2));
;             const int cbase = 256 * ((pn - 8) & 3) + wc * 32 + 8 * fq;
; #pragma unroll
;             for (int ai = 0; ai < 2; ++ai)
; #pragma unroll
;                 for (int m = 0; m < 4; ++m) {
;                     const size_t row = (size_t)u.pm * 256 + rl0 + ai * 128 + m * 16;
; #pragma unroll
;                     for (int bj = 0; bj < 2; ++bj) {
;                         f32x4 a0 = acc[ai][bj][m][0], a1 = acc[ai][bj][m][1];
;                         if (seg == 0) { a0[0] = siluf_(a0[0]); a0[1] = siluf_(a0[1]); a0[2] = siluf_(a0[2]); a0[3] = siluf_(a0[3]); a1[0] = siluf_(a1[0]); a1[1] = siluf_(a1[1]); a1[2] = siluf_(a1[2]); a1[3] = siluf_(a1[3]); }
;                         else if (seg == 2) { a0[0] = gelu_tanh_(a0[0]); a0[1] = gelu_tanh_(a0[1]); a0[2] = gelu_tanh_(a0[2]); a0[3] = gelu_tanh_(a0[3]); a1[0] = gelu_tanh_(a1[0]); a1[1] = gelu_tanh_(a1[1]); a1[2] = gelu_tanh_(a1[2]); a1[3] = gelu_tanh_(a1[3]); }
;                         else if (seg >= 3) { a0[0] = sigmoidf_(a0[0]); a0[1] = sigmoidf_(a0[1]); a0[2] = sigmoidf_(a0[2]); a0[3] = sigmoidf_(a0[3]); a1[0] = sigmoidf_(a1[0]); a1[1] = sigmoidf_(a1[1]); a1[2] = sigmoidf_(a1[2]); a1[3] = sigmoidf_(a1[3]); }
;                         u32x4 o; o[0] = pk2(a0[0], a0[1]); o[1] = pk2(a0[2], a0[3]); o[2] = pk2(a1[0], a1[1]); o[3] = pk2(a1[2], a1[3]);
;                         *(u32x4*)(base + row * D + cbase + bj * 128) = o;
;                     }
;                 }
	v_pk_mul_f32 v[136:137], v[128:129], v[136:137]
	v_cvt_pk_bf16_f32 v122, v130, v131
	v_cvt_pk_bf16_f32 v123, v132, v133
	v_cvt_pk_bf16_f32 v124, v134, v135
	v_cvt_pk_bf16_f32 v125, v136, v137
	global_store_dwordx4 v153, v[122:125], s[78:79]
	v_pk_mul_f32 v[130:131], v[114:115], s[12:13] op_sel_hi:[1,0]
	v_pk_mul_f32 v[132:133], v[116:117], s[12:13] op_sel_hi:[1,0]
	v_pk_mul_f32 v[134:135], v[118:119], s[12:13] op_sel_hi:[1,0]
	v_pk_mul_f32 v[136:137], v[120:121], s[12:13] op_sel_hi:[1,0]
	v_pk_mul_f32 v[130:131], v[114:115], v[130:131]
	v_pk_mul_f32 v[132:133], v[116:117], v[132:133]
	v_pk_mul_f32 v[134:135], v[118:119], v[134:135]
	v_pk_mul_f32 v[136:137], v[120:121], v[136:137]
	v_pk_fma_f32 v[130:131], v[114:115], v[130:131], v[114:115]
	v_pk_fma_f32 v[132:133], v[116:117], v[132:133], v[116:117]
	v_pk_fma_f32 v[134:135], v[118:119], v[134:135], v[118:119]
	v_pk_fma_f32 v[136:137], v[120:121], v[136:137], v[120:121]
	v_pk_mul_f32 v[130:131], v[130:131], s[100:101] op_sel_hi:[1,0]
	v_pk_mul_f32 v[132:133], v[132:133], s[100:101] op_sel_hi:[1,0]
	v_pk_mul_f32 v[134:135], v[134:135], s[100:101] op_sel_hi:[1,0]
	v_pk_mul_f32 v[136:137], v[136:137], s[100:101] op_sel_hi:[1,0]
	v_pk_add_f32 v[130:131], v[130:131], v[130:131]
	v_pk_add_f32 v[132:133], v[132:133], v[132:133]
	v_pk_add_f32 v[134:135], v[134:135], v[134:135]
	v_pk_add_f32 v[136:137], v[136:137], v[136:137]
	v_pk_mul_f32 v[130:131], v[130:131], s[8:9] op_sel_hi:[1,0]
	v_pk_mul_f32 v[132:133], v[132:133], s[8:9] op_sel_hi:[1,0]
	v_pk_mul_f32 v[134:135], v[134:135], s[8:9] op_sel_hi:[1,0]
	v_pk_mul_f32 v[136:137], v[136:137], s[8:9] op_sel_hi:[1,0]
	v_exp_f32_e32 v130, v130
	v_exp_f32_e32 v131, v131
	v_exp_f32_e32 v132, v132
	v_exp_f32_e32 v133, v133
	v_exp_f32_e32 v134, v134
	v_exp_f32_e32 v135, v135
	v_exp_f32_e32 v136, v136
	v_exp_f32_e32 v137, v137
	v_pk_add_f32 v[130:131], v[130:131], s[10:11] op_sel_hi:[1,0]
	v_pk_add_f32 v[132:133], v[132:133], s[10:11] op_sel_hi:[1,0]
	v_pk_add_f32 v[134:135], v[134:135], s[10:11] op_sel_hi:[1,0]
	v_pk_add_f32 v[136:137], v[136:137], s[10:11] op_sel_hi:[1,0]
	v_rcp_f32_e32 v130, v130
	v_rcp_f32_e32 v131, v131
	v_rcp_f32_e32 v132, v132
	v_rcp_f32_e32 v133, v133
	v_rcp_f32_e32 v134, v134
	v_rcp_f32_e32 v135, v135
	v_rcp_f32_e32 v136, v136
	v_rcp_f32_e32 v137, v137
	v_pk_mul_f32 v[130:131], v[114:115], v[130:131]
	v_pk_mul_f32 v[132:133], v[116:117], v[132:133]
	v_pk_mul_f32 v[134:135], v[118:119], v[134:135]
	v_pk_mul_f32 v[136:137], v[120:121], v[136:137]
	v_cvt_pk_bf16_f32 v114, v130, v131
	v_cvt_pk_bf16_f32 v115, v132, v133
	v_cvt_pk_bf16_f32 v116, v134, v135
	v_cvt_pk_bf16_f32 v117, v136, v137
	global_store_dwordx4 v153, v[114:117], s[78:79] offset:256
	s_add_u32 s98, s78, 0x8000
	s_addc_u32 s99, s79, 0
	v_pk_mul_f32 v[130:131], v[106:107], s[12:13] op_sel_hi:[1,0]
	v_pk_mul_f32 v[132:133], v[108:109], s[12:13] op_sel_hi:[1,0]
	v_pk_mul_f32 v[134:135], v[110:111], s[12:13] op_sel_hi:[1,0]
	v_pk_mul_f32 v[136:137], v[112:113], s[12:13] op_sel_hi:[1,0]
	v_pk_mul_f32 v[130:131], v[106:107], v[130:131]
	v_pk_mul_f32 v[132:133], v[108:109], v[132:133]
	v_pk_mul_f32 v[134:135], v[110:111], v[134:135]
	v_pk_mul_f32 v[136:137], v[112:113], v[136:137]
	v_pk_fma_f32 v[130:131], v[106:107], v[130:131], v[106:107]
	v_pk_fma_f32 v[132:133], v[108:109], v[132:133], v[108:109]
	v_pk_fma_f32 v[134:135], v[110:111], v[134:135], v[110:111]
	v_pk_fma_f32 v[136:137], v[112:113], v[136:137], v[112:113]
	v_pk_mul_f32 v[130:131], v[130:131], s[100:101] op_sel_hi:[1,0]
	v_pk_mul_f32 v[132:133], v[132:133], s[100:101] op_sel_hi:[1,0]
	v_pk_mul_f32 v[134:135], v[134:135], s[100:101] op_sel_hi:[1,0]
	v_pk_mul_f32 v[136:137], v[136:137], s[100:101] op_sel_hi:[1,0]
	v_pk_add_f32 v[130:131], v[130:131], v[130:131]
	v_pk_add_f32 v[132:133], v[132:133], v[132:133]
	v_pk_add_f32 v[134:135], v[134:135], v[134:135]
	v_pk_add_f32 v[136:137], v[136:137], v[136:137]
	v_pk_mul_f32 v[130:131], v[130:131], s[8:9] op_sel_hi:[1,0]
	v_pk_mul_f32 v[132:133], v[132:133], s[8:9] op_sel_hi:[1,0]
	v_pk_mul_f32 v[134:135], v[134:135], s[8:9] op_sel_hi:[1,0]
	v_pk_mul_f32 v[136:137], v[136:137], s[8:9] op_sel_hi:[1,0]
	v_exp_f32_e32 v130, v130
	v_exp_f32_e32 v131, v131
	v_exp_f32_e32 v132, v132
	v_exp_f32_e32 v133, v133
	v_exp_f32_e32 v134, v134
	v_exp_f32_e32 v135, v135
	v_exp_f32_e32 v136, v136
	v_exp_f32_e32 v137, v137
	v_pk_add_f32 v[130:131], v[130:131], s[10:11] op_sel_hi:[1,0]
	v_pk_add_f32 v[132:133], v[132:133], s[10:11] op_sel_hi:[1,0]
	v_pk_add_f32 v[134:135], v[134:135], s[10:11] op_sel_hi:[1,0]
	v_pk_add_f32 v[136:137], v[136:137], s[10:11] op_sel_hi:[1,0]
	v_rcp_f32_e32 v130, v130
	v_rcp_f32_e32 v131, v131
	v_rcp_f32_e32 v132, v132
	v_rcp_f32_e32 v133, v133
	v_rcp_f32_e32 v134, v134
	v_rcp_f32_e32 v135, v135
	v_rcp_f32_e32 v136, v136
	v_rcp_f32_e32 v137, v137
	v_pk_mul_f32 v[130:131], v[106:107], v[130:131]
	v_pk_mul_f32 v[132:133], v[108:109], v[132:133]
	v_pk_mul_f32 v[134:135], v[110:111], v[134:135]
	v_pk_mul_f32 v[136:137], v[112:113], v[136:137]
	v_cvt_pk_bf16_f32 v106, v130, v131
	v_cvt_pk_bf16_f32 v107, v132, v133
	v_cvt_pk_bf16_f32 v108, v134, v135
	v_cvt_pk_bf16_f32 v109, v136, v137
	global_store_dwordx4 v153, v[106:109], s[98:99]
	v_pk_mul_f32 v[130:131], v[98:99], s[12:13] op_sel_hi:[1,0]
	v_pk_mul_f32 v[132:133], v[100:101], s[12:13] op_sel_hi:[1,0]
	v_pk_mul_f32 v[134:135], v[102:103], s[12:13] op_sel_hi:[1,0]
	v_pk_mul_f32 v[136:137], v[104:105], s[12:13] op_sel_hi:[1,0]
	v_pk_mul_f32 v[130:131], v[98:99], v[130:131]
	v_pk_mul_f32 v[132:133], v[100:101], v[132:133]
	v_pk_mul_f32 v[134:135], v[102:103], v[134:135]
	v_pk_mul_f32 v[136:137], v[104:105], v[136:137]
; __device__ __forceinline__ unsigned pk2(float lo, float hi) { const f32x2_t v = {lo, hi}; const bf16v2_t b = __builtin_convertvector(v, bf16v2_t); return __builtin_bit_cast(unsigned, b); }
; __device__ __forceinline__ float sigmoidf_(float x) { return frcp(1.f + __expf(-x)); }
; __device__ __forceinline__ float siluf_(float x) { return x * sigmoidf_(x); }
; __device__ __forceinline__ float gelu_tanh_(float x) { const float y = 0.7978845608028654f * (x + 0.044715f * x * x * x); return x * sigmoidf_(2.f * y); }
;     __device__ __forceinline__ void operator()(const AccT& acc, const pg8::Unit& u, int wr, int wc, int fr_, int fq_) const {
;     ...
;             const int seg = (pn - 8) >> 2;
;             bf16_t* base = (bf16_t*)(ws + WS_SG + (size_t)seg * ((size_t)MROWS * D * 2));
;             const int cbase = 256 * ((pn - 8) & 3) + wc * 32 + 8 * fq;
; #pragma unroll
;             for (int ai = 0; ai < 2; ++ai)
; #pragma unroll
;                 for (int m = 0; m < 4; ++m) {
;                     const size_t row = (size_t)u.pm * 256 + rl0 + ai * 128 + m * 16;
; #pragma unroll
;                     for (int bj = 0; bj < 2; ++bj) {
;                         f32x4 a0 = acc[ai][bj][m][0], a1 = acc[ai][bj][m][1];
;                         if (seg == 0) { a0[0] = siluf_(a0[0]); a0[1] = siluf_(a0[1]); a0[2] = siluf_(a0[2]); a0[3] = siluf_(a0[3]); a1[0] = siluf_(a1[0]); a1[1] = siluf_(a1[1]); a1[2] = siluf_(a1[2]); a1[3] = siluf_(a1[3]); }
;                         else if (seg == 2) { a0[0] = gelu_tanh_(a0[0]); a0[1] = gelu_tanh_(a0[1]); a0[2] = gelu_tanh_(a0[2]); a0[3] = gelu_tanh_(a0[3]); a1[0] = gelu_tanh_(a1[0]); a1[1] = gelu_tanh_(a1[1]); a1[2] = gelu_tanh_(a1[2]); a1[3] = gelu_tanh_(a1[3]); }
;                         else if (seg >= 3) { a0[0] = sigmoidf_(a0[0]); a0[1] = sigmoidf_(a0[1]); a0[2] = sigmoidf_(a0[2]); a0[3] = sigmoidf_(a0[3]); a1[0] = sigmoidf_(a1[0]); a1[1] = sigmoidf_(a1[1]); a1[2] = sigmoidf_(a1[2]); a1[3] = sigmoidf_(a1[3]); }
;                         u32x4 o; o[0] = pk2(a0[0], a0[1]); o[1] = pk2(a0[2], a0[3]); o[2] = pk2(a1[0], a1[1]); o[3] = pk2(a1[2], a1[3]);
;                         *(u32x4*)(base + row * D + cbase + bj * 128) = o;
;                     }
;                 }
	v_pk_fma_f32 v[130:131], v[98:99], v[130:131], v[98:99]
	v_pk_fma_f32 v[132:133], v[100:101], v[132:133], v[100:101]
	v_pk_fma_f32 v[134:135], v[102:103], v[134:135], v[102:103]
	v_pk_fma_f32 v[136:137], v[104:105], v[136:137], v[104:105]
	v_pk_mul_f32 v[130:131], v[130:131], s[100:101] op_sel_hi:[1,0]
	v_pk_mul_f32 v[132:133], v[132:133], s[100:101] op_sel_hi:[1,0]
	v_pk_mul_f32 v[134:135], v[134:135], s[100:101] op_sel_hi:[1,0]
	v_pk_mul_f32 v[136:137], v[136:137], s[100:101] op_sel_hi:[1,0]
	v_pk_add_f32 v[130:131], v[130:131], v[130:131]
	v_pk_add_f32 v[132:133], v[132:133], v[132:133]
	v_pk_add_f32 v[134:135], v[134:135], v[134:135]
	v_pk_add_f32 v[136:137], v[136:137], v[136:137]
	v_pk_mul_f32 v[130:131], v[130:131], s[8:9] op_sel_hi:[1,0]
	v_pk_mul_f32 v[132:133], v[132:133], s[8:9] op_sel_hi:[1,0]
	v_pk_mul_f32 v[134:135], v[134:135], s[8:9] op_sel_hi:[1,0]
	v_pk_mul_f32 v[136:137], v[136:137], s[8:9] op_sel_hi:[1,0]
	v_exp_f32_e32 v130, v130
	v_exp_f32_e32 v131, v131
	v_exp_f32_e32 v132, v132
	v_exp_f32_e32 v133, v133
	v_exp_f32_e32 v134, v134
	v_exp_f32_e32 v135, v135
	v_exp_f32_e32 v136, v136
	v_exp_f32_e32 v137, v137
	v_pk_add_f32 v[130:131], v[130:131], s[10:11] op_sel_hi:[1,0]
	v_pk_add_f32 v[132:133], v[132:133], s[10:11] op_sel_hi:[1,0]
	v_pk_add_f32 v[134:135], v[134:135], s[10:11] op_sel_hi:[1,0]
	v_pk_add_f32 v[136:137], v[136:137], s[10:11] op_sel_hi:[1,0]
	v_rcp_f32_e32 v130, v130
	v_rcp_f32_e32 v131, v131
	v_rcp_f32_e32 v132, v132
	v_rcp_f32_e32 v133, v133
	v_rcp_f32_e32 v134, v134
	v_rcp_f32_e32 v135, v135
	v_rcp_f32_e32 v136, v136
	v_rcp_f32_e32 v137, v137
	v_pk_mul_f32 v[130:131], v[98:99], v[130:131]
	v_pk_mul_f32 v[132:133], v[100:101], v[132:133]
	v_pk_mul_f32 v[134:135], v[102:103], v[134:135]
	v_pk_mul_f32 v[136:137], v[104:105], v[136:137]
	v_cvt_pk_bf16_f32 v98, v130, v131
	v_cvt_pk_bf16_f32 v99, v132, v133
	v_cvt_pk_bf16_f32 v100, v134, v135
	v_cvt_pk_bf16_f32 v101, v136, v137
	global_store_dwordx4 v153, v[98:101], s[98:99] offset:256
	s_add_u32 s98, s78, 0x10000
	s_addc_u32 s99, s79, 0
	v_pk_mul_f32 v[130:131], v[90:91], s[12:13] op_sel_hi:[1,0]
	v_pk_mul_f32 v[132:133], v[92:93], s[12:13] op_sel_hi:[1,0]
	v_pk_mul_f32 v[134:135], v[94:95], s[12:13] op_sel_hi:[1,0]
	v_pk_mul_f32 v[136:137], v[96:97], s[12:13] op_sel_hi:[1,0]
	v_pk_mul_f32 v[130:131], v[90:91], v[130:131]
	v_pk_mul_f32 v[132:133], v[92:93], v[132:133]
	v_pk_mul_f32 v[134:135], v[94:95], v[134:135]
	v_pk_mul_f32 v[136:137], v[96:97], v[136:137]
	v_pk_fma_f32 v[130:131], v[90:91], v[130:131], v[90:91]
	v_pk_fma_f32 v[132:133], v[92:93], v[132:133], v[92:93]
	v_pk_fma_f32 v[134:135], v[94:95], v[134:135], v[94:95]
	v_pk_fma_f32 v[136:137], v[96:97], v[136:137], v[96:97]
	v_pk_mul_f32 v[130:131], v[130:131], s[100:101] op_sel_hi:[1,0]
	v_pk_mul_f32 v[132:133], v[132:133], s[100:101] op_sel_hi:[1,0]
	v_pk_mul_f32 v[134:135], v[134:135], s[100:101] op_sel_hi:[1,0]
	v_pk_mul_f32 v[136:137], v[136:137], s[100:101] op_sel_hi:[1,0]
	v_pk_add_f32 v[130:131], v[130:131], v[130:131]
	v_pk_add_f32 v[132:133], v[132:133], v[132:133]
	v_pk_add_f32 v[134:135], v[134:135], v[134:135]
	v_pk_add_f32 v[136:137], v[136:137], v[136:137]
	v_pk_mul_f32 v[130:131], v[130:131], s[8:9] op_sel_hi:[1,0]
	v_pk_mul_f32 v[132:133], v[132:133], s[8:9] op_sel_hi:[1,0]
	v_pk_mul_f32 v[134:135], v[134:135], s[8:9] op_sel_hi:[1,0]
	v_pk_mul_f32 v[136:137], v[136:137], s[8:9] op_sel_hi:[1,0]
	v_exp_f32_e32 v130, v130
	v_exp_f32_e32 v131, v131
	v_exp_f32_e32 v132, v132
	v_exp_f32_e32 v133, v133
	v_exp_f32_e32 v134, v134
	v_exp_f32_e32 v135, v135
	v_exp_f32_e32 v136, v136
	v_exp_f32_e32 v137, v137
	v_pk_add_f32 v[130:131], v[130:131], s[10:11] op_sel_hi:[1,0]
	v_pk_add_f32 v[132:133], v[132:133], s[10:11] op_sel_hi:[1,0]
	v_pk_add_f32 v[134:135], v[134:135], s[10:11] op_sel_hi:[1,0]
	v_pk_add_f32 v[136:137], v[136:137], s[10:11] op_sel_hi:[1,0]
	v_rcp_f32_e32 v130, v130
	v_rcp_f32_e32 v131, v131
	v_rcp_f32_e32 v132, v132
	v_rcp_f32_e32 v133, v133
	v_rcp_f32_e32 v134, v134
	v_rcp_f32_e32 v135, v135
	v_rcp_f32_e32 v136, v136
	v_rcp_f32_e32 v137, v137
	v_pk_mul_f32 v[130:131], v[90:91], v[130:131]
	v_pk_mul_f32 v[132:133], v[92:93], v[132:133]
	v_pk_mul_f32 v[134:135], v[94:95], v[134:135]
	v_pk_mul_f32 v[136:137], v[96:97], v[136:137]
	v_cvt_pk_bf16_f32 v90, v130, v131
	v_cvt_pk_bf16_f32 v91, v132, v133
	v_cvt_pk_bf16_f32 v92, v134, v135
	v_cvt_pk_bf16_f32 v93, v136, v137
	global_store_dwordx4 v153, v[90:93], s[98:99]
	v_pk_mul_f32 v[130:131], v[82:83], s[12:13] op_sel_hi:[1,0]
	v_pk_mul_f32 v[132:133], v[84:85], s[12:13] op_sel_hi:[1,0]
	v_pk_mul_f32 v[134:135], v[86:87], s[12:13] op_sel_hi:[1,0]
	v_pk_mul_f32 v[136:137], v[88:89], s[12:13] op_sel_hi:[1,0]
	v_pk_mul_f32 v[130:131], v[82:83], v[130:131]
	v_pk_mul_f32 v[132:133], v[84:85], v[132:133]
	v_pk_mul_f32 v[134:135], v[86:87], v[134:135]
	v_pk_mul_f32 v[136:137], v[88:89], v[136:137]
	v_pk_fma_f32 v[130:131], v[82:83], v[130:131], v[82:83]
	v_pk_fma_f32 v[132:133], v[84:85], v[132:133], v[84:85]
	v_pk_fma_f32 v[134:135], v[86:87], v[134:135], v[86:87]
	v_pk_fma_f32 v[136:137], v[88:89], v[136:137], v[88:89]
	v_pk_mul_f32 v[130:131], v[130:131], s[100:101] op_sel_hi:[1,0]
	v_pk_mul_f32 v[132:133], v[132:133], s[100:101] op_sel_hi:[1,0]
	v_pk_mul_f32 v[134:135], v[134:135], s[100:101] op_sel_hi:[1,0]
	v_pk_mul_f32 v[136:137], v[136:137], s[100:101] op_sel_hi:[1,0]
	v_pk_add_f32 v[130:131], v[130:131], v[130:131]
	v_pk_add_f32 v[132:133], v[132:133], v[132:133]
	v_pk_add_f32 v[134:135], v[134:135], v[134:135]
	v_pk_add_f32 v[136:137], v[136:137], v[136:137]
	v_pk_mul_f32 v[130:131], v[130:131], s[8:9] op_sel_hi:[1,0]
; __device__ __forceinline__ unsigned pk2(float lo, float hi) { const f32x2_t v = {lo, hi}; const bf16v2_t b = __builtin_convertvector(v, bf16v2_t); return __builtin_bit_cast(unsigned, b); }
; __device__ __forceinline__ float sigmoidf_(float x) { return frcp(1.f + __expf(-x)); }
; __device__ __forceinline__ float siluf_(float x) { return x * sigmoidf_(x); }
; __device__ __forceinline__ float gelu_tanh_(float x) { const float y = 0.7978845608028654f * (x + 0.044715f * x * x * x); return x * sigmoidf_(2.f * y); }
;     __device__ __forceinline__ void operator()(const AccT& acc, const pg8::Unit& u, int wr, int wc, int fr_, int fq_) const {
;     ...
;             const int seg = (pn - 8) >> 2;
;             bf16_t* base = (bf16_t*)(ws + WS_SG + (size_t)seg * ((size_t)MROWS * D * 2));
;             const int cbase = 256 * ((pn - 8) & 3) + wc * 32 + 8 * fq;
; #pragma unroll
;             for (int ai = 0; ai < 2; ++ai)
; #pragma unroll
;                 for (int m = 0; m < 4; ++m) {
;                     const size_t row = (size_t)u.pm * 256 + rl0 + ai * 128 + m * 16;
; #pragma unroll
;                     for (int bj = 0; bj < 2; ++bj) {
;                         f32x4 a0 = acc[ai][bj][m][0], a1 = acc[ai][bj][m][1];
;                         if (seg == 0) { a0[0] = siluf_(a0[0]); a0[1] = siluf_(a0[1]); a0[2] = siluf_(a0[2]); a0[3] = siluf_(a0[3]); a1[0] = siluf_(a1[0]); a1[1] = siluf_(a1[1]); a1[2] = siluf_(a1[2]); a1[3] = siluf_(a1[3]); }
;                         else if (seg == 2) { a0[0] = gelu_tanh_(a0[0]); a0[1] = gelu_tanh_(a0[1]); a0[2] = gelu_tanh_(a0[2]); a0[3] = gelu_tanh_(a0[3]); a1[0] = gelu_tanh_(a1[0]); a1[1] = gelu_tanh_(a1[1]); a1[2] = gelu_tanh_(a1[2]); a1[3] = gelu_tanh_(a1[3]); }
;                         else if (seg >= 3) { a0[0] = sigmoidf_(a0[0]); a0[1] = sigmoidf_(a0[1]); a0[2] = sigmoidf_(a0[2]); a0[3] = sigmoidf_(a0[3]); a1[0] = sigmoidf_(a1[0]); a1[1] = sigmoidf_(a1[1]); a1[2] = sigmoidf_(a1[2]); a1[3] = sigmoidf_(a1[3]); }
;                         u32x4 o; o[0] = pk2(a0[0], a0[1]); o[1] = pk2(a0[2], a0[3]); o[2] = pk2(a1[0], a1[1]); o[3] = pk2(a1[2], a1[3]);
;                         *(u32x4*)(base + row * D + cbase + bj * 128) = o;
;                     }
;                 }
	v_pk_mul_f32 v[132:133], v[132:133], s[8:9] op_sel_hi:[1,0]
	v_pk_mul_f32 v[134:135], v[134:135], s[8:9] op_sel_hi:[1,0]
	v_pk_mul_f32 v[136:137], v[136:137], s[8:9] op_sel_hi:[1,0]
	v_exp_f32_e32 v130, v130
	v_exp_f32_e32 v131, v131
	v_exp_f32_e32 v132, v132
	v_exp_f32_e32 v133, v133
	v_exp_f32_e32 v134, v134
	v_exp_f32_e32 v135, v135
	v_exp_f32_e32 v136, v136
	v_exp_f32_e32 v137, v137
	v_pk_add_f32 v[130:131], v[130:131], s[10:11] op_sel_hi:[1,0]
	v_pk_add_f32 v[132:133], v[132:133], s[10:11] op_sel_hi:[1,0]
	v_pk_add_f32 v[134:135], v[134:135], s[10:11] op_sel_hi:[1,0]
	v_pk_add_f32 v[136:137], v[136:137], s[10:11] op_sel_hi:[1,0]
	v_rcp_f32_e32 v130, v130
	v_rcp_f32_e32 v131, v131
	v_rcp_f32_e32 v132, v132
	v_rcp_f32_e32 v133, v133
	v_rcp_f32_e32 v134, v134
	v_rcp_f32_e32 v135, v135
	v_rcp_f32_e32 v136, v136
	v_rcp_f32_e32 v137, v137
	v_pk_mul_f32 v[130:131], v[82:83], v[130:131]
	v_pk_mul_f32 v[132:133], v[84:85], v[132:133]
	v_pk_mul_f32 v[134:135], v[86:87], v[134:135]
	v_pk_mul_f32 v[136:137], v[88:89], v[136:137]
	v_cvt_pk_bf16_f32 v82, v130, v131
	v_cvt_pk_bf16_f32 v83, v132, v133
	v_cvt_pk_bf16_f32 v84, v134, v135
	v_cvt_pk_bf16_f32 v85, v136, v137
	global_store_dwordx4 v153, v[82:85], s[98:99] offset:256
	s_add_u32 s98, s78, 0x18000
	s_addc_u32 s99, s79, 0
	v_pk_mul_f32 v[130:131], v[74:75], s[12:13] op_sel_hi:[1,0]
	v_pk_mul_f32 v[132:133], v[76:77], s[12:13] op_sel_hi:[1,0]
	v_pk_mul_f32 v[134:135], v[78:79], s[12:13] op_sel_hi:[1,0]
	v_pk_mul_f32 v[136:137], v[80:81], s[12:13] op_sel_hi:[1,0]
	v_pk_mul_f32 v[130:131], v[74:75], v[130:131]
	v_pk_mul_f32 v[132:133], v[76:77], v[132:133]
	v_pk_mul_f32 v[134:135], v[78:79], v[134:135]
	v_pk_mul_f32 v[136:137], v[80:81], v[136:137]
	v_pk_fma_f32 v[130:131], v[74:75], v[130:131], v[74:75]
	v_pk_fma_f32 v[132:133], v[76:77], v[132:133], v[76:77]
	v_pk_fma_f32 v[134:135], v[78:79], v[134:135], v[78:79]
	v_pk_fma_f32 v[136:137], v[80:81], v[136:137], v[80:81]
	v_pk_mul_f32 v[130:131], v[130:131], s[100:101] op_sel_hi:[1,0]
	v_pk_mul_f32 v[132:133], v[132:133], s[100:101] op_sel_hi:[1,0]
	v_pk_mul_f32 v[134:135], v[134:135], s[100:101] op_sel_hi:[1,0]
	v_pk_mul_f32 v[136:137], v[136:137], s[100:101] op_sel_hi:[1,0]
	v_pk_add_f32 v[130:131], v[130:131], v[130:131]
	v_pk_add_f32 v[132:133], v[132:133], v[132:133]
	v_pk_add_f32 v[134:135], v[134:135], v[134:135]
	v_pk_add_f32 v[136:137], v[136:137], v[136:137]
	v_pk_mul_f32 v[130:131], v[130:131], s[8:9] op_sel_hi:[1,0]
	v_pk_mul_f32 v[132:133], v[132:133], s[8:9] op_sel_hi:[1,0]
	v_pk_mul_f32 v[134:135], v[134:135], s[8:9] op_sel_hi:[1,0]
	v_pk_mul_f32 v[136:137], v[136:137], s[8:9] op_sel_hi:[1,0]
	v_exp_f32_e32 v130, v130
	v_exp_f32_e32 v131, v131
	v_exp_f32_e32 v132, v132
	v_exp_f32_e32 v133, v133
	v_exp_f32_e32 v134, v134
	v_exp_f32_e32 v135, v135
	v_exp_f32_e32 v136, v136
	v_exp_f32_e32 v137, v137
	v_pk_add_f32 v[130:131], v[130:131], s[10:11] op_sel_hi:[1,0]
	v_pk_add_f32 v[132:133], v[132:133], s[10:11] op_sel_hi:[1,0]
	v_pk_add_f32 v[134:135], v[134:135], s[10:11] op_sel_hi:[1,0]
	v_pk_add_f32 v[136:137], v[136:137], s[10:11] op_sel_hi:[1,0]
	v_rcp_f32_e32 v130, v130
	v_rcp_f32_e32 v131, v131
	v_rcp_f32_e32 v132, v132
	v_rcp_f32_e32 v133, v133
	v_rcp_f32_e32 v134, v134
	v_rcp_f32_e32 v135, v135
	v_rcp_f32_e32 v136, v136
	v_rcp_f32_e32 v137, v137
	v_pk_mul_f32 v[130:131], v[74:75], v[130:131]
	v_pk_mul_f32 v[132:133], v[76:77], v[132:133]
	v_pk_mul_f32 v[134:135], v[78:79], v[134:135]
	v_pk_mul_f32 v[136:137], v[80:81], v[136:137]
	v_cvt_pk_bf16_f32 v74, v130, v131
	v_cvt_pk_bf16_f32 v75, v132, v133
	v_cvt_pk_bf16_f32 v76, v134, v135
	v_cvt_pk_bf16_f32 v77, v136, v137
	global_store_dwordx4 v153, v[74:77], s[98:99]
	v_pk_mul_f32 v[130:131], v[66:67], s[12:13] op_sel_hi:[1,0]
	v_pk_mul_f32 v[132:133], v[68:69], s[12:13] op_sel_hi:[1,0]
	v_pk_mul_f32 v[134:135], v[70:71], s[12:13] op_sel_hi:[1,0]
	v_pk_mul_f32 v[136:137], v[72:73], s[12:13] op_sel_hi:[1,0]
	v_pk_mul_f32 v[130:131], v[66:67], v[130:131]
	v_pk_mul_f32 v[132:133], v[68:69], v[132:133]
	v_pk_mul_f32 v[134:135], v[70:71], v[134:135]
	v_pk_mul_f32 v[136:137], v[72:73], v[136:137]
	v_pk_fma_f32 v[130:131], v[66:67], v[130:131], v[66:67]
	v_pk_fma_f32 v[132:133], v[68:69], v[132:133], v[68:69]
	v_pk_fma_f32 v[134:135], v[70:71], v[134:135], v[70:71]
	v_pk_fma_f32 v[136:137], v[72:73], v[136:137], v[72:73]
	v_pk_mul_f32 v[130:131], v[130:131], s[100:101] op_sel_hi:[1,0]
	v_pk_mul_f32 v[132:133], v[132:133], s[100:101] op_sel_hi:[1,0]
	v_pk_mul_f32 v[134:135], v[134:135], s[100:101] op_sel_hi:[1,0]
	v_pk_mul_f32 v[136:137], v[136:137], s[100:101] op_sel_hi:[1,0]
	v_pk_add_f32 v[130:131], v[130:131], v[130:131]
	v_pk_add_f32 v[132:133], v[132:133], v[132:133]
	v_pk_add_f32 v[134:135], v[134:135], v[134:135]
	v_pk_add_f32 v[136:137], v[136:137], v[136:137]
	v_pk_mul_f32 v[130:131], v[130:131], s[8:9] op_sel_hi:[1,0]
	v_pk_mul_f32 v[132:133], v[132:133], s[8:9] op_sel_hi:[1,0]
	v_pk_mul_f32 v[134:135], v[134:135], s[8:9] op_sel_hi:[1,0]
	v_pk_mul_f32 v[136:137], v[136:137], s[8:9] op_sel_hi:[1,0]
	v_exp_f32_e32 v130, v130
	v_exp_f32_e32 v131, v131
	v_exp_f32_e32 v132, v132
	v_exp_f32_e32 v133, v133
	v_exp_f32_e32 v134, v134
	v_exp_f32_e32 v135, v135
	v_exp_f32_e32 v136, v136
	v_exp_f32_e32 v137, v137
	v_pk_add_f32 v[130:131], v[130:131], s[10:11] op_sel_hi:[1,0]
	v_pk_add_f32 v[132:133], v[132:133], s[10:11] op_sel_hi:[1,0]
	v_pk_add_f32 v[134:135], v[134:135], s[10:11] op_sel_hi:[1,0]
	v_pk_add_f32 v[136:137], v[136:137], s[10:11] op_sel_hi:[1,0]
	v_rcp_f32_e32 v130, v130
	v_rcp_f32_e32 v131, v131
	v_rcp_f32_e32 v132, v132
	v_rcp_f32_e32 v133, v133
	v_rcp_f32_e32 v134, v134
; __device__ __forceinline__ unsigned pk2(float lo, float hi) { const f32x2_t v = {lo, hi}; const bf16v2_t b = __builtin_convertvector(v, bf16v2_t); return __builtin_bit_cast(unsigned, b); }
; __device__ __forceinline__ float sigmoidf_(float x) { return frcp(1.f + __expf(-x)); }
; __device__ __forceinline__ float siluf_(float x) { return x * sigmoidf_(x); }
; __device__ __forceinline__ float gelu_tanh_(float x) { const float y = 0.7978845608028654f * (x + 0.044715f * x * x * x); return x * sigmoidf_(2.f * y); }
;     __device__ __forceinline__ void operator()(const AccT& acc, const pg8::Unit& u, int wr, int wc, int fr_, int fq_) const {
;     ...
;             const int seg = (pn - 8) >> 2;
;             bf16_t* base = (bf16_t*)(ws + WS_SG + (size_t)seg * ((size_t)MROWS * D * 2));
;             const int cbase = 256 * ((pn - 8) & 3) + wc * 32 + 8 * fq;
; #pragma unroll
;             for (int ai = 0; ai < 2; ++ai)
; #pragma unroll
;                 for (int m = 0; m < 4; ++m) {
;                     const size_t row = (size_t)u.pm * 256 + rl0 + ai * 128 + m * 16;
; #pragma unroll
;                     for (int bj = 0; bj < 2; ++bj) {
;                         f32x4 a0 = acc[ai][bj][m][0], a1 = acc[ai][bj][m][1];
;                         if (seg == 0) { a0[0] = siluf_(a0[0]); a0[1] = siluf_(a0[1]); a0[2] = siluf_(a0[2]); a0[3] = siluf_(a0[3]); a1[0] = siluf_(a1[0]); a1[1] = siluf_(a1[1]); a1[2] = siluf_(a1[2]); a1[3] = siluf_(a1[3]); }
;                         else if (seg == 2) { a0[0] = gelu_tanh_(a0[0]); a0[1] = gelu_tanh_(a0[1]); a0[2] = gelu_tanh_(a0[2]); a0[3] = gelu_tanh_(a0[3]); a1[0] = gelu_tanh_(a1[0]); a1[1] = gelu_tanh_(a1[1]); a1[2] = gelu_tanh_(a1[2]); a1[3] = gelu_tanh_(a1[3]); }
;                         else if (seg >= 3) { a0[0] = sigmoidf_(a0[0]); a0[1] = sigmoidf_(a0[1]); a0[2] = sigmoidf_(a0[2]); a0[3] = sigmoidf_(a0[3]); a1[0] = sigmoidf_(a1[0]); a1[1] = sigmoidf_(a1[1]); a1[2] = sigmoidf_(a1[2]); a1[3] = sigmoidf_(a1[3]); }
;                         u32x4 o; o[0] = pk2(a0[0], a0[1]); o[1] = pk2(a0[2], a0[3]); o[2] = pk2(a1[0], a1[1]); o[3] = pk2(a1[2], a1[3]);
;                         *(u32x4*)(base + row * D + cbase + bj * 128) = o;
;                     }
;                 }
	v_rcp_f32_e32 v135, v135
	v_rcp_f32_e32 v136, v136
	v_rcp_f32_e32 v137, v137
	v_pk_mul_f32 v[130:131], v[66:67], v[130:131]
	v_pk_mul_f32 v[132:133], v[68:69], v[132:133]
	v_pk_mul_f32 v[134:135], v[70:71], v[134:135]
	v_pk_mul_f32 v[136:137], v[72:73], v[136:137]
	v_cvt_pk_bf16_f32 v66, v130, v131
	v_cvt_pk_bf16_f32 v67, v132, v133
	v_cvt_pk_bf16_f32 v68, v134, v135
	v_cvt_pk_bf16_f32 v69, v136, v137
	global_store_dwordx4 v153, v[66:69], s[98:99] offset:256
	s_add_u32 s98, s78, 0x40000
	s_addc_u32 s99, s79, 0
	v_pk_mul_f32 v[130:131], v[58:59], s[12:13] op_sel_hi:[1,0]
	v_pk_mul_f32 v[132:133], v[60:61], s[12:13] op_sel_hi:[1,0]
	v_pk_mul_f32 v[134:135], v[62:63], s[12:13] op_sel_hi:[1,0]
	v_pk_mul_f32 v[136:137], v[64:65], s[12:13] op_sel_hi:[1,0]
	v_pk_mul_f32 v[130:131], v[58:59], v[130:131]
	v_pk_mul_f32 v[132:133], v[60:61], v[132:133]
	v_pk_mul_f32 v[134:135], v[62:63], v[134:135]
	v_pk_mul_f32 v[136:137], v[64:65], v[136:137]
	v_pk_fma_f32 v[130:131], v[58:59], v[130:131], v[58:59]
	v_pk_fma_f32 v[132:133], v[60:61], v[132:133], v[60:61]
	v_pk_fma_f32 v[134:135], v[62:63], v[134:135], v[62:63]
	v_pk_fma_f32 v[136:137], v[64:65], v[136:137], v[64:65]
	v_pk_mul_f32 v[130:131], v[130:131], s[100:101] op_sel_hi:[1,0]
	v_pk_mul_f32 v[132:133], v[132:133], s[100:101] op_sel_hi:[1,0]
	v_pk_mul_f32 v[134:135], v[134:135], s[100:101] op_sel_hi:[1,0]
	v_pk_mul_f32 v[136:137], v[136:137], s[100:101] op_sel_hi:[1,0]
	v_pk_add_f32 v[130:131], v[130:131], v[130:131]
	v_pk_add_f32 v[132:133], v[132:133], v[132:133]
	v_pk_add_f32 v[134:135], v[134:135], v[134:135]
	v_pk_add_f32 v[136:137], v[136:137], v[136:137]
	v_pk_mul_f32 v[130:131], v[130:131], s[8:9] op_sel_hi:[1,0]
	v_pk_mul_f32 v[132:133], v[132:133], s[8:9] op_sel_hi:[1,0]
	v_pk_mul_f32 v[134:135], v[134:135], s[8:9] op_sel_hi:[1,0]
	v_pk_mul_f32 v[136:137], v[136:137], s[8:9] op_sel_hi:[1,0]
	v_exp_f32_e32 v130, v130
	v_exp_f32_e32 v131, v131
	v_exp_f32_e32 v132, v132
	v_exp_f32_e32 v133, v133
	v_exp_f32_e32 v134, v134
	v_exp_f32_e32 v135, v135
	v_exp_f32_e32 v136, v136
	v_exp_f32_e32 v137, v137
	v_pk_add_f32 v[130:131], v[130:131], s[10:11] op_sel_hi:[1,0]
	v_pk_add_f32 v[132:133], v[132:133], s[10:11] op_sel_hi:[1,0]
	v_pk_add_f32 v[134:135], v[134:135], s[10:11] op_sel_hi:[1,0]
	v_pk_add_f32 v[136:137], v[136:137], s[10:11] op_sel_hi:[1,0]
	v_rcp_f32_e32 v130, v130
	v_rcp_f32_e32 v131, v131
	v_rcp_f32_e32 v132, v132
	v_rcp_f32_e32 v133, v133
	v_rcp_f32_e32 v134, v134
	v_rcp_f32_e32 v135, v135
	v_rcp_f32_e32 v136, v136
	v_rcp_f32_e32 v137, v137
	v_pk_mul_f32 v[130:131], v[58:59], v[130:131]
	v_pk_mul_f32 v[132:133], v[60:61], v[132:133]
	v_pk_mul_f32 v[134:135], v[62:63], v[134:135]
	v_pk_mul_f32 v[136:137], v[64:65], v[136:137]
	v_cvt_pk_bf16_f32 v58, v130, v131
	v_cvt_pk_bf16_f32 v59, v132, v133
	v_cvt_pk_bf16_f32 v60, v134, v135
	v_cvt_pk_bf16_f32 v61, v136, v137
	global_store_dwordx4 v153, v[58:61], s[98:99]
	v_pk_mul_f32 v[130:131], v[50:51], s[12:13] op_sel_hi:[1,0]
	v_pk_mul_f32 v[132:133], v[52:53], s[12:13] op_sel_hi:[1,0]
	v_pk_mul_f32 v[134:135], v[54:55], s[12:13] op_sel_hi:[1,0]
	v_pk_mul_f32 v[136:137], v[56:57], s[12:13] op_sel_hi:[1,0]
	v_pk_mul_f32 v[130:131], v[50:51], v[130:131]
	v_pk_mul_f32 v[132:133], v[52:53], v[132:133]
	v_pk_mul_f32 v[134:135], v[54:55], v[134:135]
	v_pk_mul_f32 v[136:137], v[56:57], v[136:137]
	v_pk_fma_f32 v[130:131], v[50:51], v[130:131], v[50:51]
	v_pk_fma_f32 v[132:133], v[52:53], v[132:133], v[52:53]
	v_pk_fma_f32 v[134:135], v[54:55], v[134:135], v[54:55]
	v_pk_fma_f32 v[136:137], v[56:57], v[136:137], v[56:57]
	v_pk_mul_f32 v[130:131], v[130:131], s[100:101] op_sel_hi:[1,0]
	v_pk_mul_f32 v[132:133], v[132:133], s[100:101] op_sel_hi:[1,0]
	v_pk_mul_f32 v[134:135], v[134:135], s[100:101] op_sel_hi:[1,0]
	v_pk_mul_f32 v[136:137], v[136:137], s[100:101] op_sel_hi:[1,0]
	v_pk_add_f32 v[130:131], v[130:131], v[130:131]
	v_pk_add_f32 v[132:133], v[132:133], v[132:133]
	v_pk_add_f32 v[134:135], v[134:135], v[134:135]
	v_pk_add_f32 v[136:137], v[136:137], v[136:137]
	v_pk_mul_f32 v[130:131], v[130:131], s[8:9] op_sel_hi:[1,0]
	v_pk_mul_f32 v[132:133], v[132:133], s[8:9] op_sel_hi:[1,0]
	v_pk_mul_f32 v[134:135], v[134:135], s[8:9] op_sel_hi:[1,0]
	v_pk_mul_f32 v[136:137], v[136:137], s[8:9] op_sel_hi:[1,0]
	v_exp_f32_e32 v130, v130
	v_exp_f32_e32 v131, v131
	v_exp_f32_e32 v132, v132
	v_exp_f32_e32 v133, v133
	v_exp_f32_e32 v134, v134
	v_exp_f32_e32 v135, v135
	v_exp_f32_e32 v136, v136
	v_exp_f32_e32 v137, v137
	v_pk_add_f32 v[130:131], v[130:131], s[10:11] op_sel_hi:[1,0]
	v_pk_add_f32 v[132:133], v[132:133], s[10:11] op_sel_hi:[1,0]
	v_pk_add_f32 v[134:135], v[134:135], s[10:11] op_sel_hi:[1,0]
	v_pk_add_f32 v[136:137], v[136:137], s[10:11] op_sel_hi:[1,0]
	v_rcp_f32_e32 v130, v130
	v_rcp_f32_e32 v131, v131
	v_rcp_f32_e32 v132, v132
	v_rcp_f32_e32 v133, v133
	v_rcp_f32_e32 v134, v134
	v_rcp_f32_e32 v135, v135
	v_rcp_f32_e32 v136, v136
	v_rcp_f32_e32 v137, v137
	v_pk_mul_f32 v[130:131], v[50:51], v[130:131]
	v_pk_mul_f32 v[132:133], v[52:53], v[132:133]
	v_pk_mul_f32 v[134:135], v[54:55], v[134:135]
	v_pk_mul_f32 v[136:137], v[56:57], v[136:137]
	v_cvt_pk_bf16_f32 v50, v130, v131
	v_cvt_pk_bf16_f32 v51, v132, v133
	v_cvt_pk_bf16_f32 v52, v134, v135
	v_cvt_pk_bf16_f32 v53, v136, v137
	global_store_dwordx4 v153, v[50:53], s[98:99] offset:256
	s_add_u32 s98, s78, 0x48000
	s_addc_u32 s99, s79, 0
	v_pk_mul_f32 v[130:131], v[42:43], s[12:13] op_sel_hi:[1,0]
	v_pk_mul_f32 v[132:133], v[44:45], s[12:13] op_sel_hi:[1,0]
	v_pk_mul_f32 v[134:135], v[46:47], s[12:13] op_sel_hi:[1,0]
	v_pk_mul_f32 v[136:137], v[48:49], s[12:13] op_sel_hi:[1,0]
; __device__ __forceinline__ unsigned pk2(float lo, float hi) { const f32x2_t v = {lo, hi}; const bf16v2_t b = __builtin_convertvector(v, bf16v2_t); return __builtin_bit_cast(unsigned, b); }
; __device__ __forceinline__ float sigmoidf_(float x) { return frcp(1.f + __expf(-x)); }
; __device__ __forceinline__ float siluf_(float x) { return x * sigmoidf_(x); }
; __device__ __forceinline__ float gelu_tanh_(float x) { const float y = 0.7978845608028654f * (x + 0.044715f * x * x * x); return x * sigmoidf_(2.f * y); }
;     __device__ __forceinline__ void operator()(const AccT& acc, const pg8::Unit& u, int wr, int wc, int fr_, int fq_) const {
;     ...
;             const int seg = (pn - 8) >> 2;
;             bf16_t* base = (bf16_t*)(ws + WS_SG + (size_t)seg * ((size_t)MROWS * D * 2));
;             const int cbase = 256 * ((pn - 8) & 3) + wc * 32 + 8 * fq;
; #pragma unroll
;             for (int ai = 0; ai < 2; ++ai)
; #pragma unroll
;                 for (int m = 0; m < 4; ++m) {
;                     const size_t row = (size_t)u.pm * 256 + rl0 + ai * 128 + m * 16;
; #pragma unroll
;                     for (int bj = 0; bj < 2; ++bj) {
;                         f32x4 a0 = acc[ai][bj][m][0], a1 = acc[ai][bj][m][1];
;                         if (seg == 0) { a0[0] = siluf_(a0[0]); a0[1] = siluf_(a0[1]); a0[2] = siluf_(a0[2]); a0[3] = siluf_(a0[3]); a1[0] = siluf_(a1[0]); a1[1] = siluf_(a1[1]); a1[2] = siluf_(a1[2]); a1[3] = siluf_(a1[3]); }
;                         else if (seg == 2) { a0[0] = gelu_tanh_(a0[0]); a0[1] = gelu_tanh_(a0[1]); a0[2] = gelu_tanh_(a0[2]); a0[3] = gelu_tanh_(a0[3]); a1[0] = gelu_tanh_(a1[0]); a1[1] = gelu_tanh_(a1[1]); a1[2] = gelu_tanh_(a1[2]); a1[3] = gelu_tanh_(a1[3]); }
;                         else if (seg >= 3) { a0[0] = sigmoidf_(a0[0]); a0[1] = sigmoidf_(a0[1]); a0[2] = sigmoidf_(a0[2]); a0[3] = sigmoidf_(a0[3]); a1[0] = sigmoidf_(a1[0]); a1[1] = sigmoidf_(a1[1]); a1[2] = sigmoidf_(a1[2]); a1[3] = sigmoidf_(a1[3]); }
;                         u32x4 o; o[0] = pk2(a0[0], a0[1]); o[1] = pk2(a0[2], a0[3]); o[2] = pk2(a1[0], a1[1]); o[3] = pk2(a1[2], a1[3]);
;                         *(u32x4*)(base + row * D + cbase + bj * 128) = o;
;                     }
;                 }
	v_pk_mul_f32 v[130:131], v[42:43], v[130:131]
	v_pk_mul_f32 v[132:133], v[44:45], v[132:133]
	v_pk_mul_f32 v[134:135], v[46:47], v[134:135]
	v_pk_mul_f32 v[136:137], v[48:49], v[136:137]
	v_pk_fma_f32 v[130:131], v[42:43], v[130:131], v[42:43]
	v_pk_fma_f32 v[132:133], v[44:45], v[132:133], v[44:45]
	v_pk_fma_f32 v[134:135], v[46:47], v[134:135], v[46:47]
	v_pk_fma_f32 v[136:137], v[48:49], v[136:137], v[48:49]
	v_pk_mul_f32 v[130:131], v[130:131], s[100:101] op_sel_hi:[1,0]
	v_pk_mul_f32 v[132:133], v[132:133], s[100:101] op_sel_hi:[1,0]
	v_pk_mul_f32 v[134:135], v[134:135], s[100:101] op_sel_hi:[1,0]
	v_pk_mul_f32 v[136:137], v[136:137], s[100:101] op_sel_hi:[1,0]
	v_pk_add_f32 v[130:131], v[130:131], v[130:131]
	v_pk_add_f32 v[132:133], v[132:133], v[132:133]
	v_pk_add_f32 v[134:135], v[134:135], v[134:135]
	v_pk_add_f32 v[136:137], v[136:137], v[136:137]
	v_pk_mul_f32 v[130:131], v[130:131], s[8:9] op_sel_hi:[1,0]
	v_pk_mul_f32 v[132:133], v[132:133], s[8:9] op_sel_hi:[1,0]
	v_pk_mul_f32 v[134:135], v[134:135], s[8:9] op_sel_hi:[1,0]
	v_pk_mul_f32 v[136:137], v[136:137], s[8:9] op_sel_hi:[1,0]
	v_exp_f32_e32 v130, v130
	v_exp_f32_e32 v131, v131
	v_exp_f32_e32 v132, v132
	v_exp_f32_e32 v133, v133
	v_exp_f32_e32 v134, v134
	v_exp_f32_e32 v135, v135
	v_exp_f32_e32 v136, v136
	v_exp_f32_e32 v137, v137
	v_pk_add_f32 v[130:131], v[130:131], s[10:11] op_sel_hi:[1,0]
	v_pk_add_f32 v[132:133], v[132:133], s[10:11] op_sel_hi:[1,0]
	v_pk_add_f32 v[134:135], v[134:135], s[10:11] op_sel_hi:[1,0]
	v_pk_add_f32 v[136:137], v[136:137], s[10:11] op_sel_hi:[1,0]
	v_rcp_f32_e32 v130, v130
	v_rcp_f32_e32 v131, v131
	v_rcp_f32_e32 v132, v132
	v_rcp_f32_e32 v133, v133
	v_rcp_f32_e32 v134, v134
	v_rcp_f32_e32 v135, v135
	v_rcp_f32_e32 v136, v136
	v_rcp_f32_e32 v137, v137
	v_pk_mul_f32 v[130:131], v[42:43], v[130:131]
	v_pk_mul_f32 v[132:133], v[44:45], v[132:133]
	v_pk_mul_f32 v[134:135], v[46:47], v[134:135]
	v_pk_mul_f32 v[136:137], v[48:49], v[136:137]
	v_cvt_pk_bf16_f32 v42, v130, v131
	v_cvt_pk_bf16_f32 v43, v132, v133
	v_cvt_pk_bf16_f32 v44, v134, v135
	v_cvt_pk_bf16_f32 v45, v136, v137
	global_store_dwordx4 v153, v[42:45], s[98:99]
	v_pk_mul_f32 v[130:131], v[34:35], s[12:13] op_sel_hi:[1,0]
	v_pk_mul_f32 v[132:133], v[36:37], s[12:13] op_sel_hi:[1,0]
	v_pk_mul_f32 v[134:135], v[38:39], s[12:13] op_sel_hi:[1,0]
	v_pk_mul_f32 v[136:137], v[40:41], s[12:13] op_sel_hi:[1,0]
	v_pk_mul_f32 v[130:131], v[34:35], v[130:131]
	v_pk_mul_f32 v[132:133], v[36:37], v[132:133]
	v_pk_mul_f32 v[134:135], v[38:39], v[134:135]
	v_pk_mul_f32 v[136:137], v[40:41], v[136:137]
	v_pk_fma_f32 v[130:131], v[34:35], v[130:131], v[34:35]
	v_pk_fma_f32 v[132:133], v[36:37], v[132:133], v[36:37]
	v_pk_fma_f32 v[134:135], v[38:39], v[134:135], v[38:39]
	v_pk_fma_f32 v[136:137], v[40:41], v[136:137], v[40:41]
	v_pk_mul_f32 v[130:131], v[130:131], s[100:101] op_sel_hi:[1,0]
	v_pk_mul_f32 v[132:133], v[132:133], s[100:101] op_sel_hi:[1,0]
	v_pk_mul_f32 v[134:135], v[134:135], s[100:101] op_sel_hi:[1,0]
	v_pk_mul_f32 v[136:137], v[136:137], s[100:101] op_sel_hi:[1,0]
	v_pk_add_f32 v[130:131], v[130:131], v[130:131]
	v_pk_add_f32 v[132:133], v[132:133], v[132:133]
	v_pk_add_f32 v[134:135], v[134:135], v[134:135]
	v_pk_add_f32 v[136:137], v[136:137], v[136:137]
	v_pk_mul_f32 v[130:131], v[130:131], s[8:9] op_sel_hi:[1,0]
	v_pk_mul_f32 v[132:133], v[132:133], s[8:9] op_sel_hi:[1,0]
	v_pk_mul_f32 v[134:135], v[134:135], s[8:9] op_sel_hi:[1,0]
	v_pk_mul_f32 v[136:137], v[136:137], s[8:9] op_sel_hi:[1,0]
	v_exp_f32_e32 v130, v130
	v_exp_f32_e32 v131, v131
	v_exp_f32_e32 v132, v132
	v_exp_f32_e32 v133, v133
	v_exp_f32_e32 v134, v134
	v_exp_f32_e32 v135, v135
	v_exp_f32_e32 v136, v136
	v_exp_f32_e32 v137, v137
	v_pk_add_f32 v[130:131], v[130:131], s[10:11] op_sel_hi:[1,0]
	v_pk_add_f32 v[132:133], v[132:133], s[10:11] op_sel_hi:[1,0]
	v_pk_add_f32 v[134:135], v[134:135], s[10:11] op_sel_hi:[1,0]
	v_pk_add_f32 v[136:137], v[136:137], s[10:11] op_sel_hi:[1,0]
	v_rcp_f32_e32 v130, v130
	v_rcp_f32_e32 v131, v131
	v_rcp_f32_e32 v132, v132
	v_rcp_f32_e32 v133, v133
	v_rcp_f32_e32 v134, v134
	v_rcp_f32_e32 v135, v135
	v_rcp_f32_e32 v136, v136
	v_rcp_f32_e32 v137, v137
	v_pk_mul_f32 v[130:131], v[34:35], v[130:131]
	v_pk_mul_f32 v[132:133], v[36:37], v[132:133]
	v_pk_mul_f32 v[134:135], v[38:39], v[134:135]
	v_pk_mul_f32 v[136:137], v[40:41], v[136:137]
	v_cvt_pk_bf16_f32 v34, v130, v131
	v_cvt_pk_bf16_f32 v35, v132, v133
	v_cvt_pk_bf16_f32 v36, v134, v135
	v_cvt_pk_bf16_f32 v37, v136, v137
	global_store_dwordx4 v153, v[34:37], s[98:99] offset:256
	s_add_u32 s98, s78, 0x50000
	s_addc_u32 s99, s79, 0
	v_pk_mul_f32 v[130:131], v[26:27], s[12:13] op_sel_hi:[1,0]
	v_pk_mul_f32 v[132:133], v[28:29], s[12:13] op_sel_hi:[1,0]
	v_pk_mul_f32 v[134:135], v[30:31], s[12:13] op_sel_hi:[1,0]
	v_pk_mul_f32 v[136:137], v[32:33], s[12:13] op_sel_hi:[1,0]
	v_pk_mul_f32 v[130:131], v[26:27], v[130:131]
	v_pk_mul_f32 v[132:133], v[28:29], v[132:133]
	v_pk_mul_f32 v[134:135], v[30:31], v[134:135]
	v_pk_mul_f32 v[136:137], v[32:33], v[136:137]
	v_pk_fma_f32 v[130:131], v[26:27], v[130:131], v[26:27]
	v_pk_fma_f32 v[132:133], v[28:29], v[132:133], v[28:29]
	v_pk_fma_f32 v[134:135], v[30:31], v[134:135], v[30:31]
	v_pk_fma_f32 v[136:137], v[32:33], v[136:137], v[32:33]
	v_pk_mul_f32 v[130:131], v[130:131], s[100:101] op_sel_hi:[1,0]
	v_pk_mul_f32 v[132:133], v[132:133], s[100:101] op_sel_hi:[1,0]
	v_pk_mul_f32 v[134:135], v[134:135], s[100:101] op_sel_hi:[1,0]
	v_pk_mul_f32 v[136:137], v[136:137], s[100:101] op_sel_hi:[1,0]
	v_pk_add_f32 v[130:131], v[130:131], v[130:131]
	v_pk_add_f32 v[132:133], v[132:133], v[132:133]
; __device__ __forceinline__ unsigned pk2(float lo, float hi) { const f32x2_t v = {lo, hi}; const bf16v2_t b = __builtin_convertvector(v, bf16v2_t); return __builtin_bit_cast(unsigned, b); }
; __device__ __forceinline__ float sigmoidf_(float x) { return frcp(1.f + __expf(-x)); }
; __device__ __forceinline__ float siluf_(float x) { return x * sigmoidf_(x); }
; __device__ __forceinline__ float gelu_tanh_(float x) { const float y = 0.7978845608028654f * (x + 0.044715f * x * x * x); return x * sigmoidf_(2.f * y); }
;     __device__ __forceinline__ void operator()(const AccT& acc, const pg8::Unit& u, int wr, int wc, int fr_, int fq_) const {
;     ...
;             const int seg = (pn - 8) >> 2;
;             bf16_t* base = (bf16_t*)(ws + WS_SG + (size_t)seg * ((size_t)MROWS * D * 2));
;             const int cbase = 256 * ((pn - 8) & 3) + wc * 32 + 8 * fq;
; #pragma unroll
;             for (int ai = 0; ai < 2; ++ai)
; #pragma unroll
;                 for (int m = 0; m < 4; ++m) {
;                     const size_t row = (size_t)u.pm * 256 + rl0 + ai * 128 + m * 16;
; #pragma unroll
;                     for (int bj = 0; bj < 2; ++bj) {
;                         f32x4 a0 = acc[ai][bj][m][0], a1 = acc[ai][bj][m][1];
;                         if (seg == 0) { a0[0] = siluf_(a0[0]); a0[1] = siluf_(a0[1]); a0[2] = siluf_(a0[2]); a0[3] = siluf_(a0[3]); a1[0] = siluf_(a1[0]); a1[1] = siluf_(a1[1]); a1[2] = siluf_(a1[2]); a1[3] = siluf_(a1[3]); }
;                         else if (seg == 2) { a0[0] = gelu_tanh_(a0[0]); a0[1] = gelu_tanh_(a0[1]); a0[2] = gelu_tanh_(a0[2]); a0[3] = gelu_tanh_(a0[3]); a1[0] = gelu_tanh_(a1[0]); a1[1] = gelu_tanh_(a1[1]); a1[2] = gelu_tanh_(a1[2]); a1[3] = gelu_tanh_(a1[3]); }
;                         else if (seg >= 3) { a0[0] = sigmoidf_(a0[0]); a0[1] = sigmoidf_(a0[1]); a0[2] = sigmoidf_(a0[2]); a0[3] = sigmoidf_(a0[3]); a1[0] = sigmoidf_(a1[0]); a1[1] = sigmoidf_(a1[1]); a1[2] = sigmoidf_(a1[2]); a1[3] = sigmoidf_(a1[3]); }
;                         u32x4 o; o[0] = pk2(a0[0], a0[1]); o[1] = pk2(a0[2], a0[3]); o[2] = pk2(a1[0], a1[1]); o[3] = pk2(a1[2], a1[3]);
;                         *(u32x4*)(base + row * D + cbase + bj * 128) = o;
;                     }
;                 }
	v_pk_add_f32 v[134:135], v[134:135], v[134:135]
	v_pk_add_f32 v[136:137], v[136:137], v[136:137]
	v_pk_mul_f32 v[130:131], v[130:131], s[8:9] op_sel_hi:[1,0]
	v_pk_mul_f32 v[132:133], v[132:133], s[8:9] op_sel_hi:[1,0]
	v_pk_mul_f32 v[134:135], v[134:135], s[8:9] op_sel_hi:[1,0]
	v_pk_mul_f32 v[136:137], v[136:137], s[8:9] op_sel_hi:[1,0]
	v_exp_f32_e32 v130, v130
	v_exp_f32_e32 v131, v131
	v_exp_f32_e32 v132, v132
	v_exp_f32_e32 v133, v133
	v_exp_f32_e32 v134, v134
	v_exp_f32_e32 v135, v135
	v_exp_f32_e32 v136, v136
	v_exp_f32_e32 v137, v137
	v_pk_add_f32 v[130:131], v[130:131], s[10:11] op_sel_hi:[1,0]
	v_pk_add_f32 v[132:133], v[132:133], s[10:11] op_sel_hi:[1,0]
	v_pk_add_f32 v[134:135], v[134:135], s[10:11] op_sel_hi:[1,0]
	v_pk_add_f32 v[136:137], v[136:137], s[10:11] op_sel_hi:[1,0]
	v_rcp_f32_e32 v130, v130
	v_rcp_f32_e32 v131, v131
	v_rcp_f32_e32 v132, v132
	v_rcp_f32_e32 v133, v133
	v_rcp_f32_e32 v134, v134
	v_rcp_f32_e32 v135, v135
	v_rcp_f32_e32 v136, v136
	v_rcp_f32_e32 v137, v137
	v_pk_mul_f32 v[130:131], v[26:27], v[130:131]
	v_pk_mul_f32 v[132:133], v[28:29], v[132:133]
	v_pk_mul_f32 v[134:135], v[30:31], v[134:135]
	v_pk_mul_f32 v[136:137], v[32:33], v[136:137]
	v_cvt_pk_bf16_f32 v26, v130, v131
	v_cvt_pk_bf16_f32 v27, v132, v133
	v_cvt_pk_bf16_f32 v28, v134, v135
	v_cvt_pk_bf16_f32 v29, v136, v137
	global_store_dwordx4 v153, v[26:29], s[98:99]
	v_pk_mul_f32 v[130:131], v[18:19], s[12:13] op_sel_hi:[1,0]
	v_pk_mul_f32 v[132:133], v[20:21], s[12:13] op_sel_hi:[1,0]
	v_pk_mul_f32 v[134:135], v[22:23], s[12:13] op_sel_hi:[1,0]
	v_pk_mul_f32 v[136:137], v[24:25], s[12:13] op_sel_hi:[1,0]
	v_pk_mul_f32 v[130:131], v[18:19], v[130:131]
	v_pk_mul_f32 v[132:133], v[20:21], v[132:133]
	v_pk_mul_f32 v[134:135], v[22:23], v[134:135]
	v_pk_mul_f32 v[136:137], v[24:25], v[136:137]
	v_pk_fma_f32 v[130:131], v[18:19], v[130:131], v[18:19]
	v_pk_fma_f32 v[132:133], v[20:21], v[132:133], v[20:21]
	v_pk_fma_f32 v[134:135], v[22:23], v[134:135], v[22:23]
	v_pk_fma_f32 v[136:137], v[24:25], v[136:137], v[24:25]
	v_pk_mul_f32 v[130:131], v[130:131], s[100:101] op_sel_hi:[1,0]
	v_pk_mul_f32 v[132:133], v[132:133], s[100:101] op_sel_hi:[1,0]
	v_pk_mul_f32 v[134:135], v[134:135], s[100:101] op_sel_hi:[1,0]
	v_pk_mul_f32 v[136:137], v[136:137], s[100:101] op_sel_hi:[1,0]
	v_pk_add_f32 v[130:131], v[130:131], v[130:131]
	v_pk_add_f32 v[132:133], v[132:133], v[132:133]
	v_pk_add_f32 v[134:135], v[134:135], v[134:135]
	v_pk_add_f32 v[136:137], v[136:137], v[136:137]
	v_pk_mul_f32 v[130:131], v[130:131], s[8:9] op_sel_hi:[1,0]
	v_pk_mul_f32 v[132:133], v[132:133], s[8:9] op_sel_hi:[1,0]
	v_pk_mul_f32 v[134:135], v[134:135], s[8:9] op_sel_hi:[1,0]
	v_pk_mul_f32 v[136:137], v[136:137], s[8:9] op_sel_hi:[1,0]
	v_exp_f32_e32 v130, v130
	v_exp_f32_e32 v131, v131
	v_exp_f32_e32 v132, v132
	v_exp_f32_e32 v133, v133
	v_exp_f32_e32 v134, v134
	v_exp_f32_e32 v135, v135
	v_exp_f32_e32 v136, v136
	v_exp_f32_e32 v137, v137
	v_pk_add_f32 v[130:131], v[130:131], s[10:11] op_sel_hi:[1,0]
	v_pk_add_f32 v[132:133], v[132:133], s[10:11] op_sel_hi:[1,0]
	v_pk_add_f32 v[134:135], v[134:135], s[10:11] op_sel_hi:[1,0]
	v_pk_add_f32 v[136:137], v[136:137], s[10:11] op_sel_hi:[1,0]
	v_rcp_f32_e32 v130, v130
	v_rcp_f32_e32 v131, v131
	v_rcp_f32_e32 v132, v132
	v_rcp_f32_e32 v133, v133
	v_rcp_f32_e32 v134, v134
	v_rcp_f32_e32 v135, v135
	v_rcp_f32_e32 v136, v136
	v_rcp_f32_e32 v137, v137
	v_pk_mul_f32 v[130:131], v[18:19], v[130:131]
	v_pk_mul_f32 v[132:133], v[20:21], v[132:133]
	v_pk_mul_f32 v[134:135], v[22:23], v[134:135]
	v_pk_mul_f32 v[136:137], v[24:25], v[136:137]
	v_cvt_pk_bf16_f32 v18, v130, v131
	v_cvt_pk_bf16_f32 v19, v132, v133
	v_cvt_pk_bf16_f32 v20, v134, v135
	v_cvt_pk_bf16_f32 v21, v136, v137
	global_store_dwordx4 v153, v[18:21], s[98:99] offset:256
	s_add_u32 s98, s78, 0x58000
	s_addc_u32 s99, s79, 0
	v_pk_mul_f32 v[130:131], v[10:11], s[12:13] op_sel_hi:[1,0]
	v_pk_mul_f32 v[132:133], v[12:13], s[12:13] op_sel_hi:[1,0]
	v_pk_mul_f32 v[134:135], v[14:15], s[12:13] op_sel_hi:[1,0]
	v_pk_mul_f32 v[136:137], v[16:17], s[12:13] op_sel_hi:[1,0]
	v_pk_mul_f32 v[130:131], v[10:11], v[130:131]
	v_pk_mul_f32 v[132:133], v[12:13], v[132:133]
	v_pk_mul_f32 v[134:135], v[14:15], v[134:135]
	v_pk_mul_f32 v[136:137], v[16:17], v[136:137]
	v_pk_fma_f32 v[130:131], v[10:11], v[130:131], v[10:11]
; __device__ __forceinline__ unsigned pk2(float lo, float hi) { const f32x2_t v = {lo, hi}; const bf16v2_t b = __builtin_convertvector(v, bf16v2_t); return __builtin_bit_cast(unsigned, b); }
; __device__ __forceinline__ float sigmoidf_(float x) { return frcp(1.f + __expf(-x)); }
; __device__ __forceinline__ float siluf_(float x) { return x * sigmoidf_(x); }
; __device__ __forceinline__ float gelu_tanh_(float x) { const float y = 0.7978845608028654f * (x + 0.044715f * x * x * x); return x * sigmoidf_(2.f * y); }
;     __device__ __forceinline__ void operator()(const AccT& acc, const pg8::Unit& u, int wr, int wc, int fr_, int fq_) const {
;     ...
;             const int seg = (pn - 8) >> 2;
;             bf16_t* base = (bf16_t*)(ws + WS_SG + (size_t)seg * ((size_t)MROWS * D * 2));
;             const int cbase = 256 * ((pn - 8) & 3) + wc * 32 + 8 * fq;
; #pragma unroll
;             for (int ai = 0; ai < 2; ++ai)
; #pragma unroll
;                 for (int m = 0; m < 4; ++m) {
;                     const size_t row = (size_t)u.pm * 256 + rl0 + ai * 128 + m * 16;
; #pragma unroll
;                     for (int bj = 0; bj < 2; ++bj) {
;                         f32x4 a0 = acc[ai][bj][m][0], a1 = acc[ai][bj][m][1];
;                         if (seg == 0) { a0[0] = siluf_(a0[0]); a0[1] = siluf_(a0[1]); a0[2] = siluf_(a0[2]); a0[3] = siluf_(a0[3]); a1[0] = siluf_(a1[0]); a1[1] = siluf_(a1[1]); a1[2] = siluf_(a1[2]); a1[3] = siluf_(a1[3]); }
;                         else if (seg == 2) { a0[0] = gelu_tanh_(a0[0]); a0[1] = gelu_tanh_(a0[1]); a0[2] = gelu_tanh_(a0[2]); a0[3] = gelu_tanh_(a0[3]); a1[0] = gelu_tanh_(a1[0]); a1[1] = gelu_tanh_(a1[1]); a1[2] = gelu_tanh_(a1[2]); a1[3] = gelu_tanh_(a1[3]); }
;                         else if (seg >= 3) { a0[0] = sigmoidf_(a0[0]); a0[1] = sigmoidf_(a0[1]); a0[2] = sigmoidf_(a0[2]); a0[3] = sigmoidf_(a0[3]); a1[0] = sigmoidf_(a1[0]); a1[1] = sigmoidf_(a1[1]); a1[2] = sigmoidf_(a1[2]); a1[3] = sigmoidf_(a1[3]); }
;                         u32x4 o; o[0] = pk2(a0[0], a0[1]); o[1] = pk2(a0[2], a0[3]); o[2] = pk2(a1[0], a1[1]); o[3] = pk2(a1[2], a1[3]);
;                         *(u32x4*)(base + row * D + cbase + bj * 128) = o;
;                     }
;                 }
	v_pk_fma_f32 v[132:133], v[12:13], v[132:133], v[12:13]
	v_pk_fma_f32 v[134:135], v[14:15], v[134:135], v[14:15]
	v_pk_fma_f32 v[136:137], v[16:17], v[136:137], v[16:17]
	v_pk_mul_f32 v[130:131], v[130:131], s[100:101] op_sel_hi:[1,0]
	v_pk_mul_f32 v[132:133], v[132:133], s[100:101] op_sel_hi:[1,0]
	v_pk_mul_f32 v[134:135], v[134:135], s[100:101] op_sel_hi:[1,0]
	v_pk_mul_f32 v[136:137], v[136:137], s[100:101] op_sel_hi:[1,0]
	v_pk_add_f32 v[130:131], v[130:131], v[130:131]
	v_pk_add_f32 v[132:133], v[132:133], v[132:133]
	v_pk_add_f32 v[134:135], v[134:135], v[134:135]
	v_pk_add_f32 v[136:137], v[136:137], v[136:137]
	v_pk_mul_f32 v[130:131], v[130:131], s[8:9] op_sel_hi:[1,0]
	v_pk_mul_f32 v[132:133], v[132:133], s[8:9] op_sel_hi:[1,0]
	v_pk_mul_f32 v[134:135], v[134:135], s[8:9] op_sel_hi:[1,0]
	v_pk_mul_f32 v[136:137], v[136:137], s[8:9] op_sel_hi:[1,0]
	v_exp_f32_e32 v130, v130
	v_exp_f32_e32 v131, v131
	v_exp_f32_e32 v132, v132
	v_exp_f32_e32 v133, v133
	v_exp_f32_e32 v134, v134
	v_exp_f32_e32 v135, v135
	v_exp_f32_e32 v136, v136
	v_exp_f32_e32 v137, v137
	v_pk_add_f32 v[130:131], v[130:131], s[10:11] op_sel_hi:[1,0]
	v_pk_add_f32 v[132:133], v[132:133], s[10:11] op_sel_hi:[1,0]
	v_pk_add_f32 v[134:135], v[134:135], s[10:11] op_sel_hi:[1,0]
	v_pk_add_f32 v[136:137], v[136:137], s[10:11] op_sel_hi:[1,0]
	v_rcp_f32_e32 v130, v130
	v_rcp_f32_e32 v131, v131
	v_rcp_f32_e32 v132, v132
	v_rcp_f32_e32 v133, v133
	v_rcp_f32_e32 v134, v134
	v_rcp_f32_e32 v135, v135
	v_rcp_f32_e32 v136, v136
	v_rcp_f32_e32 v137, v137
	v_pk_mul_f32 v[130:131], v[10:11], v[130:131]
	v_pk_mul_f32 v[132:133], v[12:13], v[132:133]
	v_pk_mul_f32 v[134:135], v[14:15], v[134:135]
	v_pk_mul_f32 v[136:137], v[16:17], v[136:137]
	v_cvt_pk_bf16_f32 v10, v130, v131
	v_cvt_pk_bf16_f32 v11, v132, v133
	v_cvt_pk_bf16_f32 v12, v134, v135
	v_cvt_pk_bf16_f32 v13, v136, v137
	global_store_dwordx4 v153, v[10:13], s[98:99]
	v_pk_mul_f32 v[130:131], v[6:7], s[12:13] op_sel_hi:[1,0]
	v_pk_mul_f32 v[132:133], v[8:9], s[12:13] op_sel_hi:[1,0]
	v_pk_mul_f32 v[134:135], v[2:3], s[12:13] op_sel_hi:[1,0]
	v_pk_mul_f32 v[136:137], v[4:5], s[12:13] op_sel_hi:[1,0]
	v_pk_mul_f32 v[130:131], v[6:7], v[130:131]
	v_pk_mul_f32 v[132:133], v[8:9], v[132:133]
	v_pk_mul_f32 v[134:135], v[2:3], v[134:135]
	v_pk_mul_f32 v[136:137], v[4:5], v[136:137]
	v_pk_fma_f32 v[130:131], v[6:7], v[130:131], v[6:7]
	v_pk_fma_f32 v[132:133], v[8:9], v[132:133], v[8:9]
	v_pk_fma_f32 v[134:135], v[2:3], v[134:135], v[2:3]
	v_pk_fma_f32 v[136:137], v[4:5], v[136:137], v[4:5]
	v_pk_mul_f32 v[130:131], v[130:131], s[100:101] op_sel_hi:[1,0]
	v_pk_mul_f32 v[132:133], v[132:133], s[100:101] op_sel_hi:[1,0]
	v_pk_mul_f32 v[134:135], v[134:135], s[100:101] op_sel_hi:[1,0]
	v_pk_mul_f32 v[136:137], v[136:137], s[100:101] op_sel_hi:[1,0]
	v_pk_add_f32 v[130:131], v[130:131], v[130:131]
	v_pk_add_f32 v[132:133], v[132:133], v[132:133]
	v_pk_add_f32 v[134:135], v[134:135], v[134:135]
	v_pk_add_f32 v[136:137], v[136:137], v[136:137]
	v_pk_mul_f32 v[130:131], v[130:131], s[8:9] op_sel_hi:[1,0]
	v_pk_mul_f32 v[132:133], v[132:133], s[8:9] op_sel_hi:[1,0]
	v_pk_mul_f32 v[134:135], v[134:135], s[8:9] op_sel_hi:[1,0]
	v_pk_mul_f32 v[136:137], v[136:137], s[8:9] op_sel_hi:[1,0]
	v_exp_f32_e32 v130, v130
	v_exp_f32_e32 v131, v131
	v_exp_f32_e32 v132, v132
	v_exp_f32_e32 v133, v133
	v_exp_f32_e32 v134, v134
	v_exp_f32_e32 v135, v135
	v_exp_f32_e32 v136, v136
	v_exp_f32_e32 v137, v137
	v_pk_add_f32 v[130:131], v[130:131], s[10:11] op_sel_hi:[1,0]
	v_pk_add_f32 v[132:133], v[132:133], s[10:11] op_sel_hi:[1,0]
	v_pk_add_f32 v[134:135], v[134:135], s[10:11] op_sel_hi:[1,0]
	v_pk_add_f32 v[136:137], v[136:137], s[10:11] op_sel_hi:[1,0]
	v_rcp_f32_e32 v130, v130
	v_rcp_f32_e32 v131, v131
	v_rcp_f32_e32 v132, v132
	v_rcp_f32_e32 v133, v133
	v_rcp_f32_e32 v134, v134
	v_rcp_f32_e32 v135, v135
	v_rcp_f32_e32 v136, v136
	v_rcp_f32_e32 v137, v137
	v_pk_mul_f32 v[130:131], v[6:7], v[130:131]
	v_pk_mul_f32 v[132:133], v[8:9], v[132:133]
	v_pk_mul_f32 v[134:135], v[2:3], v[134:135]
	v_pk_mul_f32 v[136:137], v[4:5], v[136:137]
	v_cvt_pk_bf16_f32 v6, v130, v131
	v_cvt_pk_bf16_f32 v7, v132, v133
	v_cvt_pk_bf16_f32 v8, v134, v135
	v_cvt_pk_bf16_f32 v9, v136, v137
	global_store_dwordx4 v153, v[6:9], s[98:99] offset:256
	s_mov_b32 s32, 1
	s_branch .LBB0_264

; __device__ __forceinline__ unsigned pk2(float lo, float hi) { const f32x2_t v = {lo, hi}; const bf16v2_t b = __builtin_convertvector(v, bf16v2_t); return __builtin_bit_cast(unsigned, b); }
;     __device__ __forceinline__ void operator()(const AccT& acc, const pg8::Unit& u, int wr, int wc, int fr_, int fq_) const {
;     ...
;         } else if (pn < 8) {
; #pragma unroll
;             for (int ai = 0; ai < 2; ++ai)
; #pragma unroll
;                 for (int m = 0; m < 4; ++m) {
;                     const int rl = rl0 + ai * 128 + m * 16;
; #pragma unroll
;                     for (int bj = 0; bj < 2; ++bj) {
;                         const int hv = 2 * (pn - 4) + bj;
; #pragma unroll
;                         for (int n = 0; n < 2; ++n) {
;                             const int dv = 32 * wc + 16 * n + 4 * fq;
;                             bf16_t* vt = VT + ((size_t)(b * NH + hv) * DV + dv) * TB + pt * 256 + rl;
;                             const f32x4 a = acc[ai][bj][m][n];
;                             const unsigned p0 = pk2(a[0], a[1]), p1 = pk2(a[2], a[3]);
;                             vt[0] = (bf16_t)(p0 & 0xffffu); vt[(size_t)TB] = (bf16_t)(p0 >> 16); vt[(size_t)2 * TB] = (bf16_t)(p1 & 0xffffu); vt[(size_t)3 * TB] = (bf16_t)(p1 >> 16);
;                         }
;                         __builtin_amdgcn_sched_barrier(0);
;                     }
;                 }
.LBB0_263:
	s_mov_b32 s32, 3
	s_cbranch_execz .LBB0_266

; __device__ __forceinline__ unsigned pk2(float lo, float hi) { const f32x2_t v = {lo, hi}; const bf16v2_t b = __builtin_convertvector(v, bf16v2_t); return __builtin_bit_cast(unsigned, b); }
;     __device__ __forceinline__ void operator()(const AccT& acc, const pg8::Unit& u, int wr, int wc, int fr_, int fq_) const {
;     ...
;         if (pn < 4) {
;             const bool isk = pn >= 2;
;             const int jj0 = 16 * (wc & 1) + 4 * fq;
; #pragma unroll
;             for (int ai = 0; ai < 2; ++ai)
; #pragma unroll
;                 for (int m = 0; m < 4; ++m) {
;                     const int rl = rl0 + ai * 128 + m * 16;
;                     const size_t row = (size_t)u.pm * 256 + rl;
;                     f32x4 cs = (f32x4){1.f, 1.f, 1.f, 1.f}, sn = (f32x4){0.f, 0.f, 0.f, 0.f};
;                     if (pt != 0) { const int tpos = (pt - 1) * 256 + rl; cs = *(const f32x4*)(rope + (size_t)tpos * 32 + jj0); sn = *(const f32x4*)(rope + (size_t)SEQ * 32 + (size_t)tpos * 32 + jj0); }
; #pragma unroll
;                     for (int bj = 0; bj < 2; ++bj) {
;                         const int hq = 4 * (pn & 1) + 2 * bj + (wc >> 1);
;                         const f32x4 a1 = acc[ai][bj][m][0], a2 = acc[ai][bj][m][1];
;                         f32x4 o1 = a1 * cs - a2 * sn, o2 = a1 * sn + a2 * cs;
;                         if (isk) { o1 *= 0.125f; o2 *= 0.125f; }
;                         u32x2 p1, p2; p1.x = pk2(o1[0], o1[1]); p1.y = pk2(o1[2], o1[3]); p2.x = pk2(o2[0], o2[1]); p2.y = pk2(o2[2], o2[3]);
;                         bf16_t* dst = (isk ? KN : Q) + row * 512 + hq * 64 + jj0;
;                         *(u32x2*)dst = p1; *(u32x2*)(dst + 32) = p2;
.Lqk_go:
	s_and_b32 s2, s52, 1
	s_lshl_b32 s2, s2, 2
	s_or_b32 s15, s15, s2
	s_cmp_gt_i32 s52, 1
	s_mov_b32 s2, 0xb4c8000
	s_cselect_b32 s2, s2, 0xa2c8000
	s_add_u32 s78, s30, s2
	s_addc_u32 s79, s31, 0
	s_lshl_b32 s2, s14, 18
	s_add_u32 s78, s78, s2
	s_addc_u32 s79, s79, 0
	s_lshl_b32 s2, s15, 7
	s_add_u32 s78, s78, s2
	s_addc_u32 s79, s79, 0
	s_cmp_gt_i32 s52, 1
	s_cbranch_scc1 .Lqk_k
	s_waitcnt vmcnt(0)
	v_pk_mul_f32 v[152:153], v[126:127], v[194:195]
	v_pk_mul_f32 v[154:155], v[128:129], v[196:197]
	v_pk_mul_f32 v[126:127], v[126:127], v[190:191]
	v_pk_mul_f32 v[128:129], v[128:129], v[192:193]
	v_pk_fma_f32 v[152:153], v[122:123], v[190:191], v[152:153] neg_lo:[0,0,1] neg_hi:[0,0,1]
	v_pk_fma_f32 v[154:155], v[124:125], v[192:193], v[154:155] neg_lo:[0,0,1] neg_hi:[0,0,1]
	v_pk_fma_f32 v[126:127], v[122:123], v[194:195], v[126:127]
	v_pk_fma_f32 v[128:129], v[124:125], v[196:197], v[128:129]
	v_cvt_pk_bf16_f32 v122, v152, v153
	v_cvt_pk_bf16_f32 v123, v154, v155
	v_cvt_pk_bf16_f32 v124, v126, v127
	v_cvt_pk_bf16_f32 v125, v128, v129
	global_store_dwordx2 v189, v[122:123], s[78:79]
	global_store_dwordx2 v189, v[124:125], s[78:79] offset:64
	v_pk_mul_f32 v[156:157], v[110:111], v[202:203]
	v_pk_mul_f32 v[168:169], v[112:113], v[204:205]
	v_pk_mul_f32 v[110:111], v[110:111], v[198:199]
	v_pk_mul_f32 v[112:113], v[112:113], v[200:201]
	v_pk_fma_f32 v[156:157], v[106:107], v[198:199], v[156:157] neg_lo:[0,0,1] neg_hi:[0,0,1]
	v_pk_fma_f32 v[168:169], v[108:109], v[200:201], v[168:169] neg_lo:[0,0,1] neg_hi:[0,0,1]
	v_pk_fma_f32 v[110:111], v[106:107], v[202:203], v[110:111]
	v_pk_fma_f32 v[112:113], v[108:109], v[204:205], v[112:113]
	v_cvt_pk_bf16_f32 v106, v156, v157
	v_cvt_pk_bf16_f32 v107, v168, v169
	v_cvt_pk_bf16_f32 v108, v110, v111
	v_cvt_pk_bf16_f32 v109, v112, v113
	v_add_u32_e32 v239, 0x4000, v189
	global_store_dwordx2 v239, v[106:107], s[78:79]
	global_store_dwordx2 v239, v[108:109], s[78:79] offset:64
	v_pk_mul_f32 v[152:153], v[94:95], v[210:211]
	v_pk_mul_f32 v[154:155], v[96:97], v[212:213]
	v_pk_mul_f32 v[94:95], v[94:95], v[206:207]
	v_pk_mul_f32 v[96:97], v[96:97], v[208:209]
	v_pk_fma_f32 v[152:153], v[90:91], v[206:207], v[152:153] neg_lo:[0,0,1] neg_hi:[0,0,1]
	v_pk_fma_f32 v[154:155], v[92:93], v[208:209], v[154:155] neg_lo:[0,0,1] neg_hi:[0,0,1]
	v_pk_fma_f32 v[94:95], v[90:91], v[210:211], v[94:95]
	v_pk_fma_f32 v[96:97], v[92:93], v[212:213], v[96:97]
	v_cvt_pk_bf16_f32 v90, v152, v153
	v_cvt_pk_bf16_f32 v91, v154, v155
	v_cvt_pk_bf16_f32 v92, v94, v95
	v_cvt_pk_bf16_f32 v93, v96, v97
	v_add_u32_e32 v239, 0x8000, v189
	global_store_dwordx2 v239, v[90:91], s[78:79]
	global_store_dwordx2 v239, v[92:93], s[78:79] offset:64
	v_pk_mul_f32 v[156:157], v[78:79], v[218:219]
	v_pk_mul_f32 v[168:169], v[80:81], v[220:221]
	v_pk_mul_f32 v[78:79], v[78:79], v[214:215]
	v_pk_mul_f32 v[80:81], v[80:81], v[216:217]
	v_pk_fma_f32 v[156:157], v[74:75], v[214:215], v[156:157] neg_lo:[0,0,1] neg_hi:[0,0,1]
	v_pk_fma_f32 v[168:169], v[76:77], v[216:217], v[168:169] neg_lo:[0,0,1] neg_hi:[0,0,1]
	v_pk_fma_f32 v[78:79], v[74:75], v[218:219], v[78:79]
	v_pk_fma_f32 v[80:81], v[76:77], v[220:221], v[80:81]
	v_cvt_pk_bf16_f32 v74, v156, v157
	v_cvt_pk_bf16_f32 v75, v168, v169
	v_cvt_pk_bf16_f32 v76, v78, v79
	v_cvt_pk_bf16_f32 v77, v80, v81
	v_add_u32_e32 v239, 0xc000, v189
	global_store_dwordx2 v239, v[74:75], s[78:79]
	global_store_dwordx2 v239, v[76:77], s[78:79] offset:64
	v_pk_mul_f32 v[152:153], v[62:63], v[226:227]
	v_pk_mul_f32 v[154:155], v[64:65], v[228:229]
	v_pk_mul_f32 v[62:63], v[62:63], v[222:223]
	v_pk_mul_f32 v[64:65], v[64:65], v[224:225]
	v_pk_fma_f32 v[152:153], v[58:59], v[222:223], v[152:153] neg_lo:[0,0,1] neg_hi:[0,0,1]
	v_pk_fma_f32 v[154:155], v[60:61], v[224:225], v[154:155] neg_lo:[0,0,1] neg_hi:[0,0,1]
	v_pk_fma_f32 v[62:63], v[58:59], v[226:227], v[62:63]
	v_pk_fma_f32 v[64:65], v[60:61], v[228:229], v[64:65]
	v_cvt_pk_bf16_f32 v58, v152, v153
	v_cvt_pk_bf16_f32 v59, v154, v155
	v_cvt_pk_bf16_f32 v60, v62, v63
	v_cvt_pk_bf16_f32 v61, v64, v65
	v_add_u32_e32 v239, 0x20000, v189
	global_store_dwordx2 v239, v[58:59], s[78:79]
	global_store_dwordx2 v239, v[60:61], s[78:79] offset:64
	v_pk_mul_f32 v[156:157], v[46:47], v[234:235]
	v_pk_mul_f32 v[168:169], v[48:49], v[236:237]
	v_pk_mul_f32 v[46:47], v[46:47], v[230:231]
	v_pk_mul_f32 v[48:49], v[48:49], v[232:233]
	v_pk_fma_f32 v[156:157], v[42:43], v[230:231], v[156:157] neg_lo:[0,0,1] neg_hi:[0,0,1]
	v_pk_fma_f32 v[168:169], v[44:45], v[232:233], v[168:169] neg_lo:[0,0,1] neg_hi:[0,0,1]
	v_pk_fma_f32 v[46:47], v[42:43], v[234:235], v[46:47]
	v_pk_fma_f32 v[48:49], v[44:45], v[236:237], v[48:49]
	v_cvt_pk_bf16_f32 v42, v156, v157
	v_cvt_pk_bf16_f32 v43, v168, v169
	v_cvt_pk_bf16_f32 v44, v46, v47
	v_cvt_pk_bf16_f32 v45, v48, v49
	v_add_u32_e32 v239, 0x24000, v189
	global_store_dwordx2 v239, v[42:43], s[78:79]
	global_store_dwordx2 v239, v[44:45], s[78:79] offset:64
	v_pk_mul_f32 v[152:153], v[30:31], v[134:135]
	v_pk_mul_f32 v[154:155], v[32:33], v[136:137]
	v_pk_mul_f32 v[30:31], v[30:31], v[130:131]
	v_pk_mul_f32 v[32:33], v[32:33], v[132:133]
	v_pk_fma_f32 v[152:153], v[26:27], v[130:131], v[152:153] neg_lo:[0,0,1] neg_hi:[0,0,1]
	v_pk_fma_f32 v[154:155], v[28:29], v[132:133], v[154:155] neg_lo:[0,0,1] neg_hi:[0,0,1]
	v_pk_fma_f32 v[30:31], v[26:27], v[134:135], v[30:31]
	v_pk_fma_f32 v[32:33], v[28:29], v[136:137], v[32:33]
	v_cvt_pk_bf16_f32 v26, v152, v153
	v_cvt_pk_bf16_f32 v27, v154, v155
	v_cvt_pk_bf16_f32 v28, v30, v31
	v_cvt_pk_bf16_f32 v29, v32, v33
	v_add_u32_e32 v239, 0x28000, v189
	global_store_dwordx2 v239, v[26:27], s[78:79]
; __device__ __forceinline__ unsigned pk2(float lo, float hi) { const f32x2_t v = {lo, hi}; const bf16v2_t b = __builtin_convertvector(v, bf16v2_t); return __builtin_bit_cast(unsigned, b); }
;     __device__ __forceinline__ void operator()(const AccT& acc, const pg8::Unit& u, int wr, int wc, int fr_, int fq_) const {
;     ...
;         if (pn < 4) {
;             const bool isk = pn >= 2;
;             const int jj0 = 16 * (wc & 1) + 4 * fq;
; #pragma unroll
;             for (int ai = 0; ai < 2; ++ai)
; #pragma unroll
;                 for (int m = 0; m < 4; ++m) {
;                     const int rl = rl0 + ai * 128 + m * 16;
;                     const size_t row = (size_t)u.pm * 256 + rl;
;                     f32x4 cs = (f32x4){1.f, 1.f, 1.f, 1.f}, sn = (f32x4){0.f, 0.f, 0.f, 0.f};
;                     if (pt != 0) { const int tpos = (pt - 1) * 256 + rl; cs = *(const f32x4*)(rope + (size_t)tpos * 32 + jj0); sn = *(const f32x4*)(rope + (size_t)SEQ * 32 + (size_t)tpos * 32 + jj0); }
; #pragma unroll
;                     for (int bj = 0; bj < 2; ++bj) {
;                         const int hq = 4 * (pn & 1) + 2 * bj + (wc >> 1);
;                         const f32x4 a1 = acc[ai][bj][m][0], a2 = acc[ai][bj][m][1];
;                         f32x4 o1 = a1 * cs - a2 * sn, o2 = a1 * sn + a2 * cs;
;                         if (isk) { o1 *= 0.125f; o2 *= 0.125f; }
;                         u32x2 p1, p2; p1.x = pk2(o1[0], o1[1]); p1.y = pk2(o1[2], o1[3]); p2.x = pk2(o2[0], o2[1]); p2.y = pk2(o2[2], o2[3]);
;                         bf16_t* dst = (isk ? KN : Q) + row * 512 + hq * 64 + jj0;
;                         *(u32x2*)dst = p1; *(u32x2*)(dst + 32) = p2;
	global_store_dwordx2 v239, v[28:29], s[78:79] offset:64
	v_pk_mul_f32 v[156:157], v[14:15], v[162:163]
	v_pk_mul_f32 v[168:169], v[16:17], v[164:165]
	v_pk_mul_f32 v[14:15], v[14:15], v[158:159]
	v_pk_mul_f32 v[16:17], v[16:17], v[160:161]
	v_pk_fma_f32 v[156:157], v[10:11], v[158:159], v[156:157] neg_lo:[0,0,1] neg_hi:[0,0,1]
	v_pk_fma_f32 v[168:169], v[12:13], v[160:161], v[168:169] neg_lo:[0,0,1] neg_hi:[0,0,1]
	v_pk_fma_f32 v[14:15], v[10:11], v[162:163], v[14:15]
	v_pk_fma_f32 v[16:17], v[12:13], v[164:165], v[16:17]
	v_cvt_pk_bf16_f32 v10, v156, v157
	v_cvt_pk_bf16_f32 v11, v168, v169
	v_cvt_pk_bf16_f32 v12, v14, v15
	v_cvt_pk_bf16_f32 v13, v16, v17
	v_add_u32_e32 v239, 0x2c000, v189
	global_store_dwordx2 v239, v[10:11], s[78:79]
	global_store_dwordx2 v239, v[12:13], s[78:79] offset:64
	v_pk_mul_f32 v[152:153], v[118:119], v[194:195]
	v_pk_mul_f32 v[154:155], v[120:121], v[196:197]
	v_pk_mul_f32 v[118:119], v[118:119], v[190:191]
	v_pk_mul_f32 v[120:121], v[120:121], v[192:193]
	v_pk_fma_f32 v[152:153], v[114:115], v[190:191], v[152:153] neg_lo:[0,0,1] neg_hi:[0,0,1]
	v_pk_fma_f32 v[154:155], v[116:117], v[192:193], v[154:155] neg_lo:[0,0,1] neg_hi:[0,0,1]
	v_pk_fma_f32 v[118:119], v[114:115], v[194:195], v[118:119]
	v_pk_fma_f32 v[120:121], v[116:117], v[196:197], v[120:121]
	v_cvt_pk_bf16_f32 v114, v152, v153
	v_cvt_pk_bf16_f32 v115, v154, v155
	v_cvt_pk_bf16_f32 v116, v118, v119
	v_cvt_pk_bf16_f32 v117, v120, v121
	global_store_dwordx2 v189, v[114:115], s[78:79] offset:256
	global_store_dwordx2 v189, v[116:117], s[78:79] offset:320
	v_pk_mul_f32 v[156:157], v[102:103], v[202:203]
	v_pk_mul_f32 v[168:169], v[104:105], v[204:205]
	v_pk_mul_f32 v[102:103], v[102:103], v[198:199]
	v_pk_mul_f32 v[104:105], v[104:105], v[200:201]
	v_pk_fma_f32 v[156:157], v[98:99], v[198:199], v[156:157] neg_lo:[0,0,1] neg_hi:[0,0,1]
	v_pk_fma_f32 v[168:169], v[100:101], v[200:201], v[168:169] neg_lo:[0,0,1] neg_hi:[0,0,1]
	v_pk_fma_f32 v[102:103], v[98:99], v[202:203], v[102:103]
	v_pk_fma_f32 v[104:105], v[100:101], v[204:205], v[104:105]
	v_cvt_pk_bf16_f32 v98, v156, v157
	v_cvt_pk_bf16_f32 v99, v168, v169
	v_cvt_pk_bf16_f32 v100, v102, v103
	v_cvt_pk_bf16_f32 v101, v104, v105
	v_add_u32_e32 v239, 0x4000, v189
	global_store_dwordx2 v239, v[98:99], s[78:79] offset:256
	global_store_dwordx2 v239, v[100:101], s[78:79] offset:320
	v_pk_mul_f32 v[152:153], v[86:87], v[210:211]
	v_pk_mul_f32 v[154:155], v[88:89], v[212:213]
	v_pk_mul_f32 v[86:87], v[86:87], v[206:207]
	v_pk_mul_f32 v[88:89], v[88:89], v[208:209]
	v_pk_fma_f32 v[152:153], v[82:83], v[206:207], v[152:153] neg_lo:[0,0,1] neg_hi:[0,0,1]
	v_pk_fma_f32 v[154:155], v[84:85], v[208:209], v[154:155] neg_lo:[0,0,1] neg_hi:[0,0,1]
	v_pk_fma_f32 v[86:87], v[82:83], v[210:211], v[86:87]
	v_pk_fma_f32 v[88:89], v[84:85], v[212:213], v[88:89]
	v_cvt_pk_bf16_f32 v82, v152, v153
	v_cvt_pk_bf16_f32 v83, v154, v155
	v_cvt_pk_bf16_f32 v84, v86, v87
	v_cvt_pk_bf16_f32 v85, v88, v89
	v_add_u32_e32 v239, 0x8000, v189
	global_store_dwordx2 v239, v[82:83], s[78:79] offset:256
	global_store_dwordx2 v239, v[84:85], s[78:79] offset:320
	v_pk_mul_f32 v[156:157], v[70:71], v[218:219]
	v_pk_mul_f32 v[168:169], v[72:73], v[220:221]
	v_pk_mul_f32 v[70:71], v[70:71], v[214:215]
	v_pk_mul_f32 v[72:73], v[72:73], v[216:217]
	v_pk_fma_f32 v[156:157], v[66:67], v[214:215], v[156:157] neg_lo:[0,0,1] neg_hi:[0,0,1]
	v_pk_fma_f32 v[168:169], v[68:69], v[216:217], v[168:169] neg_lo:[0,0,1] neg_hi:[0,0,1]
	v_pk_fma_f32 v[70:71], v[66:67], v[218:219], v[70:71]
	v_pk_fma_f32 v[72:73], v[68:69], v[220:221], v[72:73]
	v_cvt_pk_bf16_f32 v66, v156, v157
	v_cvt_pk_bf16_f32 v67, v168, v169
	v_cvt_pk_bf16_f32 v68, v70, v71
	v_cvt_pk_bf16_f32 v69, v72, v73
	v_add_u32_e32 v239, 0xc000, v189
	global_store_dwordx2 v239, v[66:67], s[78:79] offset:256
	global_store_dwordx2 v239, v[68:69], s[78:79] offset:320
	v_pk_mul_f32 v[152:153], v[54:55], v[226:227]
	v_pk_mul_f32 v[154:155], v[56:57], v[228:229]
	v_pk_mul_f32 v[54:55], v[54:55], v[222:223]
	v_pk_mul_f32 v[56:57], v[56:57], v[224:225]
	v_pk_fma_f32 v[152:153], v[50:51], v[222:223], v[152:153] neg_lo:[0,0,1] neg_hi:[0,0,1]
	v_pk_fma_f32 v[154:155], v[52:53], v[224:225], v[154:155] neg_lo:[0,0,1] neg_hi:[0,0,1]
	v_pk_fma_f32 v[54:55], v[50:51], v[226:227], v[54:55]
	v_pk_fma_f32 v[56:57], v[52:53], v[228:229], v[56:57]
	v_cvt_pk_bf16_f32 v50, v152, v153
	v_cvt_pk_bf16_f32 v51, v154, v155
	v_cvt_pk_bf16_f32 v52, v54, v55
	v_cvt_pk_bf16_f32 v53, v56, v57
	v_add_u32_e32 v239, 0x20000, v189
	global_store_dwordx2 v239, v[50:51], s[78:79] offset:256
	global_store_dwordx2 v239, v[52:53], s[78:79] offset:320
	v_pk_mul_f32 v[156:157], v[38:39], v[234:235]
	v_pk_mul_f32 v[168:169], v[40:41], v[236:237]
	v_pk_mul_f32 v[38:39], v[38:39], v[230:231]
	v_pk_mul_f32 v[40:41], v[40:41], v[232:233]
	v_pk_fma_f32 v[156:157], v[34:35], v[230:231], v[156:157] neg_lo:[0,0,1] neg_hi:[0,0,1]
	v_pk_fma_f32 v[168:169], v[36:37], v[232:233], v[168:169] neg_lo:[0,0,1] neg_hi:[0,0,1]
	v_pk_fma_f32 v[38:39], v[34:35], v[234:235], v[38:39]
	v_pk_fma_f32 v[40:41], v[36:37], v[236:237], v[40:41]
	v_cvt_pk_bf16_f32 v34, v156, v157
	v_cvt_pk_bf16_f32 v35, v168, v169
	v_cvt_pk_bf16_f32 v36, v38, v39
	v_cvt_pk_bf16_f32 v37, v40, v41
	v_add_u32_e32 v239, 0x24000, v189
	global_store_dwordx2 v239, v[34:35], s[78:79] offset:256
	global_store_dwordx2 v239, v[36:37], s[78:79] offset:320
	v_pk_mul_f32 v[152:153], v[22:23], v[134:135]
	v_pk_mul_f32 v[154:155], v[24:25], v[136:137]
	v_pk_mul_f32 v[22:23], v[22:23], v[130:131]
	v_pk_mul_f32 v[24:25], v[24:25], v[132:133]
	v_pk_fma_f32 v[152:153], v[18:19], v[130:131], v[152:153] neg_lo:[0,0,1] neg_hi:[0,0,1]
	v_pk_fma_f32 v[154:155], v[20:21], v[132:133], v[154:155] neg_lo:[0,0,1] neg_hi:[0,0,1]
	v_pk_fma_f32 v[22:23], v[18:19], v[134:135], v[22:23]
	v_pk_fma_f32 v[24:25], v[20:21], v[136:137], v[24:25]
	v_cvt_pk_bf16_f32 v18, v152, v153
	v_cvt_pk_bf16_f32 v19, v154, v155
	v_cvt_pk_bf16_f32 v20, v22, v23
	v_cvt_pk_bf16_f32 v21, v24, v25
	v_add_u32_e32 v239, 0x28000, v189
	global_store_dwordx2 v239, v[18:19], s[78:79] offset:256
	global_store_dwordx2 v239, v[20:21], s[78:79] offset:320
	v_pk_mul_f32 v[156:157], v[2:3], v[162:163]
	v_pk_mul_f32 v[168:169], v[4:5], v[164:165]
	v_pk_mul_f32 v[2:3], v[2:3], v[158:159]
	v_pk_mul_f32 v[4:5], v[4:5], v[160:161]
	v_pk_fma_f32 v[156:157], v[6:7], v[158:159], v[156:157] neg_lo:[0,0,1] neg_hi:[0,0,1]
	v_pk_fma_f32 v[168:169], v[8:9], v[160:161], v[168:169] neg_lo:[0,0,1] neg_hi:[0,0,1]
	v_pk_fma_f32 v[2:3], v[6:7], v[162:163], v[2:3]
	v_pk_fma_f32 v[4:5], v[8:9], v[164:165], v[4:5]
	v_cvt_pk_bf16_f32 v6, v156, v157
	v_cvt_pk_bf16_f32 v7, v168, v169
	v_cvt_pk_bf16_f32 v8, v2, v3
	v_cvt_pk_bf16_f32 v9, v4, v5
	v_add_u32_e32 v239, 0x2c000, v189
	global_store_dwordx2 v239, v[6:7], s[78:79] offset:256
	global_store_dwordx2 v239, v[8:9], s[78:79] offset:320
	s_mov_b32 s32, 2
	s_branch .LBB0_323
; __device__ __forceinline__ unsigned pk2(float lo, float hi) { const f32x2_t v = {lo, hi}; const bf16v2_t b = __builtin_convertvector(v, bf16v2_t); return __builtin_bit_cast(unsigned, b); }
;     __device__ __forceinline__ void operator()(const AccT& acc, const pg8::Unit& u, int wr, int wc, int fr_, int fq_) const {
;     ...
;         if (pn < 4) {
;             const bool isk = pn >= 2;
;             const int jj0 = 16 * (wc & 1) + 4 * fq;
; #pragma unroll
;             for (int ai = 0; ai < 2; ++ai)
; #pragma unroll
;                 for (int m = 0; m < 4; ++m) {
;                     const int rl = rl0 + ai * 128 + m * 16;
;                     const size_t row = (size_t)u.pm * 256 + rl;
;                     f32x4 cs = (f32x4){1.f, 1.f, 1.f, 1.f}, sn = (f32x4){0.f, 0.f, 0.f, 0.f};
;                     if (pt != 0) { const int tpos = (pt - 1) * 256 + rl; cs = *(const f32x4*)(rope + (size_t)tpos * 32 + jj0); sn = *(const f32x4*)(rope + (size_t)SEQ * 32 + (size_t)tpos * 32 + jj0); }
; #pragma unroll
;                     for (int bj = 0; bj < 2; ++bj) {
;                         const int hq = 4 * (pn & 1) + 2 * bj + (wc >> 1);
;                         const f32x4 a1 = acc[ai][bj][m][0], a2 = acc[ai][bj][m][1];
;                         f32x4 o1 = a1 * cs - a2 * sn, o2 = a1 * sn + a2 * cs;
;                         if (isk) { o1 *= 0.125f; o2 *= 0.125f; }
;                         u32x2 p1, p2; p1.x = pk2(o1[0], o1[1]); p1.y = pk2(o1[2], o1[3]); p2.x = pk2(o2[0], o2[1]); p2.y = pk2(o2[2], o2[3]);
;                         bf16_t* dst = (isk ? KN : Q) + row * 512 + hq * 64 + jj0;
;                         *(u32x2*)dst = p1; *(u32x2*)(dst + 32) = p2;
;                         if (isk) {
;                             bf16_t* kt = KT + ((size_t)(b * NH + hq) * DK + jj0) * TB + pt * 256 + rl;
;                             kt[0] = (bf16_t)(p1.x & 0xffffu); kt[(size_t)TB] = (bf16_t)(p1.x >> 16); kt[(size_t)2 * TB] = (bf16_t)(p1.y & 0xffffu); kt[(size_t)3 * TB] = (bf16_t)(p1.y >> 16);
;                             bf16_t* kt2 = kt + (size_t)32 * TB;
;                             kt2[0] = (bf16_t)(p2.x & 0xffffu); kt2[(size_t)TB] = (bf16_t)(p2.x >> 16); kt2[(size_t)2 * TB] = (bf16_t)(p2.y & 0xffffu); kt2[(size_t)3 * TB] = (bf16_t)(p2.y >> 16);
;                         }
.Lqk_k:
	s_lshl_b32 s2, s69, 3
	s_add_i32 s2, s2, s15
	s_mul_i32 s2, s2, 0x48000
	s_lshl_b32 s75, s71, 9
	s_add_i32 s2, s2, s75
	s_addk_i32 s2, 0x900
	s_add_u32 s4, s56, s2
	s_addc_u32 s5, s57, 0
	s_waitcnt vmcnt(0)
	s_add_u32 s8, s4, 0x2400
	s_addc_u32 s9, s5, 0
	s_add_u32 s10, s4, 0x24000
	s_addc_u32 s11, s5, 0
	s_add_u32 s12, s10, 0x2400
	s_addc_u32 s13, s11, 0
	v_pk_mul_f32 v[152:153], v[126:127], v[194:195]
	v_pk_mul_f32 v[154:155], v[128:129], v[196:197]
	v_pk_mul_f32 v[126:127], v[126:127], v[190:191]
	v_pk_mul_f32 v[128:129], v[128:129], v[192:193]
	v_pk_fma_f32 v[152:153], v[122:123], v[190:191], v[152:153] neg_lo:[0,0,1] neg_hi:[0,0,1]
	v_pk_fma_f32 v[154:155], v[124:125], v[192:193], v[154:155] neg_lo:[0,0,1] neg_hi:[0,0,1]
	v_pk_fma_f32 v[126:127], v[122:123], v[194:195], v[126:127]
	v_pk_fma_f32 v[128:129], v[124:125], v[196:197], v[128:129]
	v_pk_mul_f32 v[152:153], v[152:153], s[84:85] op_sel_hi:[1,0]
	v_pk_mul_f32 v[154:155], v[154:155], s[84:85] op_sel_hi:[1,0]
	v_pk_mul_f32 v[126:127], v[126:127], s[84:85] op_sel_hi:[1,0]
	v_pk_mul_f32 v[128:129], v[128:129], s[84:85] op_sel_hi:[1,0]
	v_cvt_pk_bf16_f32 v122, v152, v153
	v_cvt_pk_bf16_f32 v123, v154, v155
	v_cvt_pk_bf16_f32 v124, v126, v127
	v_cvt_pk_bf16_f32 v125, v128, v129
	global_store_dwordx2 v189, v[122:123], s[78:79]
	global_store_dwordx2 v189, v[124:125], s[78:79] offset:64
	global_store_short v238, v122, s[4:5] offset:-2304
	global_store_short_d16_hi v238, v122, s[4:5] offset:2304
	global_store_short v238, v123, s[8:9] offset:-2304
	global_store_short_d16_hi v238, v123, s[8:9] offset:2304
	global_store_short v238, v124, s[10:11] offset:-2304
	global_store_short_d16_hi v238, v124, s[10:11] offset:2304
	global_store_short v238, v125, s[12:13] offset:-2304
	global_store_short_d16_hi v238, v125, s[12:13] offset:2304
	v_pk_mul_f32 v[156:157], v[110:111], v[202:203]
	v_pk_mul_f32 v[168:169], v[112:113], v[204:205]
	v_pk_mul_f32 v[110:111], v[110:111], v[198:199]
	v_pk_mul_f32 v[112:113], v[112:113], v[200:201]
	v_pk_fma_f32 v[156:157], v[106:107], v[198:199], v[156:157] neg_lo:[0,0,1] neg_hi:[0,0,1]
	v_pk_fma_f32 v[168:169], v[108:109], v[200:201], v[168:169] neg_lo:[0,0,1] neg_hi:[0,0,1]
	v_pk_fma_f32 v[110:111], v[106:107], v[202:203], v[110:111]
	v_pk_fma_f32 v[112:113], v[108:109], v[204:205], v[112:113]
	v_pk_mul_f32 v[156:157], v[156:157], s[84:85] op_sel_hi:[1,0]
	v_pk_mul_f32 v[168:169], v[168:169], s[84:85] op_sel_hi:[1,0]
	v_pk_mul_f32 v[110:111], v[110:111], s[84:85] op_sel_hi:[1,0]
	v_pk_mul_f32 v[112:113], v[112:113], s[84:85] op_sel_hi:[1,0]
	v_cvt_pk_bf16_f32 v106, v156, v157
	v_cvt_pk_bf16_f32 v107, v168, v169
	v_cvt_pk_bf16_f32 v108, v110, v111
	v_cvt_pk_bf16_f32 v109, v112, v113
	v_add_u32_e32 v239, 0x4000, v189
	global_store_dwordx2 v239, v[106:107], s[78:79]
	global_store_dwordx2 v239, v[108:109], s[78:79] offset:64
	global_store_short v238, v106, s[4:5] offset:-2272
	global_store_short_d16_hi v238, v106, s[4:5] offset:2336
	global_store_short v238, v107, s[8:9] offset:-2272
	global_store_short_d16_hi v238, v107, s[8:9] offset:2336
	global_store_short v238, v108, s[10:11] offset:-2272
	global_store_short_d16_hi v238, v108, s[10:11] offset:2336
	global_store_short v238, v109, s[12:13] offset:-2272
	global_store_short_d16_hi v238, v109, s[12:13] offset:2336
	v_pk_mul_f32 v[152:153], v[94:95], v[210:211]
	v_pk_mul_f32 v[154:155], v[96:97], v[212:213]
	v_pk_mul_f32 v[94:95], v[94:95], v[206:207]
	v_pk_mul_f32 v[96:97], v[96:97], v[208:209]
	v_pk_fma_f32 v[152:153], v[90:91], v[206:207], v[152:153] neg_lo:[0,0,1] neg_hi:[0,0,1]
	v_pk_fma_f32 v[154:155], v[92:93], v[208:209], v[154:155] neg_lo:[0,0,1] neg_hi:[0,0,1]
	v_pk_fma_f32 v[94:95], v[90:91], v[210:211], v[94:95]
	v_pk_fma_f32 v[96:97], v[92:93], v[212:213], v[96:97]
	v_pk_mul_f32 v[152:153], v[152:153], s[84:85] op_sel_hi:[1,0]
	v_pk_mul_f32 v[154:155], v[154:155], s[84:85] op_sel_hi:[1,0]
	v_pk_mul_f32 v[94:95], v[94:95], s[84:85] op_sel_hi:[1,0]
	v_pk_mul_f32 v[96:97], v[96:97], s[84:85] op_sel_hi:[1,0]
	v_cvt_pk_bf16_f32 v90, v152, v153
	v_cvt_pk_bf16_f32 v91, v154, v155
	v_cvt_pk_bf16_f32 v92, v94, v95
	v_cvt_pk_bf16_f32 v93, v96, v97
	v_add_u32_e32 v239, 0x8000, v189
	global_store_dwordx2 v239, v[90:91], s[78:79]
	global_store_dwordx2 v239, v[92:93], s[78:79] offset:64
	global_store_short v238, v90, s[4:5] offset:-2240
	global_store_short_d16_hi v238, v90, s[4:5] offset:2368
	global_store_short v238, v91, s[8:9] offset:-2240
	global_store_short_d16_hi v238, v91, s[8:9] offset:2368
	global_store_short v238, v92, s[10:11] offset:-2240
	global_store_short_d16_hi v238, v92, s[10:11] offset:2368
	global_store_short v238, v93, s[12:13] offset:-2240
	global_store_short_d16_hi v238, v93, s[12:13] offset:2368
	v_pk_mul_f32 v[156:157], v[78:79], v[218:219]
	v_pk_mul_f32 v[168:169], v[80:81], v[220:221]
	v_pk_mul_f32 v[78:79], v[78:79], v[214:215]
	v_pk_mul_f32 v[80:81], v[80:81], v[216:217]
	v_pk_fma_f32 v[156:157], v[74:75], v[214:215], v[156:157] neg_lo:[0,0,1] neg_hi:[0,0,1]
	v_pk_fma_f32 v[168:169], v[76:77], v[216:217], v[168:169] neg_lo:[0,0,1] neg_hi:[0,0,1]
	v_pk_fma_f32 v[78:79], v[74:75], v[218:219], v[78:79]
	v_pk_fma_f32 v[80:81], v[76:77], v[220:221], v[80:81]
	v_pk_mul_f32 v[156:157], v[156:157], s[84:85] op_sel_hi:[1,0]
	v_pk_mul_f32 v[168:169], v[168:169], s[84:85] op_sel_hi:[1,0]
	v_pk_mul_f32 v[78:79], v[78:79], s[84:85] op_sel_hi:[1,0]
	v_pk_mul_f32 v[80:81], v[80:81], s[84:85] op_sel_hi:[1,0]
	v_cvt_pk_bf16_f32 v74, v156, v157
	v_cvt_pk_bf16_f32 v75, v168, v169
	v_cvt_pk_bf16_f32 v76, v78, v79
	v_cvt_pk_bf16_f32 v77, v80, v81
	v_add_u32_e32 v239, 0xc000, v189
; __device__ __forceinline__ unsigned pk2(float lo, float hi) { const f32x2_t v = {lo, hi}; const bf16v2_t b = __builtin_convertvector(v, bf16v2_t); return __builtin_bit_cast(unsigned, b); }
;     __device__ __forceinline__ void operator()(const AccT& acc, const pg8::Unit& u, int wr, int wc, int fr_, int fq_) const {
;     ...
;         if (pn < 4) {
;             const bool isk = pn >= 2;
;             const int jj0 = 16 * (wc & 1) + 4 * fq;
; #pragma unroll
;             for (int ai = 0; ai < 2; ++ai)
; #pragma unroll
;                 for (int m = 0; m < 4; ++m) {
;                     const int rl = rl0 + ai * 128 + m * 16;
;                     const size_t row = (size_t)u.pm * 256 + rl;
;                     f32x4 cs = (f32x4){1.f, 1.f, 1.f, 1.f}, sn = (f32x4){0.f, 0.f, 0.f, 0.f};
;                     if (pt != 0) { const int tpos = (pt - 1) * 256 + rl; cs = *(const f32x4*)(rope + (size_t)tpos * 32 + jj0); sn = *(const f32x4*)(rope + (size_t)SEQ * 32 + (size_t)tpos * 32 + jj0); }
; #pragma unroll
;                     for (int bj = 0; bj < 2; ++bj) {
;                         const int hq = 4 * (pn & 1) + 2 * bj + (wc >> 1);
;                         const f32x4 a1 = acc[ai][bj][m][0], a2 = acc[ai][bj][m][1];
;                         f32x4 o1 = a1 * cs - a2 * sn, o2 = a1 * sn + a2 * cs;
;                         if (isk) { o1 *= 0.125f; o2 *= 0.125f; }
;                         u32x2 p1, p2; p1.x = pk2(o1[0], o1[1]); p1.y = pk2(o1[2], o1[3]); p2.x = pk2(o2[0], o2[1]); p2.y = pk2(o2[2], o2[3]);
;                         bf16_t* dst = (isk ? KN : Q) + row * 512 + hq * 64 + jj0;
;                         *(u32x2*)dst = p1; *(u32x2*)(dst + 32) = p2;
;                         if (isk) {
;                             bf16_t* kt = KT + ((size_t)(b * NH + hq) * DK + jj0) * TB + pt * 256 + rl;
;                             kt[0] = (bf16_t)(p1.x & 0xffffu); kt[(size_t)TB] = (bf16_t)(p1.x >> 16); kt[(size_t)2 * TB] = (bf16_t)(p1.y & 0xffffu); kt[(size_t)3 * TB] = (bf16_t)(p1.y >> 16);
;                             bf16_t* kt2 = kt + (size_t)32 * TB;
;                             kt2[0] = (bf16_t)(p2.x & 0xffffu); kt2[(size_t)TB] = (bf16_t)(p2.x >> 16); kt2[(size_t)2 * TB] = (bf16_t)(p2.y & 0xffffu); kt2[(size_t)3 * TB] = (bf16_t)(p2.y >> 16);
;                         }
	global_store_dwordx2 v239, v[74:75], s[78:79]
	global_store_dwordx2 v239, v[76:77], s[78:79] offset:64
	global_store_short v238, v74, s[4:5] offset:-2208
	global_store_short_d16_hi v238, v74, s[4:5] offset:2400
	global_store_short v238, v75, s[8:9] offset:-2208
	global_store_short_d16_hi v238, v75, s[8:9] offset:2400
	global_store_short v238, v76, s[10:11] offset:-2208
	global_store_short_d16_hi v238, v76, s[10:11] offset:2400
	global_store_short v238, v77, s[12:13] offset:-2208
	global_store_short_d16_hi v238, v77, s[12:13] offset:2400
	v_pk_mul_f32 v[152:153], v[62:63], v[226:227]
	v_pk_mul_f32 v[154:155], v[64:65], v[228:229]
	v_pk_mul_f32 v[62:63], v[62:63], v[222:223]
	v_pk_mul_f32 v[64:65], v[64:65], v[224:225]
	v_pk_fma_f32 v[152:153], v[58:59], v[222:223], v[152:153] neg_lo:[0,0,1] neg_hi:[0,0,1]
	v_pk_fma_f32 v[154:155], v[60:61], v[224:225], v[154:155] neg_lo:[0,0,1] neg_hi:[0,0,1]
	v_pk_fma_f32 v[62:63], v[58:59], v[226:227], v[62:63]
	v_pk_fma_f32 v[64:65], v[60:61], v[228:229], v[64:65]
	v_pk_mul_f32 v[152:153], v[152:153], s[84:85] op_sel_hi:[1,0]
	v_pk_mul_f32 v[154:155], v[154:155], s[84:85] op_sel_hi:[1,0]
	v_pk_mul_f32 v[62:63], v[62:63], s[84:85] op_sel_hi:[1,0]
	v_pk_mul_f32 v[64:65], v[64:65], s[84:85] op_sel_hi:[1,0]
	v_cvt_pk_bf16_f32 v58, v152, v153
	v_cvt_pk_bf16_f32 v59, v154, v155
	v_cvt_pk_bf16_f32 v60, v62, v63
	v_cvt_pk_bf16_f32 v61, v64, v65
	v_add_u32_e32 v239, 0x20000, v189
	global_store_dwordx2 v239, v[58:59], s[78:79]
	global_store_dwordx2 v239, v[60:61], s[78:79] offset:64
	global_store_short v238, v58, s[4:5] offset:-2048
	global_store_short_d16_hi v238, v58, s[4:5] offset:2560
	global_store_short v238, v59, s[8:9] offset:-2048
	global_store_short_d16_hi v238, v59, s[8:9] offset:2560
	global_store_short v238, v60, s[10:11] offset:-2048
	global_store_short_d16_hi v238, v60, s[10:11] offset:2560
	global_store_short v238, v61, s[12:13] offset:-2048
	global_store_short_d16_hi v238, v61, s[12:13] offset:2560
	v_pk_mul_f32 v[156:157], v[46:47], v[234:235]
	v_pk_mul_f32 v[168:169], v[48:49], v[236:237]
	v_pk_mul_f32 v[46:47], v[46:47], v[230:231]
	v_pk_mul_f32 v[48:49], v[48:49], v[232:233]
	v_pk_fma_f32 v[156:157], v[42:43], v[230:231], v[156:157] neg_lo:[0,0,1] neg_hi:[0,0,1]
	v_pk_fma_f32 v[168:169], v[44:45], v[232:233], v[168:169] neg_lo:[0,0,1] neg_hi:[0,0,1]
	v_pk_fma_f32 v[46:47], v[42:43], v[234:235], v[46:47]
	v_pk_fma_f32 v[48:49], v[44:45], v[236:237], v[48:49]
	v_pk_mul_f32 v[156:157], v[156:157], s[84:85] op_sel_hi:[1,0]
	v_pk_mul_f32 v[168:169], v[168:169], s[84:85] op_sel_hi:[1,0]
	v_pk_mul_f32 v[46:47], v[46:47], s[84:85] op_sel_hi:[1,0]
	v_pk_mul_f32 v[48:49], v[48:49], s[84:85] op_sel_hi:[1,0]
	v_cvt_pk_bf16_f32 v42, v156, v157
	v_cvt_pk_bf16_f32 v43, v168, v169
	v_cvt_pk_bf16_f32 v44, v46, v47
	v_cvt_pk_bf16_f32 v45, v48, v49
	v_add_u32_e32 v239, 0x24000, v189
	global_store_dwordx2 v239, v[42:43], s[78:79]
	global_store_dwordx2 v239, v[44:45], s[78:79] offset:64
	global_store_short v238, v42, s[4:5] offset:-2016
	global_store_short_d16_hi v238, v42, s[4:5] offset:2592
	global_store_short v238, v43, s[8:9] offset:-2016
	global_store_short_d16_hi v238, v43, s[8:9] offset:2592
	global_store_short v238, v44, s[10:11] offset:-2016
	global_store_short_d16_hi v238, v44, s[10:11] offset:2592
	global_store_short v238, v45, s[12:13] offset:-2016
	global_store_short_d16_hi v238, v45, s[12:13] offset:2592
	v_pk_mul_f32 v[152:153], v[30:31], v[134:135]
	v_pk_mul_f32 v[154:155], v[32:33], v[136:137]
	v_pk_mul_f32 v[30:31], v[30:31], v[130:131]
	v_pk_mul_f32 v[32:33], v[32:33], v[132:133]
	v_pk_fma_f32 v[152:153], v[26:27], v[130:131], v[152:153] neg_lo:[0,0,1] neg_hi:[0,0,1]
	v_pk_fma_f32 v[154:155], v[28:29], v[132:133], v[154:155] neg_lo:[0,0,1] neg_hi:[0,0,1]
	v_pk_fma_f32 v[30:31], v[26:27], v[134:135], v[30:31]
	v_pk_fma_f32 v[32:33], v[28:29], v[136:137], v[32:33]
	v_pk_mul_f32 v[152:153], v[152:153], s[84:85] op_sel_hi:[1,0]
	v_pk_mul_f32 v[154:155], v[154:155], s[84:85] op_sel_hi:[1,0]
	v_pk_mul_f32 v[30:31], v[30:31], s[84:85] op_sel_hi:[1,0]
	v_pk_mul_f32 v[32:33], v[32:33], s[84:85] op_sel_hi:[1,0]
	v_cvt_pk_bf16_f32 v26, v152, v153
	v_cvt_pk_bf16_f32 v27, v154, v155
	v_cvt_pk_bf16_f32 v28, v30, v31
	v_cvt_pk_bf16_f32 v29, v32, v33
	v_add_u32_e32 v239, 0x28000, v189
	global_store_dwordx2 v239, v[26:27], s[78:79]
	global_store_dwordx2 v239, v[28:29], s[78:79] offset:64
	global_store_short v238, v26, s[4:5] offset:-1984
	global_store_short_d16_hi v238, v26, s[4:5] offset:2624
	global_store_short v238, v27, s[8:9] offset:-1984
	global_store_short_d16_hi v238, v27, s[8:9] offset:2624
	global_store_short v238, v28, s[10:11] offset:-1984
	global_store_short_d16_hi v238, v28, s[10:11] offset:2624
	global_store_short v238, v29, s[12:13] offset:-1984
	global_store_short_d16_hi v238, v29, s[12:13] offset:2624
	v_pk_mul_f32 v[156:157], v[14:15], v[162:163]
	v_pk_mul_f32 v[168:169], v[16:17], v[164:165]
	v_pk_mul_f32 v[14:15], v[14:15], v[158:159]
	v_pk_mul_f32 v[16:17], v[16:17], v[160:161]
	v_pk_fma_f32 v[156:157], v[10:11], v[158:159], v[156:157] neg_lo:[0,0,1] neg_hi:[0,0,1]
	v_pk_fma_f32 v[168:169], v[12:13], v[160:161], v[168:169] neg_lo:[0,0,1] neg_hi:[0,0,1]
	v_pk_fma_f32 v[14:15], v[10:11], v[162:163], v[14:15]
	v_pk_fma_f32 v[16:17], v[12:13], v[164:165], v[16:17]
	v_pk_mul_f32 v[156:157], v[156:157], s[84:85] op_sel_hi:[1,0]
	v_pk_mul_f32 v[168:169], v[168:169], s[84:85] op_sel_hi:[1,0]
	v_pk_mul_f32 v[14:15], v[14:15], s[84:85] op_sel_hi:[1,0]
	v_pk_mul_f32 v[16:17], v[16:17], s[84:85] op_sel_hi:[1,0]
	v_cvt_pk_bf16_f32 v10, v156, v157
	v_cvt_pk_bf16_f32 v11, v168, v169
	v_cvt_pk_bf16_f32 v12, v14, v15
; __device__ __forceinline__ unsigned pk2(float lo, float hi) { const f32x2_t v = {lo, hi}; const bf16v2_t b = __builtin_convertvector(v, bf16v2_t); return __builtin_bit_cast(unsigned, b); }
;     __device__ __forceinline__ void operator()(const AccT& acc, const pg8::Unit& u, int wr, int wc, int fr_, int fq_) const {
;     ...
;         if (pn < 4) {
;             const bool isk = pn >= 2;
;             const int jj0 = 16 * (wc & 1) + 4 * fq;
; #pragma unroll
;             for (int ai = 0; ai < 2; ++ai)
; #pragma unroll
;                 for (int m = 0; m < 4; ++m) {
;                     const int rl = rl0 + ai * 128 + m * 16;
;                     const size_t row = (size_t)u.pm * 256 + rl;
;                     f32x4 cs = (f32x4){1.f, 1.f, 1.f, 1.f}, sn = (f32x4){0.f, 0.f, 0.f, 0.f};
;                     if (pt != 0) { const int tpos = (pt - 1) * 256 + rl; cs = *(const f32x4*)(rope + (size_t)tpos * 32 + jj0); sn = *(const f32x4*)(rope + (size_t)SEQ * 32 + (size_t)tpos * 32 + jj0); }
; #pragma unroll
;                     for (int bj = 0; bj < 2; ++bj) {
;                         const int hq = 4 * (pn & 1) + 2 * bj + (wc >> 1);
;                         const f32x4 a1 = acc[ai][bj][m][0], a2 = acc[ai][bj][m][1];
;                         f32x4 o1 = a1 * cs - a2 * sn, o2 = a1 * sn + a2 * cs;
;                         if (isk) { o1 *= 0.125f; o2 *= 0.125f; }
;                         u32x2 p1, p2; p1.x = pk2(o1[0], o1[1]); p1.y = pk2(o1[2], o1[3]); p2.x = pk2(o2[0], o2[1]); p2.y = pk2(o2[2], o2[3]);
;                         bf16_t* dst = (isk ? KN : Q) + row * 512 + hq * 64 + jj0;
;                         *(u32x2*)dst = p1; *(u32x2*)(dst + 32) = p2;
;                         if (isk) {
;                             bf16_t* kt = KT + ((size_t)(b * NH + hq) * DK + jj0) * TB + pt * 256 + rl;
;                             kt[0] = (bf16_t)(p1.x & 0xffffu); kt[(size_t)TB] = (bf16_t)(p1.x >> 16); kt[(size_t)2 * TB] = (bf16_t)(p1.y & 0xffffu); kt[(size_t)3 * TB] = (bf16_t)(p1.y >> 16);
;                             bf16_t* kt2 = kt + (size_t)32 * TB;
;                             kt2[0] = (bf16_t)(p2.x & 0xffffu); kt2[(size_t)TB] = (bf16_t)(p2.x >> 16); kt2[(size_t)2 * TB] = (bf16_t)(p2.y & 0xffffu); kt2[(size_t)3 * TB] = (bf16_t)(p2.y >> 16);
;                         }
	v_cvt_pk_bf16_f32 v13, v16, v17
	v_add_u32_e32 v239, 0x2c000, v189
	global_store_dwordx2 v239, v[10:11], s[78:79]
	global_store_dwordx2 v239, v[12:13], s[78:79] offset:64
	global_store_short v238, v10, s[4:5] offset:-1952
	global_store_short_d16_hi v238, v10, s[4:5] offset:2656
	global_store_short v238, v11, s[8:9] offset:-1952
	global_store_short_d16_hi v238, v11, s[8:9] offset:2656
	global_store_short v238, v12, s[10:11] offset:-1952
	global_store_short_d16_hi v238, v12, s[10:11] offset:2656
	global_store_short v238, v13, s[12:13] offset:-1952
	global_store_short_d16_hi v238, v13, s[12:13] offset:2656
	s_add_u32 s4, s4, 0x90000
	s_addc_u32 s5, s5, 0
	s_add_u32 s8, s4, 0x2400
	s_addc_u32 s9, s5, 0
	s_add_u32 s10, s4, 0x24000
	s_addc_u32 s11, s5, 0
	s_add_u32 s12, s10, 0x2400
	s_addc_u32 s13, s11, 0
	v_pk_mul_f32 v[152:153], v[118:119], v[194:195]
	v_pk_mul_f32 v[154:155], v[120:121], v[196:197]
	v_pk_mul_f32 v[118:119], v[118:119], v[190:191]
	v_pk_mul_f32 v[120:121], v[120:121], v[192:193]
	v_pk_fma_f32 v[152:153], v[114:115], v[190:191], v[152:153] neg_lo:[0,0,1] neg_hi:[0,0,1]
	v_pk_fma_f32 v[154:155], v[116:117], v[192:193], v[154:155] neg_lo:[0,0,1] neg_hi:[0,0,1]
	v_pk_fma_f32 v[118:119], v[114:115], v[194:195], v[118:119]
	v_pk_fma_f32 v[120:121], v[116:117], v[196:197], v[120:121]
	v_pk_mul_f32 v[152:153], v[152:153], s[84:85] op_sel_hi:[1,0]
	v_pk_mul_f32 v[154:155], v[154:155], s[84:85] op_sel_hi:[1,0]
	v_pk_mul_f32 v[118:119], v[118:119], s[84:85] op_sel_hi:[1,0]
	v_pk_mul_f32 v[120:121], v[120:121], s[84:85] op_sel_hi:[1,0]
	v_cvt_pk_bf16_f32 v114, v152, v153
	v_cvt_pk_bf16_f32 v115, v154, v155
	v_cvt_pk_bf16_f32 v116, v118, v119
	v_cvt_pk_bf16_f32 v117, v120, v121
	global_store_dwordx2 v189, v[114:115], s[78:79] offset:256
	global_store_dwordx2 v189, v[116:117], s[78:79] offset:320
	global_store_short v238, v114, s[4:5] offset:-2304
	global_store_short_d16_hi v238, v114, s[4:5] offset:2304
	global_store_short v238, v115, s[8:9] offset:-2304
	global_store_short_d16_hi v238, v115, s[8:9] offset:2304
	global_store_short v238, v116, s[10:11] offset:-2304
	global_store_short_d16_hi v238, v116, s[10:11] offset:2304
	global_store_short v238, v117, s[12:13] offset:-2304
	global_store_short_d16_hi v238, v117, s[12:13] offset:2304
	v_pk_mul_f32 v[156:157], v[102:103], v[202:203]
	v_pk_mul_f32 v[168:169], v[104:105], v[204:205]
	v_pk_mul_f32 v[102:103], v[102:103], v[198:199]
	v_pk_mul_f32 v[104:105], v[104:105], v[200:201]
	v_pk_fma_f32 v[156:157], v[98:99], v[198:199], v[156:157] neg_lo:[0,0,1] neg_hi:[0,0,1]
	v_pk_fma_f32 v[168:169], v[100:101], v[200:201], v[168:169] neg_lo:[0,0,1] neg_hi:[0,0,1]
	v_pk_fma_f32 v[102:103], v[98:99], v[202:203], v[102:103]
	v_pk_fma_f32 v[104:105], v[100:101], v[204:205], v[104:105]
	v_pk_mul_f32 v[156:157], v[156:157], s[84:85] op_sel_hi:[1,0]
	v_pk_mul_f32 v[168:169], v[168:169], s[84:85] op_sel_hi:[1,0]
	v_pk_mul_f32 v[102:103], v[102:103], s[84:85] op_sel_hi:[1,0]
	v_pk_mul_f32 v[104:105], v[104:105], s[84:85] op_sel_hi:[1,0]
	v_cvt_pk_bf16_f32 v98, v156, v157
	v_cvt_pk_bf16_f32 v99, v168, v169
	v_cvt_pk_bf16_f32 v100, v102, v103
	v_cvt_pk_bf16_f32 v101, v104, v105
	v_add_u32_e32 v239, 0x4000, v189
	global_store_dwordx2 v239, v[98:99], s[78:79] offset:256
	global_store_dwordx2 v239, v[100:101], s[78:79] offset:320
	global_store_short v238, v98, s[4:5] offset:-2272
	global_store_short_d16_hi v238, v98, s[4:5] offset:2336
	global_store_short v238, v99, s[8:9] offset:-2272
	global_store_short_d16_hi v238, v99, s[8:9] offset:2336
	global_store_short v238, v100, s[10:11] offset:-2272
	global_store_short_d16_hi v238, v100, s[10:11] offset:2336
	global_store_short v238, v101, s[12:13] offset:-2272
	global_store_short_d16_hi v238, v101, s[12:13] offset:2336
	v_pk_mul_f32 v[152:153], v[86:87], v[210:211]
	v_pk_mul_f32 v[154:155], v[88:89], v[212:213]
	v_pk_mul_f32 v[86:87], v[86:87], v[206:207]
	v_pk_mul_f32 v[88:89], v[88:89], v[208:209]
	v_pk_fma_f32 v[152:153], v[82:83], v[206:207], v[152:153] neg_lo:[0,0,1] neg_hi:[0,0,1]
	v_pk_fma_f32 v[154:155], v[84:85], v[208:209], v[154:155] neg_lo:[0,0,1] neg_hi:[0,0,1]
	v_pk_fma_f32 v[86:87], v[82:83], v[210:211], v[86:87]
	v_pk_fma_f32 v[88:89], v[84:85], v[212:213], v[88:89]
	v_pk_mul_f32 v[152:153], v[152:153], s[84:85] op_sel_hi:[1,0]
	v_pk_mul_f32 v[154:155], v[154:155], s[84:85] op_sel_hi:[1,0]
	v_pk_mul_f32 v[86:87], v[86:87], s[84:85] op_sel_hi:[1,0]
	v_pk_mul_f32 v[88:89], v[88:89], s[84:85] op_sel_hi:[1,0]
	v_cvt_pk_bf16_f32 v82, v152, v153
	v_cvt_pk_bf16_f32 v83, v154, v155
	v_cvt_pk_bf16_f32 v84, v86, v87
	v_cvt_pk_bf16_f32 v85, v88, v89
	v_add_u32_e32 v239, 0x8000, v189
	global_store_dwordx2 v239, v[82:83], s[78:79] offset:256
	global_store_dwordx2 v239, v[84:85], s[78:79] offset:320
	global_store_short v238, v82, s[4:5] offset:-2240
	global_store_short_d16_hi v238, v82, s[4:5] offset:2368
	global_store_short v238, v83, s[8:9] offset:-2240
	global_store_short_d16_hi v238, v83, s[8:9] offset:2368
	global_store_short v238, v84, s[10:11] offset:-2240
	global_store_short_d16_hi v238, v84, s[10:11] offset:2368
	global_store_short v238, v85, s[12:13] offset:-2240
	global_store_short_d16_hi v238, v85, s[12:13] offset:2368
	v_pk_mul_f32 v[156:157], v[70:71], v[218:219]
	v_pk_mul_f32 v[168:169], v[72:73], v[220:221]
	v_pk_mul_f32 v[70:71], v[70:71], v[214:215]
	v_pk_mul_f32 v[72:73], v[72:73], v[216:217]
	v_pk_fma_f32 v[156:157], v[66:67], v[214:215], v[156:157] neg_lo:[0,0,1] neg_hi:[0,0,1]
	v_pk_fma_f32 v[168:169], v[68:69], v[216:217], v[168:169] neg_lo:[0,0,1] neg_hi:[0,0,1]
	v_pk_fma_f32 v[70:71], v[66:67], v[218:219], v[70:71]
; __device__ __forceinline__ unsigned pk2(float lo, float hi) { const f32x2_t v = {lo, hi}; const bf16v2_t b = __builtin_convertvector(v, bf16v2_t); return __builtin_bit_cast(unsigned, b); }
;     __device__ __forceinline__ void operator()(const AccT& acc, const pg8::Unit& u, int wr, int wc, int fr_, int fq_) const {
;     ...
;         if (pn < 4) {
;             const bool isk = pn >= 2;
;             const int jj0 = 16 * (wc & 1) + 4 * fq;
; #pragma unroll
;             for (int ai = 0; ai < 2; ++ai)
; #pragma unroll
;                 for (int m = 0; m < 4; ++m) {
;                     const int rl = rl0 + ai * 128 + m * 16;
;                     const size_t row = (size_t)u.pm * 256 + rl;
;                     f32x4 cs = (f32x4){1.f, 1.f, 1.f, 1.f}, sn = (f32x4){0.f, 0.f, 0.f, 0.f};
;                     if (pt != 0) { const int tpos = (pt - 1) * 256 + rl; cs = *(const f32x4*)(rope + (size_t)tpos * 32 + jj0); sn = *(const f32x4*)(rope + (size_t)SEQ * 32 + (size_t)tpos * 32 + jj0); }
; #pragma unroll
;                     for (int bj = 0; bj < 2; ++bj) {
;                         const int hq = 4 * (pn & 1) + 2 * bj + (wc >> 1);
;                         const f32x4 a1 = acc[ai][bj][m][0], a2 = acc[ai][bj][m][1];
;                         f32x4 o1 = a1 * cs - a2 * sn, o2 = a1 * sn + a2 * cs;
;                         if (isk) { o1 *= 0.125f; o2 *= 0.125f; }
;                         u32x2 p1, p2; p1.x = pk2(o1[0], o1[1]); p1.y = pk2(o1[2], o1[3]); p2.x = pk2(o2[0], o2[1]); p2.y = pk2(o2[2], o2[3]);
;                         bf16_t* dst = (isk ? KN : Q) + row * 512 + hq * 64 + jj0;
;                         *(u32x2*)dst = p1; *(u32x2*)(dst + 32) = p2;
;                         if (isk) {
;                             bf16_t* kt = KT + ((size_t)(b * NH + hq) * DK + jj0) * TB + pt * 256 + rl;
;                             kt[0] = (bf16_t)(p1.x & 0xffffu); kt[(size_t)TB] = (bf16_t)(p1.x >> 16); kt[(size_t)2 * TB] = (bf16_t)(p1.y & 0xffffu); kt[(size_t)3 * TB] = (bf16_t)(p1.y >> 16);
;                             bf16_t* kt2 = kt + (size_t)32 * TB;
;                             kt2[0] = (bf16_t)(p2.x & 0xffffu); kt2[(size_t)TB] = (bf16_t)(p2.x >> 16); kt2[(size_t)2 * TB] = (bf16_t)(p2.y & 0xffffu); kt2[(size_t)3 * TB] = (bf16_t)(p2.y >> 16);
;                         }
	v_pk_fma_f32 v[72:73], v[68:69], v[220:221], v[72:73]
	v_pk_mul_f32 v[156:157], v[156:157], s[84:85] op_sel_hi:[1,0]
	v_pk_mul_f32 v[168:169], v[168:169], s[84:85] op_sel_hi:[1,0]
	v_pk_mul_f32 v[70:71], v[70:71], s[84:85] op_sel_hi:[1,0]
	v_pk_mul_f32 v[72:73], v[72:73], s[84:85] op_sel_hi:[1,0]
	v_cvt_pk_bf16_f32 v66, v156, v157
	v_cvt_pk_bf16_f32 v67, v168, v169
	v_cvt_pk_bf16_f32 v68, v70, v71
	v_cvt_pk_bf16_f32 v69, v72, v73
	v_add_u32_e32 v239, 0xc000, v189
	global_store_dwordx2 v239, v[66:67], s[78:79] offset:256
	global_store_dwordx2 v239, v[68:69], s[78:79] offset:320
	global_store_short v238, v66, s[4:5] offset:-2208
	global_store_short_d16_hi v238, v66, s[4:5] offset:2400
	global_store_short v238, v67, s[8:9] offset:-2208
	global_store_short_d16_hi v238, v67, s[8:9] offset:2400
	global_store_short v238, v68, s[10:11] offset:-2208
	global_store_short_d16_hi v238, v68, s[10:11] offset:2400
	global_store_short v238, v69, s[12:13] offset:-2208
	global_store_short_d16_hi v238, v69, s[12:13] offset:2400
	v_pk_mul_f32 v[152:153], v[54:55], v[226:227]
	v_pk_mul_f32 v[154:155], v[56:57], v[228:229]
	v_pk_mul_f32 v[54:55], v[54:55], v[222:223]
	v_pk_mul_f32 v[56:57], v[56:57], v[224:225]
	v_pk_fma_f32 v[152:153], v[50:51], v[222:223], v[152:153] neg_lo:[0,0,1] neg_hi:[0,0,1]
	v_pk_fma_f32 v[154:155], v[52:53], v[224:225], v[154:155] neg_lo:[0,0,1] neg_hi:[0,0,1]
	v_pk_fma_f32 v[54:55], v[50:51], v[226:227], v[54:55]
	v_pk_fma_f32 v[56:57], v[52:53], v[228:229], v[56:57]
	v_pk_mul_f32 v[152:153], v[152:153], s[84:85] op_sel_hi:[1,0]
	v_pk_mul_f32 v[154:155], v[154:155], s[84:85] op_sel_hi:[1,0]
	v_pk_mul_f32 v[54:55], v[54:55], s[84:85] op_sel_hi:[1,0]
	v_pk_mul_f32 v[56:57], v[56:57], s[84:85] op_sel_hi:[1,0]
	v_cvt_pk_bf16_f32 v50, v152, v153
	v_cvt_pk_bf16_f32 v51, v154, v155
	v_cvt_pk_bf16_f32 v52, v54, v55
	v_cvt_pk_bf16_f32 v53, v56, v57
	v_add_u32_e32 v239, 0x20000, v189
	global_store_dwordx2 v239, v[50:51], s[78:79] offset:256
	global_store_dwordx2 v239, v[52:53], s[78:79] offset:320
	global_store_short v238, v50, s[4:5] offset:-2048
	global_store_short_d16_hi v238, v50, s[4:5] offset:2560
	global_store_short v238, v51, s[8:9] offset:-2048
	global_store_short_d16_hi v238, v51, s[8:9] offset:2560
	global_store_short v238, v52, s[10:11] offset:-2048
	global_store_short_d16_hi v238, v52, s[10:11] offset:2560
	global_store_short v238, v53, s[12:13] offset:-2048
	global_store_short_d16_hi v238, v53, s[12:13] offset:2560
	v_pk_mul_f32 v[156:157], v[38:39], v[234:235]
	v_pk_mul_f32 v[168:169], v[40:41], v[236:237]
	v_pk_mul_f32 v[38:39], v[38:39], v[230:231]
	v_pk_mul_f32 v[40:41], v[40:41], v[232:233]
	v_pk_fma_f32 v[156:157], v[34:35], v[230:231], v[156:157] neg_lo:[0,0,1] neg_hi:[0,0,1]
	v_pk_fma_f32 v[168:169], v[36:37], v[232:233], v[168:169] neg_lo:[0,0,1] neg_hi:[0,0,1]
	v_pk_fma_f32 v[38:39], v[34:35], v[234:235], v[38:39]
	v_pk_fma_f32 v[40:41], v[36:37], v[236:237], v[40:41]
	v_pk_mul_f32 v[156:157], v[156:157], s[84:85] op_sel_hi:[1,0]
	v_pk_mul_f32 v[168:169], v[168:169], s[84:85] op_sel_hi:[1,0]
	v_pk_mul_f32 v[38:39], v[38:39], s[84:85] op_sel_hi:[1,0]
	v_pk_mul_f32 v[40:41], v[40:41], s[84:85] op_sel_hi:[1,0]
	v_cvt_pk_bf16_f32 v34, v156, v157
	v_cvt_pk_bf16_f32 v35, v168, v169
	v_cvt_pk_bf16_f32 v36, v38, v39
	v_cvt_pk_bf16_f32 v37, v40, v41
	v_add_u32_e32 v239, 0x24000, v189
	global_store_dwordx2 v239, v[34:35], s[78:79] offset:256
	global_store_dwordx2 v239, v[36:37], s[78:79] offset:320
	global_store_short v238, v34, s[4:5] offset:-2016
	global_store_short_d16_hi v238, v34, s[4:5] offset:2592
	global_store_short v238, v35, s[8:9] offset:-2016
	global_store_short_d16_hi v238, v35, s[8:9] offset:2592
	global_store_short v238, v36, s[10:11] offset:-2016
	global_store_short_d16_hi v238, v36, s[10:11] offset:2592
	global_store_short v238, v37, s[12:13] offset:-2016
	global_store_short_d16_hi v238, v37, s[12:13] offset:2592
	v_pk_mul_f32 v[152:153], v[22:23], v[134:135]
	v_pk_mul_f32 v[154:155], v[24:25], v[136:137]
	v_pk_mul_f32 v[22:23], v[22:23], v[130:131]
	v_pk_mul_f32 v[24:25], v[24:25], v[132:133]
	v_pk_fma_f32 v[152:153], v[18:19], v[130:131], v[152:153] neg_lo:[0,0,1] neg_hi:[0,0,1]
	v_pk_fma_f32 v[154:155], v[20:21], v[132:133], v[154:155] neg_lo:[0,0,1] neg_hi:[0,0,1]
	v_pk_fma_f32 v[22:23], v[18:19], v[134:135], v[22:23]
	v_pk_fma_f32 v[24:25], v[20:21], v[136:137], v[24:25]
	v_pk_mul_f32 v[152:153], v[152:153], s[84:85] op_sel_hi:[1,0]
	v_pk_mul_f32 v[154:155], v[154:155], s[84:85] op_sel_hi:[1,0]
	v_pk_mul_f32 v[22:23], v[22:23], s[84:85] op_sel_hi:[1,0]
	v_pk_mul_f32 v[24:25], v[24:25], s[84:85] op_sel_hi:[1,0]
	v_cvt_pk_bf16_f32 v18, v152, v153
	v_cvt_pk_bf16_f32 v19, v154, v155
	v_cvt_pk_bf16_f32 v20, v22, v23
	v_cvt_pk_bf16_f32 v21, v24, v25
	v_add_u32_e32 v239, 0x28000, v189
	global_store_dwordx2 v239, v[18:19], s[78:79] offset:256
	global_store_dwordx2 v239, v[20:21], s[78:79] offset:320
	global_store_short v238, v18, s[4:5] offset:-1984
	global_store_short_d16_hi v238, v18, s[4:5] offset:2624
	global_store_short v238, v19, s[8:9] offset:-1984
	global_store_short_d16_hi v238, v19, s[8:9] offset:2624
	global_store_short v238, v20, s[10:11] offset:-1984
	global_store_short_d16_hi v238, v20, s[10:11] offset:2624
	global_store_short v238, v21, s[12:13] offset:-1984
	global_store_short_d16_hi v238, v21, s[12:13] offset:2624
	v_pk_mul_f32 v[156:157], v[2:3], v[162:163]
	v_pk_mul_f32 v[168:169], v[4:5], v[164:165]
	v_pk_mul_f32 v[2:3], v[2:3], v[158:159]
	v_pk_mul_f32 v[4:5], v[4:5], v[160:161]
	v_pk_fma_f32 v[156:157], v[6:7], v[158:159], v[156:157] neg_lo:[0,0,1] neg_hi:[0,0,1]
	v_pk_fma_f32 v[168:169], v[8:9], v[160:161], v[168:169] neg_lo:[0,0,1] neg_hi:[0,0,1]
	v_pk_fma_f32 v[2:3], v[6:7], v[162:163], v[2:3]
	v_pk_fma_f32 v[4:5], v[8:9], v[164:165], v[4:5]
	v_pk_mul_f32 v[156:157], v[156:157], s[84:85] op_sel_hi:[1,0]
	v_pk_mul_f32 v[168:169], v[168:169], s[84:85] op_sel_hi:[1,0]
	v_pk_mul_f32 v[2:3], v[2:3], s[84:85] op_sel_hi:[1,0]
	v_pk_mul_f32 v[4:5], v[4:5], s[84:85] op_sel_hi:[1,0]
	v_cvt_pk_bf16_f32 v6, v156, v157
	v_cvt_pk_bf16_f32 v7, v168, v169
	v_cvt_pk_bf16_f32 v8, v2, v3
	v_cvt_pk_bf16_f32 v9, v4, v5
	v_add_u32_e32 v239, 0x2c000, v189
	global_store_dwordx2 v239, v[6:7], s[78:79] offset:256
	global_store_dwordx2 v239, v[8:9], s[78:79] offset:320
	global_store_short v238, v6, s[4:5] offset:-1952
	global_store_short_d16_hi v238, v6, s[4:5] offset:2656
	global_store_short v238, v7, s[8:9] offset:-1952
	global_store_short_d16_hi v238, v7, s[8:9] offset:2656
	global_store_short v238, v8, s[10:11] offset:-1952
	global_store_short_d16_hi v238, v8, s[10:11] offset:2656
	global_store_short v238, v9, s[12:13] offset:-1952
	global_store_short_d16_hi v238, v9, s[12:13] offset:2656
	s_mov_b32 s32, 3
	s_branch .LBB0_323

; #define LAS __attribute__((address_space(3)))
; #define PG8_STAGE(bufoff, gbase, voff) do { _Pragma("unroll") for (int _i = 0; _i < 2; ++_i) \
;         __builtin_amdgcn_global_load_lds((const unsigned*)((const char*)(gbase) + (voff)[_i]), (LAS unsigned*)(lds + (bufoff) + ldsw + _i * 8192), 16, 0, 0); } while (0)
; #define PG8_WAIT_V(n) asm volatile("s_waitcnt vmcnt(" #n ")" ::: "memory")
; #define PG8_BAR __builtin_amdgcn_s_barrier()
; __device__ __forceinline__ void build_units(LAS unsigned char* lds, const Sched& S) {
;     const int t = threadIdx.x;
;     if (t < 16) {
;         int valid, pm, pn, sub, kt0, nt, sp;
;         S.entry(t, valid, pm, pn, sub, kt0, nt, sp);
;         asm volatile("" : "+v"(kt0), "+v"(nt), "+v"(sp), "+v"(valid));
;         LAS int* e = (LAS int*)(lds + 131072 + 64) + 8 * t;
;         e[0] = valid; e[1] = pm; e[2] = pn; e[3] = sub; e[4] = kt0; e[5] = nt; e[6] = sp; e[7] = 0;
;     }
;     __syncthreads();
; }
; template <class Epi>
; __device__ __forceinline__ void gemm_phase(LAS unsigned char* lds, const Gemm g, const Epi& E) {
;     ...
;     Unit cur; int ui = 0;
;     if (!get_unit(lds, 0, cur)) return;
;     f32x4 acc[2][2][4][2];
; #pragma unroll
;     for (int a = 0; a < 2; ++a)
; #pragma unroll
;         for (int b = 0; b < 2; ++b)
; #pragma unroll
;             for (int m = 0; m < 4; ++m)
; #pragma unroll
;                 for (int n = 0; n < 2; ++n) acc[a][b][m][n] = (f32x4){0.f, 0.f, 0.f, 0.f};
;     bf16x8 At[4][2], B0[2][2], B1[2][2];
;     const char* cA = (const char*)((cur.sub & 1) ? g.A1 : g.A0) + (size_t)cur.pm * tstep + (size_t)cur.kt0 * kstep; const char* cB = (const char*)((cur.sub & 1) ? g.B1 : g.B0) + (size_t)cur.pn * tstep + (size_t)cur.kt0 * kstep;
;     PG8_STAGE(PG8_SB(0, 0), cB, voffA); PG8_STAGE(PG8_SB(0, 1), cB + hstep, voffA); PG8_STAGE(PG8_SA(0, 0), cA, voffA); PG8_STAGE(PG8_SA(0, 1), cA + hstep, voffA);
;     if (wr == 1) PG8_BAR;
;     PG8_WAIT_V(2); PG8_BAR;
;     PG8_STAGE(PG8_SB(1, 0), cB + kstep, voffA); PG8_STAGE(PG8_SA(1, 0), cA + kstep, voffA); PG8_STAGE(PG8_SB(1, 1), cB + hstep + kstep, voffA);
;     PG8_WAIT_V(6); PG8_BAR;
.LBB0_330:
	s_mov_b32 s32, 0
	s_waitcnt vmcnt(0)
	s_movk_i32 s45, 0x7ff
	s_mov_b32 s59, 0xbfb8aa3b
	s_mov_b32 s76, 0xb2a5705f
	s_mov_b32 s77, 0x42ce8ed0
	s_mov_b32 s58, 0xc2b17218
	s_mov_b32 s65, 0x7f800000
	v_readlane_b32 s18, v254, 29
	s_barrier

; #define PG8_STAGE(bufoff, gbase, voff) do { _Pragma("unroll") for (int _i = 0; _i < 2; ++_i) \
;         __builtin_amdgcn_global_load_lds((const unsigned*)((const char*)(gbase) + (voff)[_i]), (LAS unsigned*)(lds + (bufoff) + ldsw + _i * 8192), 16, 0, 0); } while (0)
; #define PG8_LDA(dst, b, h) do { _Pragma("unroll") for (int m = 0; m < 4; ++m) _Pragma("unroll") for (int k = 0; k < 2; ++k) dst[m][k] = *(const LAS bf16x8*)(lds + PG8_SA(b, h) + aoff + m * 2048 + k * 1024); } while (0)
; #define PG8_LDB(dst, b, h) do { _Pragma("unroll") for (int n = 0; n < 2; ++n) _Pragma("unroll") for (int k = 0; k < 2; ++k) dst[n][k] = *(const LAS bf16x8*)(lds + PG8_SB(b, h) + boff + n * 2048 + k * 1024); } while (0)
; #define PG8_WAIT_V(n) asm volatile("s_waitcnt vmcnt(" #n ")" ::: "memory")
; #define PG8_WAIT_L(n) asm volatile("s_waitcnt lgkmcnt(" #n ")" ::: "memory")
; #define PG8_BAR __builtin_amdgcn_s_barrier()
; #define PG8_SCHED __builtin_amdgcn_sched_barrier(0)
; template <class Epi>
; __device__ __forceinline__ void gemm_phase(LAS unsigned char* lds, const Gemm g, const Epi& E) {
;     ...
;         Unit nxt; const bool has_next = get_unit(lds, ui + 1, nxt);
;         const char* nA = has_next ? (const char*)((nxt.sub & 1) ? g.A1 : g.A0) + (size_t)nxt.pm * tstep + (size_t)nxt.kt0 * kstep : cA; const char* nB = has_next ? (const char*)((nxt.sub & 1) ? g.B1 : g.B0) + (size_t)nxt.pn * tstep + (size_t)nxt.kt0 * kstep : cB;
;         const int nt = cur.nt;
;         for (int t = 0; t < nt; t += 2) {
;             const bool last = (t == nt - 2);
;             const char* a1 = cA + (size_t)(t + 1) * kstep;
;             const char* a2 = last ? nA : cA + (size_t)(t + 2) * kstep; const char* b2 = last ? nB : cB + (size_t)(t + 2) * kstep;
;             const char* a3 = a2 + kstep; const char* b3 = b2 + kstep;
;             PG8_LDB(B0, 0, 0); PG8_LDB(B1, 0, 1); PG8_SCHED; PG8_LDA(At, 0, 0); PG8_STAGE(PG8_SA(1, 1), a1 + hstep, voffA);
;             PG8_WAIT_V(8); PG8_WAIT_L(0); PG8_BAR; PG8_MMA(0, 0, At, B0); PG8_MMA(0, 1, At, B1); PG8_BAR; PG8_SCHED;
;             PG8_LDA(At, 0, 1); PG8_STAGE(PG8_SB(0, 0), b2, voffA); PG8_STAGE(PG8_SB(0, 1), b2 + hstep, voffA); PG8_STAGE(PG8_SA(0, 0), a2, voffA);
;             PG8_WAIT_V(8); PG8_WAIT_L(0); PG8_BAR; PG8_MMA(1, 0, At, B0); PG8_MMA(1, 1, At, B1); PG8_BAR; PG8_SCHED;
.Lk3_peel:
	s_add_i32 vcc_hi, s4, 2
	s_add_u32 s5, s68, 0xfffc0080
	s_addc_u32 s70, s69, -1
	s_cmp_eq_u32 s92, s4
	s_cselect_b32 s71, s15, s70
	s_cselect_b32 s70, s55, s5
	v_add_u32_e32 v136, s21, v144
	s_cselect_b32 s5, s57, vcc_lo
	s_cselect_b32 s4, s82, s93
	s_add_i32 s25, 0, 0x14000
	ds_read_b128 v[146:149], v136
	ds_read_b128 v[150:153], v136 offset:1024
	ds_read_b128 v[154:157], v136 offset:2048
	ds_read_b128 v[158:161], v136 offset:3072
	v_add_u32_e32 v136, s25, v144
	ds_read_b128 v[162:165], v136
	ds_read_b128 v[166:169], v136 offset:1024
	ds_read_b128 v[190:193], v136 offset:2048
	ds_read_b128 v[194:197], v136 offset:3072
	v_lshl_add_u64 v[136:137], s[68:69], 0, v[132:133]
	s_add_i32 m0, s7, 0xc000
	ds_read_b128 v[198:201], v145
	ds_read_b128 v[202:205], v145 offset:1024
	ds_read_b128 v[206:209], v145 offset:2048
	ds_read_b128 v[210:213], v145 offset:3072
	ds_read_b128 v[214:217], v145 offset:4096
	ds_read_b128 v[218:221], v145 offset:5120
	ds_read_b128 v[222:225], v145 offset:6144
	ds_read_b128 v[226:229], v145 offset:7168
	global_load_lds_dwordx4 v[136:137], off
	v_lshl_add_u64 v[136:137], s[68:69], 0, v[134:135]
	s_add_i32 m0, s7, 0xe000
	s_nop 0
	global_load_lds_dwordx4 v[136:137], off
	s_cmp_eq_u32 s32, 1
	s_cbranch_scc1 .Lrw3a_1
	s_waitcnt vmcnt(16)
	s_branch .Lrw3a_d
.Lrw3a_1:
	s_waitcnt vmcnt(16)
	s_branch .Lrw3a_d
.Lrw3a_d:
	s_waitcnt lgkmcnt(0)
	s_barrier
	s_setprio 1
	s_waitcnt lgkmcnt(0)
	v_mfma_f32_16x16x32_bf16 v[126:129], v[146:149], v[198:201], v[126:129]
	v_mfma_f32_16x16x32_bf16 v[118:121], v[154:157], v[198:201], v[118:121]
	v_mfma_f32_16x16x32_bf16 v[110:113], v[146:149], v[206:209], v[110:113]
	v_mfma_f32_16x16x32_bf16 v[102:105], v[154:157], v[206:209], v[102:105]
	v_mfma_f32_16x16x32_bf16 v[94:97], v[146:149], v[214:217], v[94:97]
	v_mfma_f32_16x16x32_bf16 v[86:89], v[154:157], v[214:217], v[86:89]
	v_mfma_f32_16x16x32_bf16 v[78:81], v[146:149], v[222:225], v[78:81]
	v_mfma_f32_16x16x32_bf16 v[70:73], v[154:157], v[222:225], v[70:73]
	v_mfma_f32_16x16x32_bf16 v[126:129], v[150:153], v[202:205], v[126:129]
	v_mfma_f32_16x16x32_bf16 v[118:121], v[158:161], v[202:205], v[118:121]
	v_mfma_f32_16x16x32_bf16 v[110:113], v[150:153], v[210:213], v[110:113]
	v_mfma_f32_16x16x32_bf16 v[102:105], v[158:161], v[210:213], v[102:105]
	v_mfma_f32_16x16x32_bf16 v[94:97], v[150:153], v[218:221], v[94:97]
	v_mfma_f32_16x16x32_bf16 v[86:89], v[158:161], v[218:221], v[86:89]
	v_mfma_f32_16x16x32_bf16 v[78:81], v[150:153], v[226:229], v[78:81]
	v_mfma_f32_16x16x32_bf16 v[70:73], v[158:161], v[226:229], v[70:73]
	s_setprio 0
	s_setprio 1
	v_mfma_f32_16x16x32_bf16 v[122:125], v[162:165], v[198:201], v[122:125]
	v_mfma_f32_16x16x32_bf16 v[114:117], v[190:193], v[198:201], v[114:117]
	v_mfma_f32_16x16x32_bf16 v[106:109], v[162:165], v[206:209], v[106:109]
	v_mfma_f32_16x16x32_bf16 v[98:101], v[190:193], v[206:209], v[98:101]
	v_mfma_f32_16x16x32_bf16 v[90:93], v[162:165], v[214:217], v[90:93]
	v_mfma_f32_16x16x32_bf16 v[82:85], v[190:193], v[214:217], v[82:85]
	v_mfma_f32_16x16x32_bf16 v[74:77], v[162:165], v[222:225], v[74:77]
	v_mfma_f32_16x16x32_bf16 v[66:69], v[190:193], v[222:225], v[66:69]
	v_mfma_f32_16x16x32_bf16 v[122:125], v[166:169], v[202:205], v[122:125]
	v_mfma_f32_16x16x32_bf16 v[114:117], v[194:197], v[202:205], v[114:117]
	v_mfma_f32_16x16x32_bf16 v[106:109], v[166:169], v[210:213], v[106:109]
	v_mfma_f32_16x16x32_bf16 v[98:101], v[194:197], v[210:213], v[98:101]
	v_mfma_f32_16x16x32_bf16 v[90:93], v[166:169], v[218:221], v[90:93]
	v_mfma_f32_16x16x32_bf16 v[82:85], v[194:197], v[218:221], v[82:85]
	v_mfma_f32_16x16x32_bf16 v[74:77], v[166:169], v[226:229], v[74:77]
	v_mfma_f32_16x16x32_bf16 v[66:69], v[194:197], v[226:229], v[66:69]
	s_setprio 0
	s_barrier
	s_add_i32 s72, s21, s2
	v_lshl_add_u64 v[136:137], s[4:5], 0, v[0:1]
	s_mov_b32 m0, s72
	ds_read_b128 v[198:201], v145 offset:16384
	ds_read_b128 v[202:205], v145 offset:17408
	ds_read_b128 v[206:209], v145 offset:18432
	ds_read_b128 v[210:213], v145 offset:19456
	ds_read_b128 v[214:217], v145 offset:20480
	ds_read_b128 v[218:221], v145 offset:21504
	ds_read_b128 v[222:225], v145 offset:22528
	ds_read_b128 v[226:229], v145 offset:23552
	global_load_lds_dwordx4 v[136:137], off
	s_add_i32 m0, s72, 0x2000
	s_add_u32 s72, s4, 0x40000
	v_lshl_add_u64 v[230:231], s[4:5], 0, v[130:131]
	s_addc_u32 s73, s5, 0
	s_add_i32 s25, s25, s2
	global_load_lds_dwordx4 v[230:231], off
	v_lshl_add_u64 v[232:233], s[72:73], 0, v[0:1]
	s_mov_b32 m0, s25
	v_lshl_add_u64 v[234:235], s[70:71], 0, v[130:131]
	global_load_lds_dwordx4 v[232:233], off
	v_lshl_add_u64 v[232:233], s[72:73], 0, v[130:131]
	s_add_i32 m0, s25, 0x2000
	s_nop 0
	global_load_lds_dwordx4 v[232:233], off
	v_lshl_add_u64 v[232:233], s[70:71], 0, v[0:1]
	s_mov_b32 m0, s7
	s_nop 0
	global_load_lds_dwordx4 v[232:233], off
	s_mov_b32 m0, s9
	s_nop 0
	global_load_lds_dwordx4 v[234:235], off
	s_cmp_eq_u32 s32, 1
	s_cbranch_scc1 .Lrw3b_1
	s_waitcnt vmcnt(16)
	s_branch .Lrw3b_d

; #define PG8_STAGE(bufoff, gbase, voff) do { _Pragma("unroll") for (int _i = 0; _i < 2; ++_i) \
;         __builtin_amdgcn_global_load_lds((const unsigned*)((const char*)(gbase) + (voff)[_i]), (LAS unsigned*)(lds + (bufoff) + ldsw + _i * 8192), 16, 0, 0); } while (0)
; #define PG8_LDA(dst, b, h) do { _Pragma("unroll") for (int m = 0; m < 4; ++m) _Pragma("unroll") for (int k = 0; k < 2; ++k) dst[m][k] = *(const LAS bf16x8*)(lds + PG8_SA(b, h) + aoff + m * 2048 + k * 1024); } while (0)
; #define PG8_LDB(dst, b, h) do { _Pragma("unroll") for (int n = 0; n < 2; ++n) _Pragma("unroll") for (int k = 0; k < 2; ++k) dst[n][k] = *(const LAS bf16x8*)(lds + PG8_SB(b, h) + boff + n * 2048 + k * 1024); } while (0)
; #define PG8_MMA(ai, bj, At, Bt) do { __builtin_amdgcn_s_setprio(1); _Pragma("unroll") for (int m = 0; m < 4; ++m) _Pragma("unroll") for (int n = 0; n < 2; ++n) _Pragma("unroll") for (int k = 0; k < 2; ++k) \
;         acc[ai][bj][m][n] = __builtin_amdgcn_mfma_f32_16x16x32_bf16(Bt[n][k], At[m][k], acc[ai][bj][m][n], 0, 0, 0); __builtin_amdgcn_s_setprio(0); } while (0)
; #define PG8_WAIT_V(n) asm volatile("s_waitcnt vmcnt(" #n ")" ::: "memory")
; #define PG8_WAIT_L(n) asm volatile("s_waitcnt lgkmcnt(" #n ")" ::: "memory")
; #define PG8_BAR __builtin_amdgcn_s_barrier()
; #define PG8_SCHED __builtin_amdgcn_sched_barrier(0)
; template <class Epi>
; __device__ __forceinline__ void gemm_phase(LAS unsigned char* lds, const Gemm g, const Epi& E) {
;     ...
;             PG8_WAIT_V(8); PG8_WAIT_L(0); PG8_BAR; PG8_MMA(1, 0, At, B0); PG8_MMA(1, 1, At, B1); PG8_BAR; PG8_SCHED;
;             PG8_LDB(B0, 1, 0); PG8_LDB(B1, 1, 1); PG8_SCHED; PG8_LDA(At, 1, 0); PG8_STAGE(PG8_SA(0, 1), a2 + hstep, voffA);
;             PG8_WAIT_V(8); PG8_WAIT_L(0); PG8_BAR; PG8_MMA(0, 0, At, B0); PG8_MMA(0, 1, At, B1); PG8_BAR; PG8_SCHED;
.Lrw3b_d:
	s_mov_b32 s32, 0
	s_waitcnt lgkmcnt(0)
	s_barrier
	s_setprio 1
	s_waitcnt lgkmcnt(0)
	v_mfma_f32_16x16x32_bf16 v[62:65], v[146:149], v[198:201], v[62:65]
	v_mfma_f32_16x16x32_bf16 v[54:57], v[154:157], v[198:201], v[54:57]
	v_mfma_f32_16x16x32_bf16 v[46:49], v[146:149], v[206:209], v[46:49]
	v_mfma_f32_16x16x32_bf16 v[38:41], v[154:157], v[206:209], v[38:41]
	v_mfma_f32_16x16x32_bf16 v[30:33], v[146:149], v[214:217], v[30:33]
	v_mfma_f32_16x16x32_bf16 v[22:25], v[154:157], v[214:217], v[22:25]
	v_mfma_f32_16x16x32_bf16 v[14:17], v[146:149], v[222:225], v[14:17]
	v_mfma_f32_16x16x32_bf16 v[6:9], v[154:157], v[222:225], v[6:9]
	v_mfma_f32_16x16x32_bf16 v[62:65], v[150:153], v[202:205], v[62:65]
	v_mfma_f32_16x16x32_bf16 v[54:57], v[158:161], v[202:205], v[54:57]
	v_mfma_f32_16x16x32_bf16 v[46:49], v[150:153], v[210:213], v[46:49]
	v_mfma_f32_16x16x32_bf16 v[38:41], v[158:161], v[210:213], v[38:41]
	v_mfma_f32_16x16x32_bf16 v[30:33], v[150:153], v[218:221], v[30:33]
	v_mfma_f32_16x16x32_bf16 v[22:25], v[158:161], v[218:221], v[22:25]
	v_mfma_f32_16x16x32_bf16 v[14:17], v[150:153], v[226:229], v[14:17]
	v_mfma_f32_16x16x32_bf16 v[6:9], v[158:161], v[226:229], v[6:9]
	s_setprio 0
	s_setprio 1
	v_mfma_f32_16x16x32_bf16 v[58:61], v[162:165], v[198:201], v[58:61]
	v_mfma_f32_16x16x32_bf16 v[50:53], v[190:193], v[198:201], v[50:53]
	v_mfma_f32_16x16x32_bf16 v[42:45], v[162:165], v[206:209], v[42:45]
	v_mfma_f32_16x16x32_bf16 v[34:37], v[190:193], v[206:209], v[34:37]
	v_mfma_f32_16x16x32_bf16 v[26:29], v[162:165], v[214:217], v[26:29]
	v_mfma_f32_16x16x32_bf16 v[18:21], v[190:193], v[214:217], v[18:21]
	v_mfma_f32_16x16x32_bf16 v[10:13], v[162:165], v[222:225], v[10:13]
	v_mfma_f32_16x16x32_bf16 v[2:5], v[190:193], v[222:225], v[2:5]
	v_mfma_f32_16x16x32_bf16 v[58:61], v[166:169], v[202:205], v[58:61]
	v_mfma_f32_16x16x32_bf16 v[50:53], v[194:197], v[202:205], v[50:53]
	v_mfma_f32_16x16x32_bf16 v[42:45], v[166:169], v[210:213], v[42:45]
	v_mfma_f32_16x16x32_bf16 v[34:37], v[194:197], v[210:213], v[34:37]
	v_mfma_f32_16x16x32_bf16 v[26:29], v[166:169], v[218:221], v[26:29]
	v_mfma_f32_16x16x32_bf16 v[18:21], v[194:197], v[218:221], v[18:21]
	v_mfma_f32_16x16x32_bf16 v[10:13], v[166:169], v[226:229], v[10:13]
	v_mfma_f32_16x16x32_bf16 v[2:5], v[194:197], v[226:229], v[2:5]
	s_setprio 0
	s_barrier
	s_add_i32 s25, 0, 0x18000
	s_add_i32 s72, 0, 0x1c000
	v_add_u32_e32 v158, s25, v144
	v_add_u32_e32 v189, s72, v144
	ds_read_b128 v[146:149], v158
	ds_read_b128 v[150:153], v158 offset:1024
	ds_read_b128 v[154:157], v158 offset:2048
	ds_read_b128 v[158:161], v158 offset:3072
	ds_read_b128 v[162:165], v189
	ds_read_b128 v[166:169], v189 offset:1024
	ds_read_b128 v[190:193], v189 offset:2048
	ds_read_b128 v[194:197], v189 offset:3072
	s_add_u32 s70, s70, 0x40000
	s_addc_u32 s71, s71, 0
	s_mov_b32 m0, s45
	v_lshl_add_u64 v[236:237], s[70:71], 0, v[0:1]
	ds_read_b128 v[198:201], v145 offset:32768
	ds_read_b128 v[202:205], v145 offset:33792
	ds_read_b128 v[206:209], v145 offset:34816
	ds_read_b128 v[210:213], v145 offset:35840
	ds_read_b128 v[214:217], v145 offset:36864
	ds_read_b128 v[218:221], v145 offset:37888
	ds_read_b128 v[222:225], v145 offset:38912
	ds_read_b128 v[226:229], v145 offset:39936
	global_load_lds_dwordx4 v[236:237], off
	v_lshl_add_u64 v[236:237], s[70:71], 0, v[130:131]
	s_mov_b32 m0, s52
	s_nop 0
	global_load_lds_dwordx4 v[236:237], off
	s_waitcnt vmcnt(8)
	s_waitcnt lgkmcnt(0)
	s_barrier
	s_setprio 1
	s_waitcnt lgkmcnt(0)
	v_mfma_f32_16x16x32_bf16 v[126:129], v[146:149], v[198:201], v[126:129]
	v_mfma_f32_16x16x32_bf16 v[118:121], v[154:157], v[198:201], v[118:121]
	v_mfma_f32_16x16x32_bf16 v[110:113], v[146:149], v[206:209], v[110:113]
	v_mfma_f32_16x16x32_bf16 v[102:105], v[154:157], v[206:209], v[102:105]
	v_mfma_f32_16x16x32_bf16 v[94:97], v[146:149], v[214:217], v[94:97]
	v_mfma_f32_16x16x32_bf16 v[86:89], v[154:157], v[214:217], v[86:89]
	v_mfma_f32_16x16x32_bf16 v[78:81], v[146:149], v[222:225], v[78:81]
	v_mfma_f32_16x16x32_bf16 v[70:73], v[154:157], v[222:225], v[70:73]
	v_mfma_f32_16x16x32_bf16 v[126:129], v[150:153], v[202:205], v[126:129]
	v_mfma_f32_16x16x32_bf16 v[118:121], v[158:161], v[202:205], v[118:121]
	v_mfma_f32_16x16x32_bf16 v[110:113], v[150:153], v[210:213], v[110:113]
	v_mfma_f32_16x16x32_bf16 v[102:105], v[158:161], v[210:213], v[102:105]
	v_mfma_f32_16x16x32_bf16 v[94:97], v[150:153], v[218:221], v[94:97]
	v_mfma_f32_16x16x32_bf16 v[86:89], v[158:161], v[218:221], v[86:89]
	v_mfma_f32_16x16x32_bf16 v[78:81], v[150:153], v[226:229], v[78:81]
	v_mfma_f32_16x16x32_bf16 v[70:73], v[158:161], v[226:229], v[70:73]
	s_setprio 0
	s_setprio 1
	v_mfma_f32_16x16x32_bf16 v[122:125], v[162:165], v[198:201], v[122:125]
	v_mfma_f32_16x16x32_bf16 v[114:117], v[190:193], v[198:201], v[114:117]
	v_mfma_f32_16x16x32_bf16 v[106:109], v[162:165], v[206:209], v[106:109]
	v_mfma_f32_16x16x32_bf16 v[98:101], v[190:193], v[206:209], v[98:101]
	v_mfma_f32_16x16x32_bf16 v[90:93], v[162:165], v[214:217], v[90:93]
	v_mfma_f32_16x16x32_bf16 v[82:85], v[190:193], v[214:217], v[82:85]
	v_mfma_f32_16x16x32_bf16 v[74:77], v[162:165], v[222:225], v[74:77]
	v_mfma_f32_16x16x32_bf16 v[66:69], v[190:193], v[222:225], v[66:69]
	v_mfma_f32_16x16x32_bf16 v[122:125], v[166:169], v[202:205], v[122:125]
	v_mfma_f32_16x16x32_bf16 v[114:117], v[194:197], v[202:205], v[114:117]
	v_mfma_f32_16x16x32_bf16 v[106:109], v[166:169], v[210:213], v[106:109]
	v_mfma_f32_16x16x32_bf16 v[98:101], v[194:197], v[210:213], v[98:101]
	v_mfma_f32_16x16x32_bf16 v[90:93], v[166:169], v[218:221], v[90:93]
	v_mfma_f32_16x16x32_bf16 v[82:85], v[194:197], v[218:221], v[82:85]
	v_mfma_f32_16x16x32_bf16 v[74:77], v[166:169], v[226:229], v[74:77]
	v_mfma_f32_16x16x32_bf16 v[66:69], v[194:197], v[226:229], v[66:69]
	s_setprio 0
	s_barrier
; #define PG8_STAGE(bufoff, gbase, voff) do { _Pragma("unroll") for (int _i = 0; _i < 2; ++_i) \
;         __builtin_amdgcn_global_load_lds((const unsigned*)((const char*)(gbase) + (voff)[_i]), (LAS unsigned*)(lds + (bufoff) + ldsw + _i * 8192), 16, 0, 0); } while (0)
; #define PG8_LDA(dst, b, h) do { _Pragma("unroll") for (int m = 0; m < 4; ++m) _Pragma("unroll") for (int k = 0; k < 2; ++k) dst[m][k] = *(const LAS bf16x8*)(lds + PG8_SA(b, h) + aoff + m * 2048 + k * 1024); } while (0)
; #define PG8_MMA(ai, bj, At, Bt) do { __builtin_amdgcn_s_setprio(1); _Pragma("unroll") for (int m = 0; m < 4; ++m) _Pragma("unroll") for (int n = 0; n < 2; ++n) _Pragma("unroll") for (int k = 0; k < 2; ++k) \
;         acc[ai][bj][m][n] = __builtin_amdgcn_mfma_f32_16x16x32_bf16(Bt[n][k], At[m][k], acc[ai][bj][m][n], 0, 0, 0); __builtin_amdgcn_s_setprio(0); } while (0)
; #define PG8_WAIT_V(n) asm volatile("s_waitcnt vmcnt(" #n ")" ::: "memory")
; #define PG8_WAIT_L(n) asm volatile("s_waitcnt lgkmcnt(" #n ")" ::: "memory")
; #define PG8_BAR __builtin_amdgcn_s_barrier()
; #define PG8_SCHED __builtin_amdgcn_sched_barrier(0)
; template <class Epi>
; __device__ __forceinline__ void gemm_phase(LAS unsigned char* lds, const Gemm g, const Epi& E) {
;     ...
;         for (int t = 0; t < nt; t += 2) {
;             const bool last = (t == nt - 2);
;     ...
;             PG8_LDA(At, 1, 1); PG8_STAGE(PG8_SB(1, 0), b3, voffA); PG8_STAGE(PG8_SB(1, 1), b3 + hstep, voffA); PG8_STAGE(PG8_SA(1, 0), a3, voffA);
;             PG8_WAIT_V(8); PG8_WAIT_L(0); PG8_BAR; PG8_MMA(1, 0, At, B0); PG8_MMA(1, 1, At, B1); PG8_BAR; PG8_SCHED;
	s_add_i32 s25, s25, s2
	v_lshl_add_u64 v[136:137], v[136:137], 0, s[80:81]
	s_mov_b32 m0, s25
	ds_read_b128 v[198:201], v145 offset:49152
	ds_read_b128 v[202:205], v145 offset:50176
	ds_read_b128 v[206:209], v145 offset:51200
	ds_read_b128 v[210:213], v145 offset:52224
	ds_read_b128 v[214:217], v145 offset:53248
	ds_read_b128 v[218:221], v145 offset:54272
	ds_read_b128 v[222:225], v145 offset:55296
	ds_read_b128 v[226:229], v145 offset:56320
	global_load_lds_dwordx4 v[136:137], off
	s_add_i32 m0, s25, 0x2000
	s_add_u32 s4, s4, 0x40080
	v_lshl_add_u64 v[136:137], v[230:231], 0, s[80:81]
	s_addc_u32 s5, s5, 0
	s_add_i32 s25, s72, s2
	global_load_lds_dwordx4 v[136:137], off
	v_lshl_add_u64 v[136:137], s[4:5], 0, v[0:1]
	s_mov_b32 m0, s25
	s_nop 0
	global_load_lds_dwordx4 v[136:137], off
	v_lshl_add_u64 v[136:137], s[4:5], 0, v[130:131]
	s_add_i32 m0, s25, 0x2000
	s_nop 0
	global_load_lds_dwordx4 v[136:137], off
	v_lshl_add_u64 v[136:137], v[232:233], 0, s[80:81]
	s_mov_b32 m0, s75
	s_nop 0
	global_load_lds_dwordx4 v[136:137], off
	v_lshl_add_u64 v[136:137], v[234:235], 0, s[80:81]
	s_mov_b32 m0, s76
	s_nop 0
	global_load_lds_dwordx4 v[136:137], off
	s_waitcnt vmcnt(8)
	s_waitcnt lgkmcnt(0)
	s_barrier
	s_setprio 1
	s_waitcnt lgkmcnt(0)
	v_mfma_f32_16x16x32_bf16 v[62:65], v[146:149], v[198:201], v[62:65]
	v_mfma_f32_16x16x32_bf16 v[54:57], v[154:157], v[198:201], v[54:57]
	v_mfma_f32_16x16x32_bf16 v[46:49], v[146:149], v[206:209], v[46:49]
	v_mfma_f32_16x16x32_bf16 v[38:41], v[154:157], v[206:209], v[38:41]
	v_mfma_f32_16x16x32_bf16 v[30:33], v[146:149], v[214:217], v[30:33]
	v_mfma_f32_16x16x32_bf16 v[22:25], v[154:157], v[214:217], v[22:25]
	v_mfma_f32_16x16x32_bf16 v[14:17], v[146:149], v[222:225], v[14:17]
	v_mfma_f32_16x16x32_bf16 v[6:9], v[154:157], v[222:225], v[6:9]
	v_mfma_f32_16x16x32_bf16 v[62:65], v[150:153], v[202:205], v[62:65]
	v_mfma_f32_16x16x32_bf16 v[54:57], v[158:161], v[202:205], v[54:57]
	v_mfma_f32_16x16x32_bf16 v[46:49], v[150:153], v[210:213], v[46:49]
	v_mfma_f32_16x16x32_bf16 v[38:41], v[158:161], v[210:213], v[38:41]
	v_mfma_f32_16x16x32_bf16 v[30:33], v[150:153], v[218:221], v[30:33]
	v_mfma_f32_16x16x32_bf16 v[22:25], v[158:161], v[218:221], v[22:25]
	v_mfma_f32_16x16x32_bf16 v[14:17], v[150:153], v[226:229], v[14:17]
	v_mfma_f32_16x16x32_bf16 v[6:9], v[158:161], v[226:229], v[6:9]
	s_setprio 0
	s_setprio 1
	v_mfma_f32_16x16x32_bf16 v[58:61], v[162:165], v[198:201], v[58:61]
	v_mfma_f32_16x16x32_bf16 v[50:53], v[190:193], v[198:201], v[50:53]
	v_mfma_f32_16x16x32_bf16 v[42:45], v[162:165], v[206:209], v[42:45]
	v_mfma_f32_16x16x32_bf16 v[34:37], v[190:193], v[206:209], v[34:37]
	v_mfma_f32_16x16x32_bf16 v[26:29], v[162:165], v[214:217], v[26:29]
	v_mfma_f32_16x16x32_bf16 v[18:21], v[190:193], v[214:217], v[18:21]
	v_mfma_f32_16x16x32_bf16 v[10:13], v[162:165], v[222:225], v[10:13]
	v_mfma_f32_16x16x32_bf16 v[2:5], v[190:193], v[222:225], v[2:5]
	v_mfma_f32_16x16x32_bf16 v[58:61], v[166:169], v[202:205], v[58:61]
	v_mfma_f32_16x16x32_bf16 v[50:53], v[194:197], v[202:205], v[50:53]
	v_mfma_f32_16x16x32_bf16 v[42:45], v[166:169], v[210:213], v[42:45]
	v_mfma_f32_16x16x32_bf16 v[34:37], v[194:197], v[210:213], v[34:37]
	v_mfma_f32_16x16x32_bf16 v[26:29], v[166:169], v[218:221], v[26:29]
	v_mfma_f32_16x16x32_bf16 v[18:21], v[194:197], v[218:221], v[18:21]
	v_mfma_f32_16x16x32_bf16 v[10:13], v[166:169], v[226:229], v[10:13]
	v_mfma_f32_16x16x32_bf16 v[2:5], v[194:197], v[226:229], v[2:5]
	s_setprio 0
	s_barrier
	s_add_u32 s68, s68, 0x100
	s_addc_u32 s69, s69, 0
	s_add_u32 s93, s93, 0x100
	s_addc_u32 vcc_lo, vcc_lo, 0
	s_cmp_ge_i32 vcc_hi, s37
	s_mov_b32 s4, vcc_hi
	s_cbranch_scc0 .LBB0_441
	s_branch .Lk3_exit

; #define PG8_WAIT_V(n) asm volatile("s_waitcnt vmcnt(" #n ")" ::: "memory")
; #define PG8_BAR __builtin_amdgcn_s_barrier()
; template <class Epi>
; __device__ __forceinline__ void gemm_phase(LAS unsigned char* lds, const Gemm g, const Epi& E) {
;     ...
;         const char* nA = has_next ? (const char*)((nxt.sub & 1) ? g.A1 : g.A0) + (size_t)nxt.pm * tstep + (size_t)nxt.kt0 * kstep : cA; const char* nB = has_next ? (const char*)((nxt.sub & 1) ? g.B1 : g.B0) + (size_t)nxt.pn * tstep + (size_t)nxt.kt0 * kstep : cB;
;         const int nt = cur.nt;
;         for (int t = 0; t < nt; t += 2) {
;             const bool last = (t == nt - 2);
;             const char* a1 = cA + (size_t)(t + 1) * kstep;
;             const char* a2 = last ? nA : cA + (size_t)(t + 2) * kstep; const char* b2 = last ? nB : cB + (size_t)(t + 2) * kstep;
;             const char* a3 = a2 + kstep; const char* b3 = b2 + kstep;
;             PG8_LDB(B0, 0, 0); PG8_LDB(B1, 0, 1); PG8_SCHED; PG8_LDA(At, 0, 0); PG8_STAGE(PG8_SA(1, 1), a1 + hstep, voffA);
;             PG8_WAIT_V(8); PG8_WAIT_L(0); PG8_BAR; PG8_MMA(0, 0, At, B0); PG8_MMA(0, 1, At, B1); PG8_BAR; PG8_SCHED;
;             PG8_LDA(At, 0, 1); PG8_STAGE(PG8_SB(0, 0), b2, voffA); PG8_STAGE(PG8_SB(0, 1), b2 + hstep, voffA); PG8_STAGE(PG8_SA(0, 0), a2, voffA);
;             PG8_WAIT_V(8); PG8_WAIT_L(0); PG8_BAR; PG8_MMA(1, 0, At, B0); PG8_MMA(1, 1, At, B1); PG8_BAR; PG8_SCHED;
;             PG8_LDB(B0, 1, 0); PG8_LDB(B1, 1, 1); PG8_SCHED; PG8_LDA(At, 1, 0); PG8_STAGE(PG8_SA(0, 1), a2 + hstep, voffA);
;             PG8_WAIT_V(8); PG8_WAIT_L(0); PG8_BAR; PG8_MMA(0, 0, At, B0); PG8_MMA(0, 1, At, B1); PG8_BAR; PG8_SCHED;
;             PG8_LDA(At, 1, 1); PG8_STAGE(PG8_SB(1, 0), b3, voffA); PG8_STAGE(PG8_SB(1, 1), b3 + hstep, voffA); PG8_STAGE(PG8_SA(1, 0), a3, voffA);
;             PG8_WAIT_V(8); PG8_WAIT_L(0); PG8_BAR; PG8_MMA(1, 0, At, B0); PG8_MMA(1, 1, At, B1); PG8_BAR; PG8_SCHED;
;         }
;         if (wr == 0) PG8_BAR;
;         E(acc, cur, wr, wc, fr, fq);
;         if (!has_next) break;
;         if (!(Epi::KEEP && cur.sub == 0))
; #pragma unroll
;         for (int a = 0; a < 2; ++a)
; #pragma unroll
;             for (int b = 0; b < 2; ++b)
; #pragma unroll
;                 for (int m = 0; m < 4; ++m)
; #pragma unroll
;                     for (int n = 0; n < 2; ++n) acc[a][b][m][n] = (f32x4){0.f, 0.f, 0.f, 0.f};
.LBB0_439:
	s_ashr_i32 s15, s14, 31
	s_lshl_b64 s[58:59], s[14:15], 19
	s_add_u32 s15, s35, s58
	s_addc_u32 s55, s28, s59
	s_ashr_i32 s57, s56, 31
	s_lshl_b64 s[62:63], s[56:57], 7
	s_add_u32 s58, s15, s62
	s_addc_u32 s59, s55, s63
	s_ashr_i32 s55, s54, 31
	s_lshl_b64 s[70:71], s[54:55], 19
	s_add_u32 s15, s20, s70
	s_addc_u32 s55, s26, s71
	s_add_u32 s62, s15, s62
	s_addc_u32 s63, s55, s63
	s_cmp_lt_i32 s37, 1
	s_cbranch_scc1 .LBB0_449
	s_and_b64 s[70:71], s[66:67], exec
	s_cselect_b32 s15, s59, s69
	s_cselect_b32 s55, s58, s68
	s_cselect_b32 s57, s63, s5
	s_cselect_b32 s82, s62, s4
	s_add_i32 s92, s37, -2
	s_add_u32 s68, s68, 0x40080
	s_addc_u32 s69, s69, 0
	s_add_u32 s93, s4, 0x100
	v_mov_b32_e32 v2, 0
	s_addc_u32 vcc_lo, s5, 0
	s_mov_b32 s4, 0
	v_mov_b32_e32 v3, v2
	v_mov_b32_e32 v4, v2
	v_mov_b32_e32 v5, v2
	v_mov_b32_e32 v10, v2
	v_mov_b32_e32 v11, v2
	v_mov_b32_e32 v12, v2
	v_mov_b32_e32 v13, v2
	v_mov_b32_e32 v18, v2
	v_mov_b32_e32 v19, v2
	v_mov_b32_e32 v20, v2
	v_mov_b32_e32 v21, v2
	v_mov_b32_e32 v26, v2
	v_mov_b32_e32 v27, v2
	v_mov_b32_e32 v28, v2
	v_mov_b32_e32 v29, v2
	v_mov_b32_e32 v34, v2
	v_mov_b32_e32 v35, v2
	v_mov_b32_e32 v36, v2
	v_mov_b32_e32 v37, v2
	v_mov_b32_e32 v42, v2
	v_mov_b32_e32 v43, v2
	v_mov_b32_e32 v44, v2
	v_mov_b32_e32 v45, v2
	v_mov_b32_e32 v50, v2
	v_mov_b32_e32 v51, v2
	v_mov_b32_e32 v52, v2
	v_mov_b32_e32 v53, v2
	v_mov_b32_e32 v58, v2
	v_mov_b32_e32 v59, v2
	v_mov_b32_e32 v60, v2
	v_mov_b32_e32 v61, v2
	v_mov_b32_e32 v6, v2
	v_mov_b32_e32 v7, v2
	v_mov_b32_e32 v8, v2
	v_mov_b32_e32 v9, v2
	v_mov_b32_e32 v14, v2
	v_mov_b32_e32 v15, v2
	v_mov_b32_e32 v16, v2
	v_mov_b32_e32 v17, v2
	v_mov_b32_e32 v22, v2
	v_mov_b32_e32 v23, v2
	v_mov_b32_e32 v24, v2
	v_mov_b32_e32 v25, v2
	v_mov_b32_e32 v30, v2
	v_mov_b32_e32 v31, v2
	v_mov_b32_e32 v32, v2
	v_mov_b32_e32 v33, v2
	v_mov_b32_e32 v38, v2
	v_mov_b32_e32 v39, v2
	v_mov_b32_e32 v40, v2
	v_mov_b32_e32 v41, v2
	v_mov_b32_e32 v46, v2
	v_mov_b32_e32 v47, v2
	v_mov_b32_e32 v48, v2
	v_mov_b32_e32 v49, v2
	v_mov_b32_e32 v54, v2
	v_mov_b32_e32 v55, v2
	v_mov_b32_e32 v56, v2
	v_mov_b32_e32 v57, v2
	v_mov_b32_e32 v62, v2
	v_mov_b32_e32 v63, v2
	v_mov_b32_e32 v64, v2
	v_mov_b32_e32 v65, v2
	v_mov_b32_e32 v66, v2
	v_mov_b32_e32 v67, v2
	v_mov_b32_e32 v68, v2
	v_mov_b32_e32 v69, v2
	v_mov_b32_e32 v74, v2
	v_mov_b32_e32 v75, v2
	v_mov_b32_e32 v76, v2
	v_mov_b32_e32 v77, v2
	v_mov_b32_e32 v82, v2
	v_mov_b32_e32 v83, v2
	v_mov_b32_e32 v84, v2
	v_mov_b32_e32 v85, v2
	v_mov_b32_e32 v90, v2
	v_mov_b32_e32 v91, v2
	v_mov_b32_e32 v92, v2
	v_mov_b32_e32 v93, v2
	v_mov_b32_e32 v98, v2
	v_mov_b32_e32 v99, v2
	v_mov_b32_e32 v100, v2
	v_mov_b32_e32 v101, v2
	v_mov_b32_e32 v106, v2
	v_mov_b32_e32 v107, v2
	v_mov_b32_e32 v108, v2
	v_mov_b32_e32 v109, v2
	v_mov_b32_e32 v114, v2
	v_mov_b32_e32 v115, v2
	v_mov_b32_e32 v116, v2
	v_mov_b32_e32 v117, v2
	v_mov_b32_e32 v122, v2
	v_mov_b32_e32 v123, v2
	v_mov_b32_e32 v124, v2
	v_mov_b32_e32 v125, v2
	v_mov_b32_e32 v70, v2
	v_mov_b32_e32 v71, v2
	v_mov_b32_e32 v72, v2
	v_mov_b32_e32 v73, v2
	v_mov_b32_e32 v78, v2
	v_mov_b32_e32 v79, v2
	v_mov_b32_e32 v80, v2
	v_mov_b32_e32 v81, v2
	v_mov_b32_e32 v86, v2
	v_mov_b32_e32 v87, v2
	v_mov_b32_e32 v88, v2
	v_mov_b32_e32 v89, v2
	v_mov_b32_e32 v94, v2
	v_mov_b32_e32 v95, v2
	v_mov_b32_e32 v96, v2
	v_mov_b32_e32 v97, v2
	v_mov_b32_e32 v102, v2
	v_mov_b32_e32 v103, v2
	v_mov_b32_e32 v104, v2
	v_mov_b32_e32 v105, v2
	v_mov_b32_e32 v110, v2
	v_mov_b32_e32 v111, v2
	v_mov_b32_e32 v112, v2
	v_mov_b32_e32 v113, v2
	v_mov_b32_e32 v118, v2
	v_mov_b32_e32 v119, v2
	v_mov_b32_e32 v120, v2
	v_mov_b32_e32 v121, v2
	v_mov_b32_e32 v126, v2
	v_mov_b32_e32 v127, v2
	v_mov_b32_e32 v128, v2
	v_mov_b32_e32 v129, v2
	s_cmp_lg_u32 s32, 0
	s_cbranch_scc1 .Lk3_peel

; #define PG8_BAR __builtin_amdgcn_s_barrier()
; template <class Epi>
; __device__ __forceinline__ void gemm_phase(LAS unsigned char* lds, const Gemm g, const Epi& E) {
;     ...
;         if (wr == 0) PG8_BAR;
.Lk3_exit:
	s_and_b64 vcc, exec, s[12:13]
	s_cbranch_vccz .LBB0_444

; __device__ __forceinline__ unsigned pk2(float lo, float hi) { const f32x2_t v = {lo, hi}; const bf16v2_t b = __builtin_convertvector(v, bf16v2_t); return __builtin_bit_cast(unsigned, b); }
; __device__ __forceinline__ float siluf_(float x) { return x * sigmoidf_(x); }
;     __device__ __forceinline__ void operator()(const AccT& acc, const pg8::Unit& u, int wr, int wc, int fr_, int fq_) const {
;     ...
; #pragma unroll
;             for (int m = 0; m < 4; ++m) {
;                 const f32x4 u0 = acc[ai][0][m][0], u1 = acc[ai][0][m][1], v0 = acc[ai][1][m][0], v1 = acc[ai][1][m][1];
;                 u32x4 o;
;                 o[0] = pk2(siluf_(u0[0]) * v0[0], siluf_(u0[1]) * v0[1]); o[1] = pk2(siluf_(u0[2]) * v0[2], siluf_(u0[3]) * v0[3]);
;                 o[2] = pk2(siluf_(u1[0]) * v1[0], siluf_(u1[1]) * v1[1]); o[3] = pk2(siluf_(u1[2]) * v1[2], siluf_(u1[3]) * v1[3]);
;                 *(u32x4*)(H + (size_t)(row0 + ai * 128 + m * 16) * FH) = o;
.LBB0_444:
	s_mov_b32 s32, 1
	v_mul_f32_e32 v147, 0xbfb8aa3b, v126
	v_exp_f32_e32 v147, v147
	s_lshl_b32 s4, s6, 8
	v_mov_b32_e32 v136, v141
	v_mov_b32_e32 v137, v143
	v_add_f32_e32 v147, 1.0, v147
	v_rcp_f32_e32 v148, v147
	v_mul_f32_e32 v147, 0xbfb8aa3b, v127
	v_exp_f32_e32 v147, v147
	s_add_i32 s4, s4, s53
	v_add_f32_e32 v147, 1.0, v147
	v_rcp_f32_e32 v149, v147
	v_add_u32_e32 v146, s4, v136
	s_lshl_b32 s4, s8, 7
	s_ashr_i32 s5, s4, 31
	v_pk_mul_f32 v[126:127], v[126:127], v[148:149]
	s_lshl_b64 s[4:5], s[4:5], 1
	v_pk_mul_f32 v[122:123], v[122:123], v[126:127]
	s_add_u32 s4, s77, s4
	v_cvt_pk_bf16_f32 v122, v122, v123
	v_mul_f32_e32 v123, 0xbfb8aa3b, v128
	v_exp_f32_e32 v123, v123
	v_lshlrev_b32_e32 v136, 3, v137
	s_addc_u32 s5, s78, s5
	v_ashrrev_i32_e32 v137, 31, v136
	v_add_f32_e32 v123, 1.0, v123
	v_rcp_f32_e32 v126, v123
	v_mul_f32_e32 v123, 0xbfb8aa3b, v129
	v_exp_f32_e32 v123, v123
	v_lshl_add_u64 v[136:137], v[136:137], 1, s[4:5]
	s_andn2_b64 vcc, exec, s[66:67]
	v_add_f32_e32 v123, 1.0, v123
	v_rcp_f32_e32 v127, v123
	s_nop 0
	v_pk_mul_f32 v[126:127], v[128:129], v[126:127]
	s_nop 0
	v_pk_mul_f32 v[124:125], v[124:125], v[126:127]
	s_nop 0
	v_cvt_pk_bf16_f32 v123, v124, v125
	v_mul_f32_e32 v124, 0xbfb8aa3b, v118
	v_mul_f32_e32 v125, 0xbfb8aa3b, v119
	v_exp_f32_e32 v124, v124
	v_exp_f32_e32 v125, v125
	v_add_f32_e32 v124, 1.0, v124
	v_add_f32_e32 v125, 1.0, v125
	v_rcp_f32_e32 v124, v124
	v_rcp_f32_e32 v125, v125
	s_nop 0
	v_pk_mul_f32 v[118:119], v[118:119], v[124:125]
	s_nop 0
	v_pk_mul_f32 v[114:115], v[114:115], v[118:119]
	s_nop 0
	v_cvt_pk_bf16_f32 v124, v114, v115
	v_mul_f32_e32 v114, 0xbfb8aa3b, v120
	v_mul_f32_e32 v115, 0xbfb8aa3b, v121
	v_exp_f32_e32 v114, v114
	v_exp_f32_e32 v115, v115
	v_add_f32_e32 v114, 1.0, v114
	v_add_f32_e32 v115, 1.0, v115
	v_rcp_f32_e32 v114, v114
	v_rcp_f32_e32 v115, v115
	s_nop 0
	v_pk_mul_f32 v[114:115], v[120:121], v[114:115]
	s_nop 0
	v_pk_mul_f32 v[114:115], v[116:117], v[114:115]
	s_nop 0
	v_cvt_pk_bf16_f32 v125, v114, v115
	v_mad_i64_i32 v[114:115], s[4:5], v146, s24, v[136:137]
	global_store_dwordx4 v[114:115], v[122:125], off
	v_mul_f32_e32 v114, 0xbfb8aa3b, v110
	v_mul_f32_e32 v115, 0xbfb8aa3b, v111
	v_exp_f32_e32 v114, v114
	v_exp_f32_e32 v115, v115
	v_add_f32_e32 v114, 1.0, v114
	v_add_f32_e32 v115, 1.0, v115
	v_rcp_f32_e32 v114, v114
	v_rcp_f32_e32 v115, v115
	s_nop 0
	v_pk_mul_f32 v[110:111], v[110:111], v[114:115]
	s_nop 0
	v_pk_mul_f32 v[106:107], v[106:107], v[110:111]
	s_nop 0
	v_cvt_pk_bf16_f32 v106, v106, v107
	v_mul_f32_e32 v107, 0xbfb8aa3b, v112
	v_exp_f32_e32 v107, v107
	s_nop 0
	v_add_f32_e32 v107, 1.0, v107
	v_rcp_f32_e32 v110, v107
	v_mul_f32_e32 v107, 0xbfb8aa3b, v113
	v_exp_f32_e32 v107, v107
	s_nop 0
	v_add_f32_e32 v107, 1.0, v107
	v_rcp_f32_e32 v111, v107
	s_nop 0
	v_pk_mul_f32 v[110:111], v[112:113], v[110:111]
	s_nop 0
	v_pk_mul_f32 v[108:109], v[108:109], v[110:111]
	s_nop 0
	v_cvt_pk_bf16_f32 v107, v108, v109
	v_mul_f32_e32 v108, 0xbfb8aa3b, v102
	v_mul_f32_e32 v109, 0xbfb8aa3b, v103
	v_exp_f32_e32 v108, v108
	v_exp_f32_e32 v109, v109
	v_add_f32_e32 v108, 1.0, v108
	v_add_f32_e32 v109, 1.0, v109
	v_rcp_f32_e32 v108, v108
	v_rcp_f32_e32 v109, v109
	s_nop 0
	v_pk_mul_f32 v[102:103], v[102:103], v[108:109]
	s_nop 0
	v_pk_mul_f32 v[98:99], v[98:99], v[102:103]
	s_nop 0
	v_cvt_pk_bf16_f32 v108, v98, v99
	v_mul_f32_e32 v98, 0xbfb8aa3b, v104
	v_mul_f32_e32 v99, 0xbfb8aa3b, v105
	v_exp_f32_e32 v98, v98
	v_exp_f32_e32 v99, v99
	v_add_f32_e32 v98, 1.0, v98
	v_add_f32_e32 v99, 1.0, v99
	v_rcp_f32_e32 v98, v98
	v_rcp_f32_e32 v99, v99
	s_nop 0
	v_pk_mul_f32 v[98:99], v[104:105], v[98:99]
	s_nop 0
	v_pk_mul_f32 v[98:99], v[100:101], v[98:99]
	s_nop 0
	v_cvt_pk_bf16_f32 v109, v98, v99
	v_add_u32_e32 v98, 16, v146
	v_mad_i64_i32 v[98:99], s[4:5], v98, s24, v[136:137]
	global_store_dwordx4 v[98:99], v[106:109], off
	v_mul_f32_e32 v98, 0xbfb8aa3b, v94
	v_mul_f32_e32 v99, 0xbfb8aa3b, v95
	v_exp_f32_e32 v98, v98
	v_exp_f32_e32 v99, v99
	v_add_f32_e32 v98, 1.0, v98
	v_add_f32_e32 v99, 1.0, v99
	v_rcp_f32_e32 v98, v98
	v_rcp_f32_e32 v99, v99
	s_nop 0
	v_pk_mul_f32 v[94:95], v[94:95], v[98:99]
	s_nop 0
	v_pk_mul_f32 v[90:91], v[90:91], v[94:95]
	s_nop 0
	v_cvt_pk_bf16_f32 v90, v90, v91
	v_mul_f32_e32 v91, 0xbfb8aa3b, v96
	v_exp_f32_e32 v91, v91
	s_nop 0
	v_add_f32_e32 v91, 1.0, v91
	v_rcp_f32_e32 v94, v91
	v_mul_f32_e32 v91, 0xbfb8aa3b, v97
	v_exp_f32_e32 v91, v91
	s_nop 0
	v_add_f32_e32 v91, 1.0, v91
	v_rcp_f32_e32 v95, v91
	s_nop 0
	v_pk_mul_f32 v[94:95], v[96:97], v[94:95]
	s_nop 0
	v_pk_mul_f32 v[92:93], v[92:93], v[94:95]
	s_nop 0
	v_cvt_pk_bf16_f32 v91, v92, v93
	v_mul_f32_e32 v92, 0xbfb8aa3b, v86
	v_mul_f32_e32 v93, 0xbfb8aa3b, v87
	v_exp_f32_e32 v92, v92
	v_exp_f32_e32 v93, v93
	v_add_f32_e32 v92, 1.0, v92
	v_add_f32_e32 v93, 1.0, v93
	v_rcp_f32_e32 v92, v92
	v_rcp_f32_e32 v93, v93
	s_nop 0
	v_pk_mul_f32 v[86:87], v[86:87], v[92:93]
	s_nop 0
	v_pk_mul_f32 v[82:83], v[82:83], v[86:87]
	s_nop 0
	v_cvt_pk_bf16_f32 v92, v82, v83
	v_mul_f32_e32 v82, 0xbfb8aa3b, v88
	v_mul_f32_e32 v83, 0xbfb8aa3b, v89
	v_exp_f32_e32 v82, v82
	v_exp_f32_e32 v83, v83
	v_add_f32_e32 v82, 1.0, v82
	v_add_f32_e32 v83, 1.0, v83
	v_rcp_f32_e32 v82, v82
	v_rcp_f32_e32 v83, v83
	s_nop 0
	v_pk_mul_f32 v[82:83], v[88:89], v[82:83]
	s_nop 0
	v_pk_mul_f32 v[82:83], v[84:85], v[82:83]
	s_nop 0
	v_cvt_pk_bf16_f32 v93, v82, v83
	v_add_u32_e32 v82, 32, v146
	v_mad_i64_i32 v[82:83], s[4:5], v82, s24, v[136:137]
	global_store_dwordx4 v[82:83], v[90:93], off
	v_mul_f32_e32 v82, 0xbfb8aa3b, v78
	v_mul_f32_e32 v83, 0xbfb8aa3b, v79
	v_exp_f32_e32 v82, v82
	v_exp_f32_e32 v83, v83
	v_add_f32_e32 v82, 1.0, v82
; __device__ __forceinline__ unsigned pk2(float lo, float hi) { const f32x2_t v = {lo, hi}; const bf16v2_t b = __builtin_convertvector(v, bf16v2_t); return __builtin_bit_cast(unsigned, b); }
; __device__ __forceinline__ float siluf_(float x) { return x * sigmoidf_(x); }
;     __device__ __forceinline__ void operator()(const AccT& acc, const pg8::Unit& u, int wr, int wc, int fr_, int fq_) const {
;     ...
; #pragma unroll
;             for (int m = 0; m < 4; ++m) {
;                 const f32x4 u0 = acc[ai][0][m][0], u1 = acc[ai][0][m][1], v0 = acc[ai][1][m][0], v1 = acc[ai][1][m][1];
;                 u32x4 o;
;                 o[0] = pk2(siluf_(u0[0]) * v0[0], siluf_(u0[1]) * v0[1]); o[1] = pk2(siluf_(u0[2]) * v0[2], siluf_(u0[3]) * v0[3]);
;                 o[2] = pk2(siluf_(u1[0]) * v1[0], siluf_(u1[1]) * v1[1]); o[3] = pk2(siluf_(u1[2]) * v1[2], siluf_(u1[3]) * v1[3]);
;                 *(u32x4*)(H + (size_t)(row0 + ai * 128 + m * 16) * FH) = o;
	v_add_f32_e32 v83, 1.0, v83
	v_rcp_f32_e32 v82, v82
	v_rcp_f32_e32 v83, v83
	s_nop 0
	v_pk_mul_f32 v[78:79], v[78:79], v[82:83]
	s_nop 0
	v_pk_mul_f32 v[74:75], v[74:75], v[78:79]
	s_nop 0
	v_cvt_pk_bf16_f32 v74, v74, v75
	v_mul_f32_e32 v75, 0xbfb8aa3b, v80
	v_exp_f32_e32 v75, v75
	s_nop 0
	v_add_f32_e32 v75, 1.0, v75
	v_rcp_f32_e32 v78, v75
	v_mul_f32_e32 v75, 0xbfb8aa3b, v81
	v_exp_f32_e32 v75, v75
	s_nop 0
	v_add_f32_e32 v75, 1.0, v75
	v_rcp_f32_e32 v79, v75
	s_nop 0
	v_pk_mul_f32 v[78:79], v[80:81], v[78:79]
	s_nop 0
	v_pk_mul_f32 v[76:77], v[76:77], v[78:79]
	s_nop 0
	v_cvt_pk_bf16_f32 v75, v76, v77
	v_mul_f32_e32 v76, 0xbfb8aa3b, v70
	v_mul_f32_e32 v77, 0xbfb8aa3b, v71
	v_exp_f32_e32 v76, v76
	v_exp_f32_e32 v77, v77
	v_add_f32_e32 v76, 1.0, v76
	v_add_f32_e32 v77, 1.0, v77
	v_rcp_f32_e32 v76, v76
	v_rcp_f32_e32 v77, v77
	s_nop 0
	v_pk_mul_f32 v[70:71], v[70:71], v[76:77]
	s_nop 0
	v_pk_mul_f32 v[66:67], v[66:67], v[70:71]
	s_nop 0
	v_cvt_pk_bf16_f32 v76, v66, v67
	v_mul_f32_e32 v66, 0xbfb8aa3b, v72
	v_mul_f32_e32 v67, 0xbfb8aa3b, v73
	v_exp_f32_e32 v66, v66
	v_exp_f32_e32 v67, v67
	v_add_f32_e32 v66, 1.0, v66
	v_add_f32_e32 v67, 1.0, v67
	v_rcp_f32_e32 v66, v66
	v_rcp_f32_e32 v67, v67
	s_nop 0
	v_pk_mul_f32 v[66:67], v[72:73], v[66:67]
	s_nop 0
	v_pk_mul_f32 v[66:67], v[68:69], v[66:67]
	v_add_u32_e32 v68, 0x80, v146
	v_cvt_pk_bf16_f32 v77, v66, v67
	v_add_u32_e32 v66, 48, v146
	v_mad_i64_i32 v[66:67], s[4:5], v66, s24, v[136:137]
	global_store_dwordx4 v[66:67], v[74:77], off
	v_mul_f32_e32 v66, 0xbfb8aa3b, v62
	v_mul_f32_e32 v67, 0xbfb8aa3b, v63
	v_exp_f32_e32 v66, v66
	v_exp_f32_e32 v67, v67
	v_add_f32_e32 v66, 1.0, v66
	v_add_f32_e32 v67, 1.0, v67
	v_rcp_f32_e32 v66, v66
	v_rcp_f32_e32 v67, v67
	s_nop 0
	v_pk_mul_f32 v[62:63], v[62:63], v[66:67]
	s_nop 0
	v_pk_mul_f32 v[58:59], v[58:59], v[62:63]
	s_nop 0
	v_cvt_pk_bf16_f32 v58, v58, v59
	v_mul_f32_e32 v59, 0xbfb8aa3b, v64
	v_exp_f32_e32 v59, v59
	s_nop 0
	v_add_f32_e32 v59, 1.0, v59
	v_rcp_f32_e32 v62, v59
	v_mul_f32_e32 v59, 0xbfb8aa3b, v65
	v_exp_f32_e32 v59, v59
	s_nop 0
	v_add_f32_e32 v59, 1.0, v59
	v_rcp_f32_e32 v63, v59
	s_nop 0
	v_pk_mul_f32 v[62:63], v[64:65], v[62:63]
	s_nop 0
	v_pk_mul_f32 v[60:61], v[60:61], v[62:63]
	s_nop 0
	v_cvt_pk_bf16_f32 v59, v60, v61
	v_mul_f32_e32 v60, 0xbfb8aa3b, v54
	v_mul_f32_e32 v61, 0xbfb8aa3b, v55
	v_exp_f32_e32 v60, v60
	v_exp_f32_e32 v61, v61
	v_add_f32_e32 v60, 1.0, v60
	v_add_f32_e32 v61, 1.0, v61
	v_rcp_f32_e32 v60, v60
	v_rcp_f32_e32 v61, v61
	s_nop 0
	v_pk_mul_f32 v[54:55], v[54:55], v[60:61]
	s_nop 0
	v_pk_mul_f32 v[50:51], v[50:51], v[54:55]
	s_nop 0
	v_cvt_pk_bf16_f32 v60, v50, v51
	v_mul_f32_e32 v50, 0xbfb8aa3b, v56
	v_mul_f32_e32 v51, 0xbfb8aa3b, v57
	v_exp_f32_e32 v50, v50
	v_exp_f32_e32 v51, v51
	v_add_f32_e32 v50, 1.0, v50
	v_add_f32_e32 v51, 1.0, v51
	v_rcp_f32_e32 v50, v50
	v_rcp_f32_e32 v51, v51
	s_nop 0
	v_pk_mul_f32 v[50:51], v[56:57], v[50:51]
	s_nop 0
	v_pk_mul_f32 v[50:51], v[52:53], v[50:51]
	s_nop 0
	v_cvt_pk_bf16_f32 v61, v50, v51
	v_mad_i64_i32 v[50:51], s[4:5], v68, s24, v[136:137]
	global_store_dwordx4 v[50:51], v[58:61], off
	v_mul_f32_e32 v50, 0xbfb8aa3b, v46
	v_mul_f32_e32 v51, 0xbfb8aa3b, v47
	v_exp_f32_e32 v50, v50
	v_exp_f32_e32 v51, v51
	v_add_f32_e32 v50, 1.0, v50
	v_add_f32_e32 v51, 1.0, v51
	v_rcp_f32_e32 v50, v50
	v_rcp_f32_e32 v51, v51
	s_nop 0
	v_pk_mul_f32 v[46:47], v[46:47], v[50:51]
	s_nop 0
	v_pk_mul_f32 v[42:43], v[42:43], v[46:47]
	s_nop 0
	v_cvt_pk_bf16_f32 v42, v42, v43
	v_mul_f32_e32 v43, 0xbfb8aa3b, v48
	v_exp_f32_e32 v43, v43
	s_nop 0
	v_add_f32_e32 v43, 1.0, v43
	v_rcp_f32_e32 v46, v43
	v_mul_f32_e32 v43, 0xbfb8aa3b, v49
	v_exp_f32_e32 v43, v43
	s_nop 0
	v_add_f32_e32 v43, 1.0, v43
	v_rcp_f32_e32 v47, v43
	s_nop 0
	v_pk_mul_f32 v[46:47], v[48:49], v[46:47]
	s_nop 0
	v_pk_mul_f32 v[44:45], v[44:45], v[46:47]
	s_nop 0
	v_cvt_pk_bf16_f32 v43, v44, v45
	v_mul_f32_e32 v44, 0xbfb8aa3b, v38
	v_mul_f32_e32 v45, 0xbfb8aa3b, v39
	v_exp_f32_e32 v44, v44
	v_exp_f32_e32 v45, v45
	v_add_f32_e32 v44, 1.0, v44
	v_add_f32_e32 v45, 1.0, v45
	v_rcp_f32_e32 v44, v44
	v_rcp_f32_e32 v45, v45
	s_nop 0
	v_pk_mul_f32 v[38:39], v[38:39], v[44:45]
	s_nop 0
	v_pk_mul_f32 v[34:35], v[34:35], v[38:39]
; __device__ __forceinline__ unsigned pk2(float lo, float hi) { const f32x2_t v = {lo, hi}; const bf16v2_t b = __builtin_convertvector(v, bf16v2_t); return __builtin_bit_cast(unsigned, b); }
; __device__ __forceinline__ float siluf_(float x) { return x * sigmoidf_(x); }
; template <class Epi>
; __device__ __forceinline__ void gemm_phase(LAS unsigned char* lds, const Gemm g, const Epi& E) {
;     ...
;         E(acc, cur, wr, wc, fr, fq);
;         if (!has_next) break;
;         if (!(Epi::KEEP && cur.sub == 0))
; #pragma unroll
;         for (int a = 0; a < 2; ++a)
; #pragma unroll
;             for (int b = 0; b < 2; ++b)
; #pragma unroll
;                 for (int m = 0; m < 4; ++m)
; #pragma unroll
;                     for (int n = 0; n < 2; ++n) acc[a][b][m][n] = (f32x4){0.f, 0.f, 0.f, 0.f};
;         ++ui; get_unit(lds, ui, cur); cA = nA; cB = nB;
;     __device__ __forceinline__ void operator()(const AccT& acc, const pg8::Unit& u, int wr, int wc, int fr_, int fq_) const {
;     ...
; #pragma unroll
;             for (int m = 0; m < 4; ++m) {
;                 const f32x4 u0 = acc[ai][0][m][0], u1 = acc[ai][0][m][1], v0 = acc[ai][1][m][0], v1 = acc[ai][1][m][1];
;                 u32x4 o;
;                 o[0] = pk2(siluf_(u0[0]) * v0[0], siluf_(u0[1]) * v0[1]); o[1] = pk2(siluf_(u0[2]) * v0[2], siluf_(u0[3]) * v0[3]);
;                 o[2] = pk2(siluf_(u1[0]) * v1[0], siluf_(u1[1]) * v1[1]); o[3] = pk2(siluf_(u1[2]) * v1[2], siluf_(u1[3]) * v1[3]);
;                 *(u32x4*)(H + (size_t)(row0 + ai * 128 + m * 16) * FH) = o;
	s_nop 0
	v_cvt_pk_bf16_f32 v44, v34, v35
	v_mul_f32_e32 v34, 0xbfb8aa3b, v40
	v_mul_f32_e32 v35, 0xbfb8aa3b, v41
	v_exp_f32_e32 v34, v34
	v_exp_f32_e32 v35, v35
	v_add_f32_e32 v34, 1.0, v34
	v_add_f32_e32 v35, 1.0, v35
	v_rcp_f32_e32 v34, v34
	v_rcp_f32_e32 v35, v35
	s_nop 0
	v_pk_mul_f32 v[34:35], v[40:41], v[34:35]
	s_nop 0
	v_pk_mul_f32 v[34:35], v[36:37], v[34:35]
	s_nop 0
	v_cvt_pk_bf16_f32 v45, v34, v35
	v_add_u32_e32 v34, 0x90, v146
	v_mad_i64_i32 v[34:35], s[4:5], v34, s24, v[136:137]
	global_store_dwordx4 v[34:35], v[42:45], off
	v_mul_f32_e32 v34, 0xbfb8aa3b, v30
	v_mul_f32_e32 v35, 0xbfb8aa3b, v31
	v_exp_f32_e32 v34, v34
	v_exp_f32_e32 v35, v35
	v_add_f32_e32 v34, 1.0, v34
	v_add_f32_e32 v35, 1.0, v35
	v_rcp_f32_e32 v34, v34
	v_rcp_f32_e32 v35, v35
	s_nop 0
	v_pk_mul_f32 v[30:31], v[30:31], v[34:35]
	s_nop 0
	v_pk_mul_f32 v[26:27], v[26:27], v[30:31]
	s_nop 0
	v_cvt_pk_bf16_f32 v26, v26, v27
	v_mul_f32_e32 v27, 0xbfb8aa3b, v32
	v_exp_f32_e32 v27, v27
	s_nop 0
	v_add_f32_e32 v27, 1.0, v27
	v_rcp_f32_e32 v30, v27
	v_mul_f32_e32 v27, 0xbfb8aa3b, v33
	v_exp_f32_e32 v27, v27
	s_nop 0
	v_add_f32_e32 v27, 1.0, v27
	v_rcp_f32_e32 v31, v27
	s_nop 0
	v_pk_mul_f32 v[30:31], v[32:33], v[30:31]
	s_nop 0
	v_pk_mul_f32 v[28:29], v[28:29], v[30:31]
	s_nop 0
	v_cvt_pk_bf16_f32 v27, v28, v29
	v_mul_f32_e32 v28, 0xbfb8aa3b, v22
	v_mul_f32_e32 v29, 0xbfb8aa3b, v23
	v_exp_f32_e32 v28, v28
	v_exp_f32_e32 v29, v29
	v_add_f32_e32 v28, 1.0, v28
	v_add_f32_e32 v29, 1.0, v29
	v_rcp_f32_e32 v28, v28
	v_rcp_f32_e32 v29, v29
	s_nop 0
	v_pk_mul_f32 v[22:23], v[22:23], v[28:29]
	s_nop 0
	v_pk_mul_f32 v[18:19], v[18:19], v[22:23]
	s_nop 0
	v_cvt_pk_bf16_f32 v28, v18, v19
	v_mul_f32_e32 v18, 0xbfb8aa3b, v24
	v_mul_f32_e32 v19, 0xbfb8aa3b, v25
	v_exp_f32_e32 v18, v18
	v_exp_f32_e32 v19, v19
	v_add_f32_e32 v18, 1.0, v18
	v_add_f32_e32 v19, 1.0, v19
	v_rcp_f32_e32 v18, v18
	v_rcp_f32_e32 v19, v19
	s_nop 0
	v_pk_mul_f32 v[18:19], v[24:25], v[18:19]
	s_nop 0
	v_pk_mul_f32 v[18:19], v[20:21], v[18:19]
	s_nop 0
	v_cvt_pk_bf16_f32 v29, v18, v19
	v_add_u32_e32 v18, 0xa0, v146
	v_mad_i64_i32 v[18:19], s[4:5], v18, s24, v[136:137]
	global_store_dwordx4 v[18:19], v[26:29], off
	v_mul_f32_e32 v18, 0xbfb8aa3b, v14
	v_mul_f32_e32 v19, 0xbfb8aa3b, v15
	v_exp_f32_e32 v18, v18
	v_exp_f32_e32 v19, v19
	v_add_f32_e32 v18, 1.0, v18
	v_add_f32_e32 v19, 1.0, v19
	v_rcp_f32_e32 v18, v18
	v_rcp_f32_e32 v19, v19
	s_nop 0
	v_pk_mul_f32 v[14:15], v[14:15], v[18:19]
	s_nop 0
	v_pk_mul_f32 v[10:11], v[10:11], v[14:15]
	s_nop 0
	v_cvt_pk_bf16_f32 v10, v10, v11
	v_mul_f32_e32 v11, 0xbfb8aa3b, v16
	v_exp_f32_e32 v11, v11
	s_nop 0
	v_add_f32_e32 v11, 1.0, v11
	v_rcp_f32_e32 v14, v11
	v_mul_f32_e32 v11, 0xbfb8aa3b, v17
	v_exp_f32_e32 v11, v11
	s_nop 0
	v_add_f32_e32 v11, 1.0, v11
	v_rcp_f32_e32 v15, v11
	s_nop 0
	v_pk_mul_f32 v[14:15], v[16:17], v[14:15]
	s_nop 0
	v_pk_mul_f32 v[12:13], v[12:13], v[14:15]
	s_nop 0
	v_cvt_pk_bf16_f32 v11, v12, v13
	v_mul_f32_e32 v12, 0xbfb8aa3b, v6
	v_mul_f32_e32 v13, 0xbfb8aa3b, v7
	v_exp_f32_e32 v12, v12
	v_exp_f32_e32 v13, v13
	v_add_f32_e32 v12, 1.0, v12
	v_add_f32_e32 v13, 1.0, v13
	v_rcp_f32_e32 v12, v12
	v_rcp_f32_e32 v13, v13
	s_nop 0
	v_pk_mul_f32 v[6:7], v[6:7], v[12:13]
	s_nop 0
	v_pk_mul_f32 v[2:3], v[2:3], v[6:7]
	s_nop 0
	v_cvt_pk_bf16_f32 v12, v2, v3
	v_mul_f32_e32 v2, 0xbfb8aa3b, v8
	v_mul_f32_e32 v3, 0xbfb8aa3b, v9
	v_exp_f32_e32 v2, v2
	v_exp_f32_e32 v3, v3
	v_add_f32_e32 v2, 1.0, v2
	v_add_f32_e32 v3, 1.0, v3
	v_rcp_f32_e32 v2, v2
	v_rcp_f32_e32 v3, v3
	s_nop 0
	v_pk_mul_f32 v[2:3], v[8:9], v[2:3]
	s_nop 0
	v_pk_mul_f32 v[2:3], v[4:5], v[2:3]
	s_nop 0
	v_cvt_pk_bf16_f32 v13, v2, v3
	v_add_u32_e32 v2, 0xb0, v146
	v_mad_i64_i32 v[2:3], s[4:5], v2, s24, v[136:137]
	s_mov_b64 s[4:5], -1
	global_store_dwordx4 v[2:3], v[10:13], off
	s_cbranch_vccnz .LBB0_436
	s_andn2_b64 vcc, exec, s[64:65]
	s_cbranch_vccnz .LBB0_447
	s_lshl_b32 s4, s79, 5
	s_add_i32 s4, s4, 0
	s_add_i32 s4, s4, 0x20040
	v_mov_b32_e32 v4, s4
	ds_read2_b32 v[2:3], v4 offset0:1 offset1:2
	s_waitcnt lgkmcnt(0)
	v_readfirstlane_b32 s6, v2
	ds_read_b32 v2, v4 offset:20
	v_readfirstlane_b32 s8, v3
	s_waitcnt lgkmcnt(0)
	v_readfirstlane_b32 s37, v2

; #define PG8_WAIT_V(n) asm volatile("s_waitcnt vmcnt(" #n ")" ::: "memory")
; #define PG8_BAR __builtin_amdgcn_s_barrier()
; template <class Epi>
; __device__ __forceinline__ void gemm_phase(LAS unsigned char* lds, const Gemm g, const Epi& E) {
;     ...
;     PG8_WAIT_V(0);
;     PG8_BAR;
.LBB0_450:
	s_mov_b32 s32, 0
	s_waitcnt vmcnt(0)
	s_mov_b32 s68, s60
	v_readlane_b32 s60, v254, 30
	s_movk_i32 s45, 0x7ff
	s_mov_b32 s59, 0xbfb8aa3b
	s_mov_b32 s76, 0xb2a5705f
	s_mov_b32 s77, 0x42ce8ed0
	s_mov_b32 s58, 0xc2b17218
	s_mov_b32 s65, 0x7f800000
	v_readlane_b32 s18, v254, 29
	v_readlane_b32 s61, v254, 31
	s_barrier
